# loop-edge edit: GEMM K-loop counter/pointer updates and back branch moved in front of the loop-back barrier (barrier becomes loop head)
# baseline (speedup 1.0000x reference)
; #define PG8_STAGE(bufoff, gbase, voff) do { _Pragma("unroll") for (int _i = 0; _i < 2; ++_i) \
;         __builtin_amdgcn_global_load_lds((const unsigned*)((const char*)(gbase) + (voff)[_i]), (LAS unsigned*)(lds + (bufoff) + ldsw + _i * 8192), 16, 0, 0); } while (0)
; #define PG8_LDA(dst, b, h) do { _Pragma("unroll") for (int m = 0; m < 4; ++m) _Pragma("unroll") for (int k = 0; k < 2; ++k) dst[m][k] = *(const LAS bf16x8*)(lds + PG8_SA(b, h) + aoff + m * 2048 + k * 1024); } while (0)
; #define PG8_LDB(dst, b, h) do { _Pragma("unroll") for (int n = 0; n < 2; ++n) _Pragma("unroll") for (int k = 0; k < 2; ++k) dst[n][k] = *(const LAS bf16x8*)(lds + PG8_SB(b, h) + boff + n * 2048 + k * 1024); } while (0)
; #define PG8_MMA(ai, bj, At, Bt) do { __builtin_amdgcn_s_setprio(1); _Pragma("unroll") for (int m = 0; m < 4; ++m) _Pragma("unroll") for (int n = 0; n < 2; ++n) _Pragma("unroll") for (int k = 0; k < 2; ++k) \
;         acc[ai][bj][m][n] = __builtin_amdgcn_mfma_f32_16x16x32_bf16(Bt[n][k], At[m][k], acc[ai][bj][m][n], 0, 0, 0); __builtin_amdgcn_s_setprio(0); } while (0)
; template <class GEO, class Epi>
; __device__ __forceinline__ void gemm_phase(LAS unsigned char* lds, const Gemm g, const StaticOrder& S, const Epi& E) {
;     ...
;         const bool has_next = S.next(ui + 1, nxt);
;         const char* nA = has_next ? PG8_APTR(nxt) : cA; const char* nB = has_next ? PG8_BPTR(nxt) : cB;
; #pragma nounroll
;         for (int t = 0; t < nt; t += 2) {
;             const bool last = (t == nt - 2);
;             const char* a1 = cA + (size_t)(t + 1) * kstep;
;             const char* a2 = last ? nA : cA + (size_t)(t + 2) * kstep; const char* b2 = last ? nB : cB + (size_t)(t + 2) * kstep;
;             const char* a3 = a2 + kstep; const char* b3 = b2 + kstep;
;             PG8_LDB(B0, 0, 0); PG8_LDB(B1, 0, 1); PG8_SCHED; PG8_LDA(At, 0, 0); PG8_STAGE(PG8_SA(1, 1), a1 + hstepA, voffA);
;             PG8_WAIT_V(8); PG8_WAIT_L(0); PG8_BAR; PG8_MMA(0, 0, At, B0); PG8_MMA(0, 1, At, B1); PG8_BAR; PG8_SCHED;
;     ...
; #pragma unroll
;         for (int a = 0; a < 2; ++a)
; #pragma unroll
;             for (int b = 0; b < 2; ++b)
; #pragma unroll
;                 for (int m = 0; m < 4; ++m)
; #pragma unroll
;                     for (int n = 0; n < 2; ++n) acc[a][b][m][n] = (f32x4){0.f, 0.f, 0.f, 0.f};
;         cur = nxt; cA = nA; cB = nB; ++ui;
.LBB0_164:
	s_ashr_i32 s51, s50, 31
	s_lshl_b64 s[20:21], s[50:51], 19
	s_add_u32 s62, s96, s20
	s_addc_u32 s63, s97, s21
	s_and_b64 s[20:21], s[6:7], exec
	s_cselect_b32 s13, s63, s9
	s_cselect_b32 s20, s62, s8
	s_and_b32 s22, s84, 0x3fffffff
	s_lshl_b64 s[34:35], s[22:23], 19
	s_add_u32 s78, s36, s34
	s_addc_u32 s79, s37, s35
	s_and_b64 s[34:35], s[6:7], exec
	s_cselect_b32 s21, s79, s89
	s_cselect_b32 s22, s78, s88
	s_add_u32 s8, s8, 0x40080
	s_addc_u32 s9, s9, 0
	s_add_u32 s34, s88, 0x100
	v_mov_b32_e32 v32, 0
	s_addc_u32 s35, s89, 0
	s_mov_b32 s38, -2
	v_mov_b32_e32 v33, v32
	v_mov_b32_e32 v34, v32
	v_mov_b32_e32 v35, v32
	s_waitcnt vmcnt(0)
	v_mov_b32_e32 v36, v32
	v_mov_b32_e32 v37, v32
	v_mov_b32_e32 v38, v32
	v_mov_b32_e32 v39, v32
	v_mov_b32_e32 v72, v32
	v_mov_b32_e32 v73, v32
	v_mov_b32_e32 v74, v32
	v_mov_b32_e32 v75, v32
	v_mov_b32_e32 v76, v32
	v_mov_b32_e32 v77, v32
	v_mov_b32_e32 v78, v32
	v_mov_b32_e32 v79, v32
	v_mov_b32_e32 v80, v32
	v_mov_b32_e32 v81, v32
	v_mov_b32_e32 v82, v32
	v_mov_b32_e32 v83, v32
	v_mov_b32_e32 v84, v32
	v_mov_b32_e32 v85, v32
	v_mov_b32_e32 v86, v32
	v_mov_b32_e32 v87, v32
	v_mov_b32_e32 v88, v32
	v_mov_b32_e32 v89, v32
	v_mov_b32_e32 v90, v32
	v_mov_b32_e32 v91, v32
	v_mov_b32_e32 v92, v32
	v_mov_b32_e32 v93, v32
	v_mov_b32_e32 v94, v32
	v_mov_b32_e32 v95, v32
	v_mov_b32_e32 v0, v32
	v_mov_b32_e32 v1, v32
	v_mov_b32_e32 v2, v32
	v_mov_b32_e32 v3, v32
	v_mov_b32_e32 v4, v32
	v_mov_b32_e32 v5, v32
	v_mov_b32_e32 v6, v32
	v_mov_b32_e32 v7, v32
	v_mov_b32_e32 v8, v32
	v_mov_b32_e32 v9, v32
	v_mov_b32_e32 v10, v32
	v_mov_b32_e32 v11, v32
	v_mov_b32_e32 v12, v32
	v_mov_b32_e32 v13, v32
	v_mov_b32_e32 v14, v32
	v_mov_b32_e32 v15, v32
	v_mov_b32_e32 v16, v32
	v_mov_b32_e32 v17, v32
	v_mov_b32_e32 v18, v32
	v_mov_b32_e32 v19, v32
	v_mov_b32_e32 v20, v32
	v_mov_b32_e32 v21, v32
	v_mov_b32_e32 v22, v32
	v_mov_b32_e32 v23, v32
	v_mov_b32_e32 v24, v32
	v_mov_b32_e32 v25, v32
	v_mov_b32_e32 v26, v32
	v_mov_b32_e32 v27, v32
	v_mov_b32_e32 v28, v32
	v_mov_b32_e32 v29, v32
	v_mov_b32_e32 v30, v32
	v_mov_b32_e32 v31, v32
	v_mov_b32_e32 v96, v32
	v_mov_b32_e32 v97, v32
	v_mov_b32_e32 v98, v32
	v_mov_b32_e32 v99, v32
	v_mov_b32_e32 v100, v32
	v_mov_b32_e32 v101, v32
	v_mov_b32_e32 v102, v32
	v_mov_b32_e32 v103, v32
	v_mov_b32_e32 v104, v32
	v_mov_b32_e32 v105, v32
	v_mov_b32_e32 v106, v32
	v_mov_b32_e32 v107, v32
	v_mov_b32_e32 v108, v32
	v_mov_b32_e32 v109, v32
	v_mov_b32_e32 v110, v32
	v_mov_b32_e32 v111, v32
	v_mov_b32_e32 v112, v32
	v_mov_b32_e32 v113, v32
	v_mov_b32_e32 v114, v32
	v_mov_b32_e32 v115, v32
	v_mov_b32_e32 v116, v32
	v_mov_b32_e32 v117, v32
	v_mov_b32_e32 v118, v32
	v_mov_b32_e32 v119, v32
	v_mov_b32_e32 v128, v32
	v_mov_b32_e32 v129, v32
	v_mov_b32_e32 v130, v32
	v_mov_b32_e32 v131, v32
	v_mov_b32_e32 v132, v32
	v_mov_b32_e32 v133, v32
	v_mov_b32_e32 v134, v32
	v_mov_b32_e32 v135, v32
	v_mov_b32_e32 v40, v32
	v_mov_b32_e32 v41, v32
	v_mov_b32_e32 v42, v32
	v_mov_b32_e32 v43, v32
	v_mov_b32_e32 v44, v32
	v_mov_b32_e32 v45, v32
	v_mov_b32_e32 v46, v32
	v_mov_b32_e32 v47, v32
	v_mov_b32_e32 v48, v32
	v_mov_b32_e32 v49, v32
	v_mov_b32_e32 v50, v32
	v_mov_b32_e32 v51, v32
	v_mov_b32_e32 v52, v32
	v_mov_b32_e32 v53, v32
	v_mov_b32_e32 v54, v32
	v_mov_b32_e32 v55, v32
	v_mov_b32_e32 v56, v32
	v_mov_b32_e32 v57, v32
	v_mov_b32_e32 v58, v32
	v_mov_b32_e32 v59, v32
	v_mov_b32_e32 v60, v32
	v_mov_b32_e32 v61, v32
	v_mov_b32_e32 v62, v32
	v_mov_b32_e32 v63, v32
	v_mov_b32_e32 v64, v32
	v_mov_b32_e32 v65, v32
	v_mov_b32_e32 v66, v32
	v_mov_b32_e32 v67, v32
	v_mov_b32_e32 v68, v32
	v_mov_b32_e32 v69, v32
	v_mov_b32_e32 v70, v32
	v_mov_b32_e32 v71, v32
	s_branch .LBB0_165
.Lrot_0:
	s_barrier
.LBB0_165:
	ds_read_b128 v[120:123], v172
	ds_read_b128 v[124:127], v172 offset:1024
	ds_read_b128 v[156:159], v172 offset:2048
	ds_read_b128 v[186:189], v172 offset:3072
	ds_read_b128 v[190:193], v173
	ds_read_b128 v[194:197], v173 offset:1024
	ds_read_b128 v[198:201], v173 offset:2048
	ds_read_b128 v[202:205], v173 offset:3072
	s_add_u32 s39, s8, 0xfffc0080
	s_addc_u32 s51, s9, -1
	s_cmp_eq_u32 s38, 12
	s_cselect_b32 s93, s13, s51
	s_cselect_b32 s92, s20, s39
	s_cselect_b32 s89, s21, s35
	s_cselect_b32 s88, s22, s34
	v_lshl_add_u64 v[160:161], s[8:9], 0, v[148:149]
	s_add_i32 m0, s19, 0xc000
	ds_read_b128 v[210:213], v174
	ds_read_b128 v[214:217], v174 offset:1024
	ds_read_b128 v[218:221], v174 offset:2048
	ds_read_b128 v[222:225], v174 offset:3072
	ds_read_b128 v[226:229], v174 offset:4096
	ds_read_b128 v[230:233], v174 offset:5120
	ds_read_b128 v[234:237], v174 offset:6144
	ds_read_b128 v[238:241], v174 offset:7168
	global_load_lds_dwordx4 v[160:161], off
	v_lshl_add_u64 v[160:161], s[8:9], 0, v[150:151]
	s_add_i32 m0, s19, 0xe000
	s_nop 0
	global_load_lds_dwordx4 v[160:161], off
	s_waitcnt vmcnt(8)
	s_waitcnt lgkmcnt(0)
	s_barrier
; #define PG8_STAGE(bufoff, gbase, voff) do { _Pragma("unroll") for (int _i = 0; _i < 2; ++_i) \
;         __builtin_amdgcn_global_load_lds((const unsigned*)((const char*)(gbase) + (voff)[_i]), (LAS unsigned*)(lds + (bufoff) + ldsw + _i * 8192), 16, 0, 0); } while (0)
; #define PG8_LDA(dst, b, h) do { _Pragma("unroll") for (int m = 0; m < 4; ++m) _Pragma("unroll") for (int k = 0; k < 2; ++k) dst[m][k] = *(const LAS bf16x8*)(lds + PG8_SA(b, h) + aoff + m * 2048 + k * 1024); } while (0)
; #define PG8_MMA(ai, bj, At, Bt) do { __builtin_amdgcn_s_setprio(1); _Pragma("unroll") for (int m = 0; m < 4; ++m) _Pragma("unroll") for (int n = 0; n < 2; ++n) _Pragma("unroll") for (int k = 0; k < 2; ++k) \
;         acc[ai][bj][m][n] = __builtin_amdgcn_mfma_f32_16x16x32_bf16(Bt[n][k], At[m][k], acc[ai][bj][m][n], 0, 0, 0); __builtin_amdgcn_s_setprio(0); } while (0)
; #define PG8_WAIT_V(n) asm volatile("s_waitcnt vmcnt(" #n ")" ::: "memory")
; #define PG8_WAIT_L(n) asm volatile("s_waitcnt lgkmcnt(" #n ")" ::: "memory")
; #define PG8_BAR __builtin_amdgcn_s_barrier()
; #define PG8_SCHED __builtin_amdgcn_sched_barrier(0)
; template <class GEO, class Epi>
; __device__ __forceinline__ void gemm_phase(LAS unsigned char* lds, const Gemm g, const StaticOrder& S, const Epi& E) {
;     ...
;             PG8_WAIT_V(8); PG8_WAIT_L(0); PG8_BAR; PG8_MMA(0, 0, At, B0); PG8_MMA(0, 1, At, B1); PG8_BAR; PG8_SCHED;
;             PG8_LDA(At, 0, 1); PG8_STAGE(PG8_SB(0, 0), b2, voffB); PG8_STAGE(PG8_SB(0, 1), b2 + hstepB, voffB); PG8_STAGE(PG8_SA(0, 0), a2, voffA);
;             PG8_WAIT_V(8); PG8_WAIT_L(0); PG8_BAR; PG8_MMA(1, 0, At, B0); PG8_MMA(1, 1, At, B1); PG8_BAR; PG8_SCHED;
	s_waitcnt lgkmcnt(0)
	v_mfma_f32_16x16x32_bf16 v[68:71], v[120:123], v[210:213], v[68:71]
	v_mfma_f32_16x16x32_bf16 v[64:67], v[156:159], v[210:213], v[64:67]
	v_mfma_f32_16x16x32_bf16 v[60:63], v[120:123], v[218:221], v[60:63]
	v_mfma_f32_16x16x32_bf16 v[56:59], v[156:159], v[218:221], v[56:59]
	v_mfma_f32_16x16x32_bf16 v[52:55], v[120:123], v[226:229], v[52:55]
	v_mfma_f32_16x16x32_bf16 v[48:51], v[156:159], v[226:229], v[48:51]
	v_mfma_f32_16x16x32_bf16 v[44:47], v[120:123], v[234:237], v[44:47]
	v_mfma_f32_16x16x32_bf16 v[40:43], v[156:159], v[234:237], v[40:43]
	v_mfma_f32_16x16x32_bf16 v[68:71], v[124:127], v[214:217], v[68:71]
	v_mfma_f32_16x16x32_bf16 v[64:67], v[186:189], v[214:217], v[64:67]
	v_mfma_f32_16x16x32_bf16 v[60:63], v[124:127], v[222:225], v[60:63]
	v_mfma_f32_16x16x32_bf16 v[56:59], v[186:189], v[222:225], v[56:59]
	v_mfma_f32_16x16x32_bf16 v[52:55], v[124:127], v[230:233], v[52:55]
	v_mfma_f32_16x16x32_bf16 v[48:51], v[186:189], v[230:233], v[48:51]
	v_mfma_f32_16x16x32_bf16 v[44:47], v[124:127], v[238:241], v[44:47]
	v_mfma_f32_16x16x32_bf16 v[40:43], v[186:189], v[238:241], v[40:43]
	v_mfma_f32_16x16x32_bf16 v[132:135], v[190:193], v[210:213], v[132:135]
	v_mfma_f32_16x16x32_bf16 v[128:131], v[198:201], v[210:213], v[128:131]
	v_mfma_f32_16x16x32_bf16 v[116:119], v[190:193], v[218:221], v[116:119]
	v_mfma_f32_16x16x32_bf16 v[112:115], v[198:201], v[218:221], v[112:115]
	v_mfma_f32_16x16x32_bf16 v[108:111], v[190:193], v[226:229], v[108:111]
	v_mfma_f32_16x16x32_bf16 v[104:107], v[198:201], v[226:229], v[104:107]
	v_mfma_f32_16x16x32_bf16 v[100:103], v[190:193], v[234:237], v[100:103]
	v_mfma_f32_16x16x32_bf16 v[96:99], v[198:201], v[234:237], v[96:99]
	v_mfma_f32_16x16x32_bf16 v[132:135], v[194:197], v[214:217], v[132:135]
	v_mfma_f32_16x16x32_bf16 v[128:131], v[202:205], v[214:217], v[128:131]
	v_mfma_f32_16x16x32_bf16 v[116:119], v[194:197], v[222:225], v[116:119]
	v_mfma_f32_16x16x32_bf16 v[112:115], v[202:205], v[222:225], v[112:115]
	v_mfma_f32_16x16x32_bf16 v[108:111], v[194:197], v[230:233], v[108:111]
	v_mfma_f32_16x16x32_bf16 v[104:107], v[202:205], v[230:233], v[104:107]
	v_mfma_f32_16x16x32_bf16 v[100:103], v[194:197], v[238:241], v[100:103]
	v_mfma_f32_16x16x32_bf16 v[96:99], v[202:205], v[238:241], v[96:99]
	s_barrier
	s_add_i32 s39, s87, s49
	v_lshl_add_u64 v[160:161], s[88:89], 0, v[140:141]
	s_mov_b32 m0, s39
	ds_read_b128 v[210:213], v174 offset:16384
	ds_read_b128 v[214:217], v174 offset:17408
	ds_read_b128 v[218:221], v174 offset:18432
	ds_read_b128 v[222:225], v174 offset:19456
	ds_read_b128 v[226:229], v174 offset:20480
	ds_read_b128 v[230:233], v174 offset:21504
	ds_read_b128 v[234:237], v174 offset:22528
	ds_read_b128 v[238:241], v174 offset:23552
	global_load_lds_dwordx4 v[160:161], off
	s_add_i32 m0, s39, 0x2000
	s_add_u32 s52, s88, 0x40000
	v_lshl_add_u64 v[242:243], s[88:89], 0, v[144:145]
	s_addc_u32 s53, s89, 0
	s_add_i32 s39, s90, s49
	global_load_lds_dwordx4 v[242:243], off
	v_lshl_add_u64 v[244:245], s[52:53], 0, v[140:141]
	s_mov_b32 m0, s39
	v_lshl_add_u64 v[246:247], s[92:93], 0, v[142:143]
	global_load_lds_dwordx4 v[244:245], off
	v_lshl_add_u64 v[244:245], s[52:53], 0, v[144:145]
	s_add_i32 m0, s39, 0x2000
	s_nop 0
	global_load_lds_dwordx4 v[244:245], off
	v_lshl_add_u64 v[244:245], s[92:93], 0, v[138:139]
	s_mov_b32 m0, s19
	s_nop 0
	global_load_lds_dwordx4 v[244:245], off
	s_mov_b32 m0, s55
	s_nop 0
	global_load_lds_dwordx4 v[246:247], off
	s_waitcnt vmcnt(8)
	s_waitcnt lgkmcnt(0)
	s_barrier
	s_waitcnt lgkmcnt(0)
	v_mfma_f32_16x16x32_bf16 v[28:31], v[120:123], v[210:213], v[28:31]
	v_mfma_f32_16x16x32_bf16 v[24:27], v[156:159], v[210:213], v[24:27]
	v_mfma_f32_16x16x32_bf16 v[20:23], v[120:123], v[218:221], v[20:23]
	v_mfma_f32_16x16x32_bf16 v[16:19], v[156:159], v[218:221], v[16:19]
	v_mfma_f32_16x16x32_bf16 v[12:15], v[120:123], v[226:229], v[12:15]
	v_mfma_f32_16x16x32_bf16 v[8:11], v[156:159], v[226:229], v[8:11]
	v_mfma_f32_16x16x32_bf16 v[4:7], v[120:123], v[234:237], v[4:7]
	v_mfma_f32_16x16x32_bf16 v[0:3], v[156:159], v[234:237], v[0:3]
	v_mfma_f32_16x16x32_bf16 v[28:31], v[124:127], v[214:217], v[28:31]
	v_mfma_f32_16x16x32_bf16 v[24:27], v[186:189], v[214:217], v[24:27]
	v_mfma_f32_16x16x32_bf16 v[20:23], v[124:127], v[222:225], v[20:23]
	v_mfma_f32_16x16x32_bf16 v[16:19], v[186:189], v[222:225], v[16:19]
	v_mfma_f32_16x16x32_bf16 v[12:15], v[124:127], v[230:233], v[12:15]
	v_mfma_f32_16x16x32_bf16 v[8:11], v[186:189], v[230:233], v[8:11]
	v_mfma_f32_16x16x32_bf16 v[4:7], v[124:127], v[238:241], v[4:7]
	v_mfma_f32_16x16x32_bf16 v[0:3], v[186:189], v[238:241], v[0:3]
	v_mfma_f32_16x16x32_bf16 v[92:95], v[190:193], v[210:213], v[92:95]
	v_mfma_f32_16x16x32_bf16 v[88:91], v[198:201], v[210:213], v[88:91]
	v_mfma_f32_16x16x32_bf16 v[84:87], v[190:193], v[218:221], v[84:87]
	v_mfma_f32_16x16x32_bf16 v[80:83], v[198:201], v[218:221], v[80:83]
	v_mfma_f32_16x16x32_bf16 v[76:79], v[190:193], v[226:229], v[76:79]
	v_mfma_f32_16x16x32_bf16 v[72:75], v[198:201], v[226:229], v[72:75]
	v_mfma_f32_16x16x32_bf16 v[36:39], v[190:193], v[234:237], v[36:39]
	v_mfma_f32_16x16x32_bf16 v[32:35], v[198:201], v[234:237], v[32:35]
	v_mfma_f32_16x16x32_bf16 v[92:95], v[194:197], v[214:217], v[92:95]
	v_mfma_f32_16x16x32_bf16 v[88:91], v[202:205], v[214:217], v[88:91]
	v_mfma_f32_16x16x32_bf16 v[84:87], v[194:197], v[222:225], v[84:87]
	v_mfma_f32_16x16x32_bf16 v[80:83], v[202:205], v[222:225], v[80:83]
	v_mfma_f32_16x16x32_bf16 v[76:79], v[194:197], v[230:233], v[76:79]
	v_mfma_f32_16x16x32_bf16 v[72:75], v[202:205], v[230:233], v[72:75]
	v_mfma_f32_16x16x32_bf16 v[36:39], v[194:197], v[238:241], v[36:39]
	v_mfma_f32_16x16x32_bf16 v[32:35], v[202:205], v[238:241], v[32:35]
	s_barrier
; #define PG8_STAGE(bufoff, gbase, voff) do { _Pragma("unroll") for (int _i = 0; _i < 2; ++_i) \
;         __builtin_amdgcn_global_load_lds((const unsigned*)((const char*)(gbase) + (voff)[_i]), (LAS unsigned*)(lds + (bufoff) + ldsw + _i * 8192), 16, 0, 0); } while (0)
; #define PG8_LDA(dst, b, h) do { _Pragma("unroll") for (int m = 0; m < 4; ++m) _Pragma("unroll") for (int k = 0; k < 2; ++k) dst[m][k] = *(const LAS bf16x8*)(lds + PG8_SA(b, h) + aoff + m * 2048 + k * 1024); } while (0)
; #define PG8_LDB(dst, b, h) do { _Pragma("unroll") for (int n = 0; n < 2; ++n) _Pragma("unroll") for (int k = 0; k < 2; ++k) dst[n][k] = *(const LAS bf16x8*)(lds + PG8_SB(b, h) + boff + n * 2048 + k * 1024); } while (0)
; #define PG8_MMA(ai, bj, At, Bt) do { __builtin_amdgcn_s_setprio(1); _Pragma("unroll") for (int m = 0; m < 4; ++m) _Pragma("unroll") for (int n = 0; n < 2; ++n) _Pragma("unroll") for (int k = 0; k < 2; ++k) \
;         acc[ai][bj][m][n] = __builtin_amdgcn_mfma_f32_16x16x32_bf16(Bt[n][k], At[m][k], acc[ai][bj][m][n], 0, 0, 0); __builtin_amdgcn_s_setprio(0); } while (0)
; #define PG8_WAIT_V(n) asm volatile("s_waitcnt vmcnt(" #n ")" ::: "memory")
; #define PG8_WAIT_L(n) asm volatile("s_waitcnt lgkmcnt(" #n ")" ::: "memory")
; #define PG8_BAR __builtin_amdgcn_s_barrier()
; #define PG8_SCHED __builtin_amdgcn_sched_barrier(0)
; template <class GEO, class Epi>
; __device__ __forceinline__ void gemm_phase(LAS unsigned char* lds, const Gemm g, const StaticOrder& S, const Epi& E) {
;     ...
;             PG8_LDB(B0, 1, 0); PG8_LDB(B1, 1, 1); PG8_SCHED; PG8_LDA(At, 1, 0); PG8_STAGE(PG8_SA(0, 1), a2 + hstepA, voffA);
;             PG8_WAIT_V(8); PG8_WAIT_L(0); PG8_BAR; PG8_MMA(0, 0, At, B0); PG8_MMA(0, 1, At, B1); PG8_BAR; PG8_SCHED;
	s_add_i32 s39, 0, 0x18000
	s_add_i32 s51, 0, 0x1c000
	v_add_u32_e32 v186, s39, v163
	v_add_u32_e32 v202, s51, v163
	ds_read_b128 v[120:123], v186
	ds_read_b128 v[124:127], v186 offset:1024
	ds_read_b128 v[156:159], v186 offset:2048
	ds_read_b128 v[186:189], v186 offset:3072
	ds_read_b128 v[190:193], v202
	ds_read_b128 v[194:197], v202 offset:1024
	ds_read_b128 v[198:201], v202 offset:2048
	ds_read_b128 v[202:205], v202 offset:3072
	s_add_u32 s52, s92, 0x40000
	s_addc_u32 s53, s93, 0
	s_mov_b32 m0, s58
	v_lshl_add_u64 v[248:249], s[52:53], 0, v[138:139]
	ds_read_b128 v[210:213], v174 offset:32768
	ds_read_b128 v[214:217], v174 offset:33792
	ds_read_b128 v[218:221], v174 offset:34816
	ds_read_b128 v[222:225], v174 offset:35840
	ds_read_b128 v[226:229], v174 offset:36864
	ds_read_b128 v[230:233], v174 offset:37888
	ds_read_b128 v[234:237], v174 offset:38912
	ds_read_b128 v[238:241], v174 offset:39936
	global_load_lds_dwordx4 v[248:249], off
	v_lshl_add_u64 v[248:249], s[52:53], 0, v[142:143]
	s_mov_b32 m0, s59
	s_nop 0
	global_load_lds_dwordx4 v[248:249], off
	s_waitcnt vmcnt(8)
	s_waitcnt lgkmcnt(0)
	s_barrier
	s_waitcnt lgkmcnt(0)
	v_mfma_f32_16x16x32_bf16 v[68:71], v[120:123], v[210:213], v[68:71]
	v_mfma_f32_16x16x32_bf16 v[64:67], v[156:159], v[210:213], v[64:67]
	v_mfma_f32_16x16x32_bf16 v[60:63], v[120:123], v[218:221], v[60:63]
	v_mfma_f32_16x16x32_bf16 v[56:59], v[156:159], v[218:221], v[56:59]
	v_mfma_f32_16x16x32_bf16 v[52:55], v[120:123], v[226:229], v[52:55]
	v_mfma_f32_16x16x32_bf16 v[48:51], v[156:159], v[226:229], v[48:51]
	v_mfma_f32_16x16x32_bf16 v[44:47], v[120:123], v[234:237], v[44:47]
	v_mfma_f32_16x16x32_bf16 v[40:43], v[156:159], v[234:237], v[40:43]
	v_mfma_f32_16x16x32_bf16 v[68:71], v[124:127], v[214:217], v[68:71]
	v_mfma_f32_16x16x32_bf16 v[64:67], v[186:189], v[214:217], v[64:67]
	v_mfma_f32_16x16x32_bf16 v[60:63], v[124:127], v[222:225], v[60:63]
	v_mfma_f32_16x16x32_bf16 v[56:59], v[186:189], v[222:225], v[56:59]
	v_mfma_f32_16x16x32_bf16 v[52:55], v[124:127], v[230:233], v[52:55]
	v_mfma_f32_16x16x32_bf16 v[48:51], v[186:189], v[230:233], v[48:51]
	v_mfma_f32_16x16x32_bf16 v[44:47], v[124:127], v[238:241], v[44:47]
	v_mfma_f32_16x16x32_bf16 v[40:43], v[186:189], v[238:241], v[40:43]
	v_mfma_f32_16x16x32_bf16 v[132:135], v[190:193], v[210:213], v[132:135]
	v_mfma_f32_16x16x32_bf16 v[128:131], v[198:201], v[210:213], v[128:131]
	v_mfma_f32_16x16x32_bf16 v[116:119], v[190:193], v[218:221], v[116:119]
	v_mfma_f32_16x16x32_bf16 v[112:115], v[198:201], v[218:221], v[112:115]
	v_mfma_f32_16x16x32_bf16 v[108:111], v[190:193], v[226:229], v[108:111]
	v_mfma_f32_16x16x32_bf16 v[104:107], v[198:201], v[226:229], v[104:107]
	v_mfma_f32_16x16x32_bf16 v[100:103], v[190:193], v[234:237], v[100:103]
	v_mfma_f32_16x16x32_bf16 v[96:99], v[198:201], v[234:237], v[96:99]
	v_mfma_f32_16x16x32_bf16 v[132:135], v[194:197], v[214:217], v[132:135]
	v_mfma_f32_16x16x32_bf16 v[128:131], v[202:205], v[214:217], v[128:131]
	v_mfma_f32_16x16x32_bf16 v[116:119], v[194:197], v[222:225], v[116:119]
	v_mfma_f32_16x16x32_bf16 v[112:115], v[202:205], v[222:225], v[112:115]
	v_mfma_f32_16x16x32_bf16 v[108:111], v[194:197], v[230:233], v[108:111]
	v_mfma_f32_16x16x32_bf16 v[104:107], v[202:205], v[230:233], v[104:107]
	v_mfma_f32_16x16x32_bf16 v[100:103], v[194:197], v[238:241], v[100:103]
	v_mfma_f32_16x16x32_bf16 v[96:99], v[202:205], v[238:241], v[96:99]
	s_barrier
; #define PG8_STAGE(bufoff, gbase, voff) do { _Pragma("unroll") for (int _i = 0; _i < 2; ++_i) \
;         __builtin_amdgcn_global_load_lds((const unsigned*)((const char*)(gbase) + (voff)[_i]), (LAS unsigned*)(lds + (bufoff) + ldsw + _i * 8192), 16, 0, 0); } while (0)
; #define PG8_LDA(dst, b, h) do { _Pragma("unroll") for (int m = 0; m < 4; ++m) _Pragma("unroll") for (int k = 0; k < 2; ++k) dst[m][k] = *(const LAS bf16x8*)(lds + PG8_SA(b, h) + aoff + m * 2048 + k * 1024); } while (0)
; #define PG8_MMA(ai, bj, At, Bt) do { __builtin_amdgcn_s_setprio(1); _Pragma("unroll") for (int m = 0; m < 4; ++m) _Pragma("unroll") for (int n = 0; n < 2; ++n) _Pragma("unroll") for (int k = 0; k < 2; ++k) \
;         acc[ai][bj][m][n] = __builtin_amdgcn_mfma_f32_16x16x32_bf16(Bt[n][k], At[m][k], acc[ai][bj][m][n], 0, 0, 0); __builtin_amdgcn_s_setprio(0); } while (0)
; #define PG8_WAIT_V(n) asm volatile("s_waitcnt vmcnt(" #n ")" ::: "memory")
; #define PG8_WAIT_L(n) asm volatile("s_waitcnt lgkmcnt(" #n ")" ::: "memory")
; #define PG8_BAR __builtin_amdgcn_s_barrier()
; #define PG8_SCHED __builtin_amdgcn_sched_barrier(0)
; template <class GEO, class Epi>
; __device__ __forceinline__ void gemm_phase(LAS unsigned char* lds, const Gemm g, const StaticOrder& S, const Epi& E) {
;     ...
;             PG8_LDA(At, 1, 1); PG8_STAGE(PG8_SB(1, 0), b3, voffB); PG8_STAGE(PG8_SB(1, 1), b3 + hstepB, voffB); PG8_STAGE(PG8_SA(1, 0), a3, voffA);
;             PG8_WAIT_V(8); PG8_WAIT_L(0); PG8_BAR; PG8_MMA(1, 0, At, B0); PG8_MMA(1, 1, At, B1); PG8_BAR; PG8_SCHED;
;         }
;         if (wr == 0) PG8_BAR;
	s_add_i32 s39, s39, s49
	v_lshl_add_u64 v[160:161], v[160:161], 0, s[42:43]
	s_mov_b32 m0, s39
	ds_read_b128 v[210:213], v174 offset:49152
	ds_read_b128 v[214:217], v174 offset:50176
	ds_read_b128 v[218:221], v174 offset:51200
	ds_read_b128 v[222:225], v174 offset:52224
	ds_read_b128 v[226:229], v174 offset:53248
	ds_read_b128 v[230:233], v174 offset:54272
	ds_read_b128 v[234:237], v174 offset:55296
	ds_read_b128 v[238:241], v174 offset:56320
	global_load_lds_dwordx4 v[160:161], off
	s_add_i32 m0, s39, 0x2000
	s_add_u32 s52, s88, 0x40080
	v_lshl_add_u64 v[160:161], v[242:243], 0, s[42:43]
	s_addc_u32 s53, s89, 0
	s_add_i32 s39, s51, s49
	global_load_lds_dwordx4 v[160:161], off
	v_lshl_add_u64 v[160:161], s[52:53], 0, v[140:141]
	s_mov_b32 m0, s39
	s_nop 0
	global_load_lds_dwordx4 v[160:161], off
	v_lshl_add_u64 v[160:161], s[52:53], 0, v[144:145]
	s_add_i32 m0, s39, 0x2000
	s_nop 0
	global_load_lds_dwordx4 v[160:161], off
	v_lshl_add_u64 v[160:161], v[244:245], 0, s[42:43]
	s_mov_b32 m0, s85
	s_nop 0
	global_load_lds_dwordx4 v[160:161], off
	v_lshl_add_u64 v[160:161], v[246:247], 0, s[42:43]
	s_mov_b32 m0, s86
	s_nop 0
	global_load_lds_dwordx4 v[160:161], off
	s_waitcnt vmcnt(8)
	s_waitcnt lgkmcnt(0)
	s_barrier
	s_waitcnt lgkmcnt(0)
	v_mfma_f32_16x16x32_bf16 v[28:31], v[120:123], v[210:213], v[28:31]
	v_mfma_f32_16x16x32_bf16 v[24:27], v[156:159], v[210:213], v[24:27]
	v_mfma_f32_16x16x32_bf16 v[20:23], v[120:123], v[218:221], v[20:23]
	v_mfma_f32_16x16x32_bf16 v[16:19], v[156:159], v[218:221], v[16:19]
	v_mfma_f32_16x16x32_bf16 v[12:15], v[120:123], v[226:229], v[12:15]
	v_mfma_f32_16x16x32_bf16 v[8:11], v[156:159], v[226:229], v[8:11]
	v_mfma_f32_16x16x32_bf16 v[4:7], v[120:123], v[234:237], v[4:7]
	v_mfma_f32_16x16x32_bf16 v[0:3], v[156:159], v[234:237], v[0:3]
	v_mfma_f32_16x16x32_bf16 v[28:31], v[124:127], v[214:217], v[28:31]
	v_mfma_f32_16x16x32_bf16 v[24:27], v[186:189], v[214:217], v[24:27]
	v_mfma_f32_16x16x32_bf16 v[20:23], v[124:127], v[222:225], v[20:23]
	v_mfma_f32_16x16x32_bf16 v[16:19], v[186:189], v[222:225], v[16:19]
	v_mfma_f32_16x16x32_bf16 v[12:15], v[124:127], v[230:233], v[12:15]
	v_mfma_f32_16x16x32_bf16 v[8:11], v[186:189], v[230:233], v[8:11]
	v_mfma_f32_16x16x32_bf16 v[4:7], v[124:127], v[238:241], v[4:7]
	v_mfma_f32_16x16x32_bf16 v[0:3], v[186:189], v[238:241], v[0:3]
	v_mfma_f32_16x16x32_bf16 v[92:95], v[190:193], v[210:213], v[92:95]
	v_mfma_f32_16x16x32_bf16 v[88:91], v[198:201], v[210:213], v[88:91]
	v_mfma_f32_16x16x32_bf16 v[84:87], v[190:193], v[218:221], v[84:87]
	v_mfma_f32_16x16x32_bf16 v[80:83], v[198:201], v[218:221], v[80:83]
	v_mfma_f32_16x16x32_bf16 v[76:79], v[190:193], v[226:229], v[76:79]
	v_mfma_f32_16x16x32_bf16 v[72:75], v[198:201], v[226:229], v[72:75]
	v_mfma_f32_16x16x32_bf16 v[36:39], v[190:193], v[234:237], v[36:39]
	v_mfma_f32_16x16x32_bf16 v[32:35], v[198:201], v[234:237], v[32:35]
	v_mfma_f32_16x16x32_bf16 v[92:95], v[194:197], v[214:217], v[92:95]
	v_mfma_f32_16x16x32_bf16 v[88:91], v[202:205], v[214:217], v[88:91]
	v_mfma_f32_16x16x32_bf16 v[84:87], v[194:197], v[222:225], v[84:87]
	v_mfma_f32_16x16x32_bf16 v[80:83], v[202:205], v[222:225], v[80:83]
	v_mfma_f32_16x16x32_bf16 v[76:79], v[194:197], v[230:233], v[76:79]
	v_mfma_f32_16x16x32_bf16 v[72:75], v[202:205], v[230:233], v[72:75]
	v_mfma_f32_16x16x32_bf16 v[36:39], v[194:197], v[238:241], v[36:39]
	v_mfma_f32_16x16x32_bf16 v[32:35], v[202:205], v[238:241], v[32:35]
	s_add_i32 s38, s38, 2
	s_add_u32 s8, s8, 0x100
	s_addc_u32 s9, s9, 0
	s_add_u32 s34, s34, 0x100
	s_addc_u32 s35, s35, 0
	s_cmp_gt_u32 s38, 13
	s_cbranch_scc0 .Lrot_0
	s_barrier
	s_and_b64 vcc, exec, s[44:45]
	s_cbranch_vccz .LBB0_168
	s_barrier

; template <class GEO, class Epi>
; __device__ __forceinline__ void gemm_phase(LAS unsigned char* lds, const Gemm g, const StaticOrder& S, const Epi& E) {
;     ...
;         const bool has_next = S.next(ui + 1, nxt);
;         const char* nA = has_next ? PG8_APTR(nxt) : cA; const char* nB = has_next ? PG8_BPTR(nxt) : cB;
; #pragma nounroll
;         for (int t = 0; t < nt; t += 2) {
;             const bool last = (t == nt - 2);
;             const char* a1 = cA + (size_t)(t + 1) * kstep;
;             const char* a2 = last ? nA : cA + (size_t)(t + 2) * kstep; const char* b2 = last ? nB : cB + (size_t)(t + 2) * kstep;
;     ...
; #pragma unroll
;         for (int a = 0; a < 2; ++a)
; #pragma unroll
;             for (int b = 0; b < 2; ++b)
; #pragma unroll
;                 for (int m = 0; m < 4; ++m)
; #pragma unroll
;                     for (int n = 0; n < 2; ++n) acc[a][b][m][n] = (f32x4){0.f, 0.f, 0.f, 0.f};
;         cur = nxt; cA = nA; cB = nB; ++ui;
.LBB0_231:
	s_ashr_i32 s47, s46, 31
	s_lshl_b64 s[8:9], s[46:47], 19
	s_add_u32 s48, s58, s8
	s_addc_u32 s49, s59, s9
	s_and_b64 s[8:9], s[44:45], exec
	s_cselect_b32 s47, s49, s93
	s_cselect_b32 s52, s48, s92
	s_and_b32 s6, s56, 0x3fffffff
	s_lshl_b64 s[8:9], s[6:7], 19
	v_readlane_b32 s0, v254, 20
	v_readlane_b32 s1, v254, 21
	s_add_u32 s50, s0, s8
	s_addc_u32 s51, s1, s9
	s_and_b64 s[8:9], s[44:45], exec
	s_cselect_b32 s6, s51, s89
	s_cselect_b32 s53, s50, s88
	s_add_u32 s64, s92, 0x40080
	s_addc_u32 s65, s93, 0
	s_add_u32 s57, s88, 0x100
	v_mov_b32_e32 v0, 0
	s_addc_u32 vcc_lo, s89, 0
	s_mov_b32 vcc_hi, -2
	v_mov_b32_e32 v1, v0
	v_mov_b32_e32 v2, v0
	v_mov_b32_e32 v3, v0
	v_mov_b32_e32 v4, v0
	v_mov_b32_e32 v5, v0
	v_mov_b32_e32 v6, v0
	v_mov_b32_e32 v7, v0
	v_mov_b32_e32 v8, v0
	v_mov_b32_e32 v9, v0
	v_mov_b32_e32 v10, v0
	v_mov_b32_e32 v11, v0
	v_mov_b32_e32 v12, v0
	v_mov_b32_e32 v13, v0
	v_mov_b32_e32 v14, v0
	v_mov_b32_e32 v15, v0
	v_mov_b32_e32 v24, v0
	v_mov_b32_e32 v25, v0
	v_mov_b32_e32 v26, v0
	v_mov_b32_e32 v27, v0
	s_waitcnt vmcnt(0)
	v_mov_b32_e32 v28, v0
	v_mov_b32_e32 v29, v0
	v_mov_b32_e32 v30, v0
	v_mov_b32_e32 v31, v0
	v_mov_b32_e32 v40, v0
	v_mov_b32_e32 v41, v0
	v_mov_b32_e32 v42, v0
	v_mov_b32_e32 v43, v0
	v_mov_b32_e32 v44, v0
	v_mov_b32_e32 v45, v0
	v_mov_b32_e32 v46, v0
	v_mov_b32_e32 v47, v0
	v_mov_b32_e32 v16, v0
	v_mov_b32_e32 v17, v0
	v_mov_b32_e32 v18, v0
	v_mov_b32_e32 v19, v0
	v_mov_b32_e32 v20, v0
	v_mov_b32_e32 v21, v0
	v_mov_b32_e32 v22, v0
	v_mov_b32_e32 v23, v0
	v_mov_b32_e32 v32, v0
	v_mov_b32_e32 v33, v0
	v_mov_b32_e32 v34, v0
	v_mov_b32_e32 v35, v0
	v_mov_b32_e32 v36, v0
	v_mov_b32_e32 v37, v0
	v_mov_b32_e32 v38, v0
	v_mov_b32_e32 v39, v0
	v_mov_b32_e32 v48, v0
	v_mov_b32_e32 v49, v0
	v_mov_b32_e32 v50, v0
	v_mov_b32_e32 v51, v0
	v_mov_b32_e32 v52, v0
	v_mov_b32_e32 v53, v0
	v_mov_b32_e32 v54, v0
	v_mov_b32_e32 v55, v0
	v_mov_b32_e32 v56, v0
	v_mov_b32_e32 v57, v0
	v_mov_b32_e32 v58, v0
	v_mov_b32_e32 v59, v0
	v_mov_b32_e32 v60, v0
	v_mov_b32_e32 v61, v0
	v_mov_b32_e32 v62, v0
	v_mov_b32_e32 v63, v0
	v_mov_b32_e32 v64, v0
	v_mov_b32_e32 v65, v0
	v_mov_b32_e32 v66, v0
	v_mov_b32_e32 v67, v0
	v_mov_b32_e32 v68, v0
	v_mov_b32_e32 v69, v0
	v_mov_b32_e32 v70, v0
	v_mov_b32_e32 v71, v0
	v_mov_b32_e32 v72, v0
	v_mov_b32_e32 v73, v0
	v_mov_b32_e32 v74, v0
	v_mov_b32_e32 v75, v0
	v_mov_b32_e32 v76, v0
	v_mov_b32_e32 v77, v0
	v_mov_b32_e32 v78, v0
	v_mov_b32_e32 v79, v0
	v_mov_b32_e32 v88, v0
	v_mov_b32_e32 v89, v0
	v_mov_b32_e32 v90, v0
	v_mov_b32_e32 v91, v0
	v_mov_b32_e32 v92, v0
	v_mov_b32_e32 v93, v0
	v_mov_b32_e32 v94, v0
	v_mov_b32_e32 v95, v0
	v_mov_b32_e32 v104, v0
	v_mov_b32_e32 v105, v0
	v_mov_b32_e32 v106, v0
	v_mov_b32_e32 v107, v0
	v_mov_b32_e32 v108, v0
	v_mov_b32_e32 v109, v0
	v_mov_b32_e32 v110, v0
	v_mov_b32_e32 v111, v0
	v_mov_b32_e32 v80, v0
	v_mov_b32_e32 v81, v0
	v_mov_b32_e32 v82, v0
	v_mov_b32_e32 v83, v0
	v_mov_b32_e32 v84, v0
	v_mov_b32_e32 v85, v0
	v_mov_b32_e32 v86, v0
	v_mov_b32_e32 v87, v0
	v_mov_b32_e32 v96, v0
	v_mov_b32_e32 v97, v0
	v_mov_b32_e32 v98, v0
	v_mov_b32_e32 v99, v0
	v_mov_b32_e32 v100, v0
	v_mov_b32_e32 v101, v0
	v_mov_b32_e32 v102, v0
	v_mov_b32_e32 v103, v0
	v_mov_b32_e32 v112, v0
	v_mov_b32_e32 v113, v0
	v_mov_b32_e32 v114, v0
	v_mov_b32_e32 v115, v0
	v_mov_b32_e32 v116, v0
	v_mov_b32_e32 v117, v0
	v_mov_b32_e32 v118, v0
	v_mov_b32_e32 v119, v0
	v_mov_b32_e32 v120, v0
	v_mov_b32_e32 v121, v0
	v_mov_b32_e32 v122, v0
	v_mov_b32_e32 v123, v0
	v_mov_b32_e32 v124, v0
	v_mov_b32_e32 v125, v0
	v_mov_b32_e32 v126, v0
	v_mov_b32_e32 v127, v0
	s_branch .LBB0_232

; #define PG8_STAGE(bufoff, gbase, voff) do { _Pragma("unroll") for (int _i = 0; _i < 2; ++_i) \
;         __builtin_amdgcn_global_load_lds((const unsigned*)((const char*)(gbase) + (voff)[_i]), (LAS unsigned*)(lds + (bufoff) + ldsw + _i * 8192), 16, 0, 0); } while (0)
; #define PG8_LDA(dst, b, h) do { _Pragma("unroll") for (int m = 0; m < 4; ++m) _Pragma("unroll") for (int k = 0; k < 2; ++k) dst[m][k] = *(const LAS bf16x8*)(lds + PG8_SA(b, h) + aoff + m * 2048 + k * 1024); } while (0)
; #define PG8_LDB(dst, b, h) do { _Pragma("unroll") for (int n = 0; n < 2; ++n) _Pragma("unroll") for (int k = 0; k < 2; ++k) dst[n][k] = *(const LAS bf16x8*)(lds + PG8_SB(b, h) + boff + n * 2048 + k * 1024); } while (0)
; #define PG8_MMA(ai, bj, At, Bt) do { __builtin_amdgcn_s_setprio(1); _Pragma("unroll") for (int m = 0; m < 4; ++m) _Pragma("unroll") for (int n = 0; n < 2; ++n) _Pragma("unroll") for (int k = 0; k < 2; ++k) \
;         acc[ai][bj][m][n] = __builtin_amdgcn_mfma_f32_16x16x32_bf16(Bt[n][k], At[m][k], acc[ai][bj][m][n], 0, 0, 0); __builtin_amdgcn_s_setprio(0); } while (0)
; #define PG8_WAIT_V(n) asm volatile("s_waitcnt vmcnt(" #n ")" ::: "memory")
; #define PG8_WAIT_L(n) asm volatile("s_waitcnt lgkmcnt(" #n ")" ::: "memory")
; #define PG8_BAR __builtin_amdgcn_s_barrier()
; #define PG8_SCHED __builtin_amdgcn_sched_barrier(0)
; template <class GEO, class Epi>
; __device__ __forceinline__ void gemm_phase(LAS unsigned char* lds, const Gemm g, const StaticOrder& S, const Epi& E) {
;     ...
;             PG8_LDB(B0, 0, 0); PG8_LDB(B1, 0, 1); PG8_SCHED; PG8_LDA(At, 0, 0); PG8_STAGE(PG8_SA(1, 1), a1 + hstepA, voffA);
;             PG8_WAIT_V(8); PG8_WAIT_L(0); PG8_BAR; PG8_MMA(0, 0, At, B0); PG8_MMA(0, 1, At, B1); PG8_BAR; PG8_SCHED;
;             PG8_LDA(At, 0, 1); PG8_STAGE(PG8_SB(0, 0), b2, voffB); PG8_STAGE(PG8_SB(0, 1), b2 + hstepB, voffB); PG8_STAGE(PG8_SA(0, 0), a2, voffA);
;             PG8_WAIT_V(8); PG8_WAIT_L(0); PG8_BAR; PG8_MMA(1, 0, At, B0); PG8_MMA(1, 1, At, B1); PG8_BAR; PG8_SCHED;
.LBB0_232:
	ds_read_b128 v[128:131], v163
	ds_read_b128 v[132:135], v163 offset:1024
	ds_read_b128 v[156:159], v163 offset:2048
	ds_read_b128 v[166:169], v163 offset:3072
	ds_read_b128 v[170:173], v164
	ds_read_b128 v[174:177], v164 offset:1024
	ds_read_b128 v[178:181], v164 offset:2048
	ds_read_b128 v[182:185], v164 offset:3072
	s_add_u32 s8, s64, 0xfffc0080
	s_addc_u32 s9, s65, -1
	s_cmp_eq_u32 vcc_hi, 12
	s_cselect_b32 s93, s47, s9
	s_cselect_b32 s92, s52, s8
	s_cselect_b32 s89, s6, vcc_lo
	s_cselect_b32 s88, s53, s57
	v_lshl_add_u64 v[222:223], s[64:65], 0, v[150:151]
	s_add_i32 m0, s79, 0xc000
	ds_read_b128 v[186:189], v165
	ds_read_b128 v[190:193], v165 offset:1024
	ds_read_b128 v[194:197], v165 offset:2048
	ds_read_b128 v[198:201], v165 offset:3072
	ds_read_b128 v[202:205], v165 offset:4096
	ds_read_b128 v[210:213], v165 offset:5120
	ds_read_b128 v[214:217], v165 offset:6144
	ds_read_b128 v[218:221], v165 offset:7168
	global_load_lds_dwordx4 v[222:223], off
	v_lshl_add_u64 v[222:223], s[64:65], 0, v[152:153]
	s_add_i32 m0, s79, 0xe000
	s_nop 0
	global_load_lds_dwordx4 v[222:223], off
	s_waitcnt vmcnt(8)
	s_waitcnt lgkmcnt(0)
	s_barrier
	s_waitcnt lgkmcnt(0)
	v_mfma_f32_16x16x32_bf16 v[124:127], v[128:131], v[186:189], v[124:127]
	v_mfma_f32_16x16x32_bf16 v[120:123], v[156:159], v[186:189], v[120:123]
	v_mfma_f32_16x16x32_bf16 v[116:119], v[128:131], v[194:197], v[116:119]
	v_mfma_f32_16x16x32_bf16 v[112:115], v[156:159], v[194:197], v[112:115]
	v_mfma_f32_16x16x32_bf16 v[100:103], v[128:131], v[202:205], v[100:103]
	v_mfma_f32_16x16x32_bf16 v[96:99], v[156:159], v[202:205], v[96:99]
	v_mfma_f32_16x16x32_bf16 v[84:87], v[128:131], v[214:217], v[84:87]
	v_mfma_f32_16x16x32_bf16 v[80:83], v[156:159], v[214:217], v[80:83]
	v_mfma_f32_16x16x32_bf16 v[124:127], v[132:135], v[190:193], v[124:127]
	v_mfma_f32_16x16x32_bf16 v[120:123], v[166:169], v[190:193], v[120:123]
	v_mfma_f32_16x16x32_bf16 v[116:119], v[132:135], v[198:201], v[116:119]
	v_mfma_f32_16x16x32_bf16 v[112:115], v[166:169], v[198:201], v[112:115]
	v_mfma_f32_16x16x32_bf16 v[100:103], v[132:135], v[210:213], v[100:103]
	v_mfma_f32_16x16x32_bf16 v[96:99], v[166:169], v[210:213], v[96:99]
	v_mfma_f32_16x16x32_bf16 v[84:87], v[132:135], v[218:221], v[84:87]
	v_mfma_f32_16x16x32_bf16 v[80:83], v[166:169], v[218:221], v[80:83]
	v_mfma_f32_16x16x32_bf16 v[108:111], v[170:173], v[186:189], v[108:111]
	v_mfma_f32_16x16x32_bf16 v[104:107], v[178:181], v[186:189], v[104:107]
	v_mfma_f32_16x16x32_bf16 v[92:95], v[170:173], v[194:197], v[92:95]
	v_mfma_f32_16x16x32_bf16 v[88:91], v[178:181], v[194:197], v[88:91]
	v_mfma_f32_16x16x32_bf16 v[76:79], v[170:173], v[202:205], v[76:79]
	v_mfma_f32_16x16x32_bf16 v[72:75], v[178:181], v[202:205], v[72:75]
	v_mfma_f32_16x16x32_bf16 v[68:71], v[170:173], v[214:217], v[68:71]
	v_mfma_f32_16x16x32_bf16 v[64:67], v[178:181], v[214:217], v[64:67]
	v_mfma_f32_16x16x32_bf16 v[108:111], v[174:177], v[190:193], v[108:111]
	v_mfma_f32_16x16x32_bf16 v[104:107], v[182:185], v[190:193], v[104:107]
	v_mfma_f32_16x16x32_bf16 v[92:95], v[174:177], v[198:201], v[92:95]
	v_mfma_f32_16x16x32_bf16 v[88:91], v[182:185], v[198:201], v[88:91]
	v_mfma_f32_16x16x32_bf16 v[76:79], v[174:177], v[210:213], v[76:79]
	v_mfma_f32_16x16x32_bf16 v[72:75], v[182:185], v[210:213], v[72:75]
	v_mfma_f32_16x16x32_bf16 v[68:71], v[174:177], v[218:221], v[68:71]
	v_mfma_f32_16x16x32_bf16 v[64:67], v[182:185], v[218:221], v[64:67]
	s_barrier
	s_add_i32 s8, s54, s55
	v_lshl_add_u64 v[222:223], s[88:89], 0, v[140:141]
	s_mov_b32 m0, s8
	ds_read_b128 v[186:189], v165 offset:16384
	ds_read_b128 v[190:193], v165 offset:17408
	ds_read_b128 v[194:197], v165 offset:18432
	ds_read_b128 v[198:201], v165 offset:19456
	ds_read_b128 v[202:205], v165 offset:20480
	ds_read_b128 v[210:213], v165 offset:21504
	ds_read_b128 v[214:217], v165 offset:22528
	ds_read_b128 v[218:221], v165 offset:23552
	global_load_lds_dwordx4 v[222:223], off
	s_add_i32 m0, s8, 0x2000
	s_add_u32 s8, s88, 0x40000
	v_lshl_add_u64 v[224:225], s[88:89], 0, v[144:145]
	s_addc_u32 s9, s89, 0
	s_add_i32 s83, s34, s55
	global_load_lds_dwordx4 v[224:225], off
	v_lshl_add_u64 v[226:227], s[8:9], 0, v[140:141]
	s_mov_b32 m0, s83
	v_lshl_add_u64 v[228:229], s[92:93], 0, v[142:143]
	global_load_lds_dwordx4 v[226:227], off
	v_lshl_add_u64 v[226:227], s[8:9], 0, v[144:145]
	s_add_i32 m0, s83, 0x2000
	s_nop 0
	global_load_lds_dwordx4 v[226:227], off
	v_lshl_add_u64 v[226:227], s[92:93], 0, v[138:139]
	s_mov_b32 m0, s79
	s_nop 0
	global_load_lds_dwordx4 v[226:227], off
	s_mov_b32 m0, s81
	s_nop 0
	global_load_lds_dwordx4 v[228:229], off
	s_waitcnt vmcnt(8)
	s_waitcnt lgkmcnt(0)
	s_barrier
; #define PG8_STAGE(bufoff, gbase, voff) do { _Pragma("unroll") for (int _i = 0; _i < 2; ++_i) \
;         __builtin_amdgcn_global_load_lds((const unsigned*)((const char*)(gbase) + (voff)[_i]), (LAS unsigned*)(lds + (bufoff) + ldsw + _i * 8192), 16, 0, 0); } while (0)
; #define PG8_LDA(dst, b, h) do { _Pragma("unroll") for (int m = 0; m < 4; ++m) _Pragma("unroll") for (int k = 0; k < 2; ++k) dst[m][k] = *(const LAS bf16x8*)(lds + PG8_SA(b, h) + aoff + m * 2048 + k * 1024); } while (0)
; #define PG8_LDB(dst, b, h) do { _Pragma("unroll") for (int n = 0; n < 2; ++n) _Pragma("unroll") for (int k = 0; k < 2; ++k) dst[n][k] = *(const LAS bf16x8*)(lds + PG8_SB(b, h) + boff + n * 2048 + k * 1024); } while (0)
; #define PG8_MMA(ai, bj, At, Bt) do { __builtin_amdgcn_s_setprio(1); _Pragma("unroll") for (int m = 0; m < 4; ++m) _Pragma("unroll") for (int n = 0; n < 2; ++n) _Pragma("unroll") for (int k = 0; k < 2; ++k) \
;         acc[ai][bj][m][n] = __builtin_amdgcn_mfma_f32_16x16x32_bf16(Bt[n][k], At[m][k], acc[ai][bj][m][n], 0, 0, 0); __builtin_amdgcn_s_setprio(0); } while (0)
; #define PG8_WAIT_V(n) asm volatile("s_waitcnt vmcnt(" #n ")" ::: "memory")
; #define PG8_WAIT_L(n) asm volatile("s_waitcnt lgkmcnt(" #n ")" ::: "memory")
; #define PG8_BAR __builtin_amdgcn_s_barrier()
; #define PG8_SCHED __builtin_amdgcn_sched_barrier(0)
; template <class GEO, class Epi>
; __device__ __forceinline__ void gemm_phase(LAS unsigned char* lds, const Gemm g, const StaticOrder& S, const Epi& E) {
;     ...
;             PG8_WAIT_V(8); PG8_WAIT_L(0); PG8_BAR; PG8_MMA(1, 0, At, B0); PG8_MMA(1, 1, At, B1); PG8_BAR; PG8_SCHED;
;             PG8_LDB(B0, 1, 0); PG8_LDB(B1, 1, 1); PG8_SCHED; PG8_LDA(At, 1, 0); PG8_STAGE(PG8_SA(0, 1), a2 + hstepA, voffA);
;             PG8_WAIT_V(8); PG8_WAIT_L(0); PG8_BAR; PG8_MMA(0, 0, At, B0); PG8_MMA(0, 1, At, B1); PG8_BAR; PG8_SCHED;
	s_waitcnt lgkmcnt(0)
	v_mfma_f32_16x16x32_bf16 v[60:63], v[128:131], v[186:189], v[60:63]
	v_mfma_f32_16x16x32_bf16 v[56:59], v[156:159], v[186:189], v[56:59]
	v_mfma_f32_16x16x32_bf16 v[52:55], v[128:131], v[194:197], v[52:55]
	v_mfma_f32_16x16x32_bf16 v[48:51], v[156:159], v[194:197], v[48:51]
	v_mfma_f32_16x16x32_bf16 v[36:39], v[128:131], v[202:205], v[36:39]
	v_mfma_f32_16x16x32_bf16 v[32:35], v[156:159], v[202:205], v[32:35]
	v_mfma_f32_16x16x32_bf16 v[20:23], v[128:131], v[214:217], v[20:23]
	v_mfma_f32_16x16x32_bf16 v[16:19], v[156:159], v[214:217], v[16:19]
	v_mfma_f32_16x16x32_bf16 v[60:63], v[132:135], v[190:193], v[60:63]
	v_mfma_f32_16x16x32_bf16 v[56:59], v[166:169], v[190:193], v[56:59]
	v_mfma_f32_16x16x32_bf16 v[52:55], v[132:135], v[198:201], v[52:55]
	v_mfma_f32_16x16x32_bf16 v[48:51], v[166:169], v[198:201], v[48:51]
	v_mfma_f32_16x16x32_bf16 v[36:39], v[132:135], v[210:213], v[36:39]
	v_mfma_f32_16x16x32_bf16 v[32:35], v[166:169], v[210:213], v[32:35]
	v_mfma_f32_16x16x32_bf16 v[20:23], v[132:135], v[218:221], v[20:23]
	v_mfma_f32_16x16x32_bf16 v[16:19], v[166:169], v[218:221], v[16:19]
	v_mfma_f32_16x16x32_bf16 v[44:47], v[170:173], v[186:189], v[44:47]
	v_mfma_f32_16x16x32_bf16 v[40:43], v[178:181], v[186:189], v[40:43]
	v_mfma_f32_16x16x32_bf16 v[28:31], v[170:173], v[194:197], v[28:31]
	v_mfma_f32_16x16x32_bf16 v[24:27], v[178:181], v[194:197], v[24:27]
	v_mfma_f32_16x16x32_bf16 v[12:15], v[170:173], v[202:205], v[12:15]
	v_mfma_f32_16x16x32_bf16 v[8:11], v[178:181], v[202:205], v[8:11]
	v_mfma_f32_16x16x32_bf16 v[4:7], v[170:173], v[214:217], v[4:7]
	v_mfma_f32_16x16x32_bf16 v[0:3], v[178:181], v[214:217], v[0:3]
	v_mfma_f32_16x16x32_bf16 v[44:47], v[174:177], v[190:193], v[44:47]
	v_mfma_f32_16x16x32_bf16 v[40:43], v[182:185], v[190:193], v[40:43]
	v_mfma_f32_16x16x32_bf16 v[28:31], v[174:177], v[198:201], v[28:31]
	v_mfma_f32_16x16x32_bf16 v[24:27], v[182:185], v[198:201], v[24:27]
	v_mfma_f32_16x16x32_bf16 v[12:15], v[174:177], v[210:213], v[12:15]
	v_mfma_f32_16x16x32_bf16 v[8:11], v[182:185], v[210:213], v[8:11]
	v_mfma_f32_16x16x32_bf16 v[4:7], v[174:177], v[218:221], v[4:7]
	v_mfma_f32_16x16x32_bf16 v[0:3], v[182:185], v[218:221], v[0:3]
	s_barrier
	s_add_i32 s83, 0, 0x18000
	v_add_u32_e32 v155, s83, v161
	s_add_i32 s0, 0, 0x1c000
	ds_read_b128 v[128:131], v155
	ds_read_b128 v[132:135], v155 offset:1024
	ds_read_b128 v[156:159], v155 offset:2048
	ds_read_b128 v[166:169], v155 offset:3072
	v_add_u32_e32 v155, s0, v161
	ds_read_b128 v[170:173], v155
	ds_read_b128 v[174:177], v155 offset:1024
	ds_read_b128 v[178:181], v155 offset:2048
	ds_read_b128 v[182:185], v155 offset:3072
	s_add_u32 s8, s92, 0x40000
	s_addc_u32 s9, s93, 0
	s_mov_b32 m0, s84
	v_lshl_add_u64 v[230:231], s[8:9], 0, v[138:139]
	ds_read_b128 v[186:189], v165 offset:32768
	ds_read_b128 v[190:193], v165 offset:33792
	ds_read_b128 v[194:197], v165 offset:34816
	ds_read_b128 v[198:201], v165 offset:35840
	ds_read_b128 v[202:205], v165 offset:36864
	ds_read_b128 v[210:213], v165 offset:37888
	ds_read_b128 v[214:217], v165 offset:38912
	ds_read_b128 v[218:221], v165 offset:39936
	global_load_lds_dwordx4 v[230:231], off
	v_lshl_add_u64 v[230:231], s[8:9], 0, v[142:143]
	s_mov_b32 m0, s85
	s_nop 0
	global_load_lds_dwordx4 v[230:231], off
	s_waitcnt vmcnt(8)
	s_waitcnt lgkmcnt(0)
	s_barrier
	s_waitcnt lgkmcnt(0)
	v_mfma_f32_16x16x32_bf16 v[124:127], v[128:131], v[186:189], v[124:127]
	v_mfma_f32_16x16x32_bf16 v[120:123], v[156:159], v[186:189], v[120:123]
	v_mfma_f32_16x16x32_bf16 v[116:119], v[128:131], v[194:197], v[116:119]
	v_mfma_f32_16x16x32_bf16 v[112:115], v[156:159], v[194:197], v[112:115]
	v_mfma_f32_16x16x32_bf16 v[100:103], v[128:131], v[202:205], v[100:103]
	v_mfma_f32_16x16x32_bf16 v[96:99], v[156:159], v[202:205], v[96:99]
	v_mfma_f32_16x16x32_bf16 v[84:87], v[128:131], v[214:217], v[84:87]
	v_mfma_f32_16x16x32_bf16 v[80:83], v[156:159], v[214:217], v[80:83]
	v_mfma_f32_16x16x32_bf16 v[124:127], v[132:135], v[190:193], v[124:127]
	v_mfma_f32_16x16x32_bf16 v[120:123], v[166:169], v[190:193], v[120:123]
	v_mfma_f32_16x16x32_bf16 v[116:119], v[132:135], v[198:201], v[116:119]
	v_mfma_f32_16x16x32_bf16 v[112:115], v[166:169], v[198:201], v[112:115]
	v_mfma_f32_16x16x32_bf16 v[100:103], v[132:135], v[210:213], v[100:103]
	v_mfma_f32_16x16x32_bf16 v[96:99], v[166:169], v[210:213], v[96:99]
	v_mfma_f32_16x16x32_bf16 v[84:87], v[132:135], v[218:221], v[84:87]
	v_mfma_f32_16x16x32_bf16 v[80:83], v[166:169], v[218:221], v[80:83]
	v_mfma_f32_16x16x32_bf16 v[108:111], v[170:173], v[186:189], v[108:111]
	v_mfma_f32_16x16x32_bf16 v[104:107], v[178:181], v[186:189], v[104:107]
	v_mfma_f32_16x16x32_bf16 v[92:95], v[170:173], v[194:197], v[92:95]
	v_mfma_f32_16x16x32_bf16 v[88:91], v[178:181], v[194:197], v[88:91]
	v_mfma_f32_16x16x32_bf16 v[76:79], v[170:173], v[202:205], v[76:79]
	v_mfma_f32_16x16x32_bf16 v[72:75], v[178:181], v[202:205], v[72:75]
	v_mfma_f32_16x16x32_bf16 v[68:71], v[170:173], v[214:217], v[68:71]
	v_mfma_f32_16x16x32_bf16 v[64:67], v[178:181], v[214:217], v[64:67]
	v_mfma_f32_16x16x32_bf16 v[108:111], v[174:177], v[190:193], v[108:111]
	v_mfma_f32_16x16x32_bf16 v[104:107], v[182:185], v[190:193], v[104:107]
	v_mfma_f32_16x16x32_bf16 v[92:95], v[174:177], v[198:201], v[92:95]
	v_mfma_f32_16x16x32_bf16 v[88:91], v[182:185], v[198:201], v[88:91]
	v_mfma_f32_16x16x32_bf16 v[76:79], v[174:177], v[210:213], v[76:79]
	v_mfma_f32_16x16x32_bf16 v[72:75], v[182:185], v[210:213], v[72:75]
	v_mfma_f32_16x16x32_bf16 v[68:71], v[174:177], v[218:221], v[68:71]
	v_mfma_f32_16x16x32_bf16 v[64:67], v[182:185], v[218:221], v[64:67]
	s_barrier
; #define PG8_STAGE(bufoff, gbase, voff) do { _Pragma("unroll") for (int _i = 0; _i < 2; ++_i) \
;         __builtin_amdgcn_global_load_lds((const unsigned*)((const char*)(gbase) + (voff)[_i]), (LAS unsigned*)(lds + (bufoff) + ldsw + _i * 8192), 16, 0, 0); } while (0)
; #define PG8_LDA(dst, b, h) do { _Pragma("unroll") for (int m = 0; m < 4; ++m) _Pragma("unroll") for (int k = 0; k < 2; ++k) dst[m][k] = *(const LAS bf16x8*)(lds + PG8_SA(b, h) + aoff + m * 2048 + k * 1024); } while (0)
; #define PG8_MMA(ai, bj, At, Bt) do { __builtin_amdgcn_s_setprio(1); _Pragma("unroll") for (int m = 0; m < 4; ++m) _Pragma("unroll") for (int n = 0; n < 2; ++n) _Pragma("unroll") for (int k = 0; k < 2; ++k) \
;         acc[ai][bj][m][n] = __builtin_amdgcn_mfma_f32_16x16x32_bf16(Bt[n][k], At[m][k], acc[ai][bj][m][n], 0, 0, 0); __builtin_amdgcn_s_setprio(0); } while (0)
; #define PG8_WAIT_V(n) asm volatile("s_waitcnt vmcnt(" #n ")" ::: "memory")
; #define PG8_WAIT_L(n) asm volatile("s_waitcnt lgkmcnt(" #n ")" ::: "memory")
; #define PG8_BAR __builtin_amdgcn_s_barrier()
; #define PG8_SCHED __builtin_amdgcn_sched_barrier(0)
; template <class GEO, class Epi>
; __device__ __forceinline__ void gemm_phase(LAS unsigned char* lds, const Gemm g, const StaticOrder& S, const Epi& E) {
;     ...
;             PG8_LDA(At, 1, 1); PG8_STAGE(PG8_SB(1, 0), b3, voffB); PG8_STAGE(PG8_SB(1, 1), b3 + hstepB, voffB); PG8_STAGE(PG8_SA(1, 0), a3, voffA);
;             PG8_WAIT_V(8); PG8_WAIT_L(0); PG8_BAR; PG8_MMA(1, 0, At, B0); PG8_MMA(1, 1, At, B1); PG8_BAR; PG8_SCHED;
;         }
;         if (wr == 0) PG8_BAR;
	s_add_i32 s1, s83, s55
	v_lshl_add_u64 v[222:223], v[222:223], 0, s[22:23]
	s_mov_b32 m0, s1
	ds_read_b128 v[186:189], v165 offset:49152
	ds_read_b128 v[190:193], v165 offset:50176
	ds_read_b128 v[194:197], v165 offset:51200
	ds_read_b128 v[198:201], v165 offset:52224
	ds_read_b128 v[202:205], v165 offset:53248
	ds_read_b128 v[210:213], v165 offset:54272
	ds_read_b128 v[214:217], v165 offset:55296
	ds_read_b128 v[218:221], v165 offset:56320
	global_load_lds_dwordx4 v[222:223], off
	s_add_i32 m0, s1, 0x2000
	s_add_u32 s8, s88, 0x40080
	v_lshl_add_u64 v[222:223], v[224:225], 0, s[22:23]
	s_addc_u32 s9, s89, 0
	s_add_i32 s0, s0, s55
	global_load_lds_dwordx4 v[222:223], off
	v_lshl_add_u64 v[222:223], s[8:9], 0, v[140:141]
	s_mov_b32 m0, s0
	s_nop 0
	global_load_lds_dwordx4 v[222:223], off
	v_lshl_add_u64 v[222:223], s[8:9], 0, v[144:145]
	s_add_i32 m0, s0, 0x2000
	s_nop 0
	global_load_lds_dwordx4 v[222:223], off
	v_lshl_add_u64 v[222:223], v[226:227], 0, s[22:23]
	s_mov_b32 m0, s86
	s_nop 0
	global_load_lds_dwordx4 v[222:223], off
	v_lshl_add_u64 v[222:223], v[228:229], 0, s[22:23]
	s_mov_b32 m0, s87
	s_nop 0
	global_load_lds_dwordx4 v[222:223], off
	s_waitcnt vmcnt(8)
	s_waitcnt lgkmcnt(0)
	s_barrier
	s_waitcnt lgkmcnt(0)
	v_mfma_f32_16x16x32_bf16 v[60:63], v[128:131], v[186:189], v[60:63]
	v_mfma_f32_16x16x32_bf16 v[56:59], v[156:159], v[186:189], v[56:59]
	v_mfma_f32_16x16x32_bf16 v[52:55], v[128:131], v[194:197], v[52:55]
	v_mfma_f32_16x16x32_bf16 v[48:51], v[156:159], v[194:197], v[48:51]
	v_mfma_f32_16x16x32_bf16 v[36:39], v[128:131], v[202:205], v[36:39]
	v_mfma_f32_16x16x32_bf16 v[32:35], v[156:159], v[202:205], v[32:35]
	v_mfma_f32_16x16x32_bf16 v[20:23], v[128:131], v[214:217], v[20:23]
	v_mfma_f32_16x16x32_bf16 v[16:19], v[156:159], v[214:217], v[16:19]
	v_mfma_f32_16x16x32_bf16 v[60:63], v[132:135], v[190:193], v[60:63]
	v_mfma_f32_16x16x32_bf16 v[56:59], v[166:169], v[190:193], v[56:59]
	v_mfma_f32_16x16x32_bf16 v[52:55], v[132:135], v[198:201], v[52:55]
	v_mfma_f32_16x16x32_bf16 v[48:51], v[166:169], v[198:201], v[48:51]
	v_mfma_f32_16x16x32_bf16 v[36:39], v[132:135], v[210:213], v[36:39]
	v_mfma_f32_16x16x32_bf16 v[32:35], v[166:169], v[210:213], v[32:35]
	v_mfma_f32_16x16x32_bf16 v[20:23], v[132:135], v[218:221], v[20:23]
	v_mfma_f32_16x16x32_bf16 v[16:19], v[166:169], v[218:221], v[16:19]
	v_mfma_f32_16x16x32_bf16 v[44:47], v[170:173], v[186:189], v[44:47]
	v_mfma_f32_16x16x32_bf16 v[40:43], v[178:181], v[186:189], v[40:43]
	v_mfma_f32_16x16x32_bf16 v[28:31], v[170:173], v[194:197], v[28:31]
	v_mfma_f32_16x16x32_bf16 v[24:27], v[178:181], v[194:197], v[24:27]
	v_mfma_f32_16x16x32_bf16 v[12:15], v[170:173], v[202:205], v[12:15]
	v_mfma_f32_16x16x32_bf16 v[8:11], v[178:181], v[202:205], v[8:11]
	v_mfma_f32_16x16x32_bf16 v[4:7], v[170:173], v[214:217], v[4:7]
	v_mfma_f32_16x16x32_bf16 v[0:3], v[178:181], v[214:217], v[0:3]
	v_mfma_f32_16x16x32_bf16 v[44:47], v[174:177], v[190:193], v[44:47]
	v_mfma_f32_16x16x32_bf16 v[40:43], v[182:185], v[190:193], v[40:43]
	v_mfma_f32_16x16x32_bf16 v[28:31], v[174:177], v[198:201], v[28:31]
	v_mfma_f32_16x16x32_bf16 v[24:27], v[182:185], v[198:201], v[24:27]
	v_mfma_f32_16x16x32_bf16 v[12:15], v[174:177], v[210:213], v[12:15]
	v_mfma_f32_16x16x32_bf16 v[8:11], v[182:185], v[210:213], v[8:11]
	v_mfma_f32_16x16x32_bf16 v[4:7], v[174:177], v[218:221], v[4:7]
	v_mfma_f32_16x16x32_bf16 v[0:3], v[182:185], v[218:221], v[0:3]
	s_add_i32 vcc_hi, vcc_hi, 2
	s_add_u32 s64, s64, 0x100
	s_addc_u32 s65, s65, 0
	s_add_u32 s57, s57, 0x100
	s_addc_u32 vcc_lo, vcc_lo, 0
	s_cmp_gt_u32 vcc_hi, 13
	s_cbranch_scc0 .Lrot_1
	s_barrier
	s_and_b64 vcc, exec, s[36:37]
	s_cbranch_vccz .LBB0_235
	s_barrier

; template <class GEO, class Epi>
; __device__ __forceinline__ void gemm_phase(LAS unsigned char* lds, const Gemm g, const StaticOrder& S, const Epi& E) {
;     ...
;         const bool has_next = S.next(ui + 1, nxt);
;         const char* nA = has_next ? PG8_APTR(nxt) : cA; const char* nB = has_next ? PG8_BPTR(nxt) : cB;
; #pragma nounroll
;         for (int t = 0; t < nt; t += 2) {
;             const bool last = (t == nt - 2);
;             const char* a1 = cA + (size_t)(t + 1) * kstep;
;             const char* a2 = last ? nA : cA + (size_t)(t + 2) * kstep; const char* b2 = last ? nB : cB + (size_t)(t + 2) * kstep;
;     ...
; #pragma unroll
;         for (int a = 0; a < 2; ++a)
; #pragma unroll
;             for (int b = 0; b < 2; ++b)
; #pragma unroll
;                 for (int m = 0; m < 4; ++m)
; #pragma unroll
;                     for (int n = 0; n < 2; ++n) acc[a][b][m][n] = (f32x4){0.f, 0.f, 0.f, 0.f};
;         cur = nxt; cA = nA; cB = nB; ++ui;
.LBB0_690:
	s_ashr_i32 s47, s46, 31
	s_lshl_b64 s[8:9], s[46:47], 19
	s_add_u32 s48, s83, s8
	s_addc_u32 s49, s88, s9
	s_and_b64 s[8:9], s[44:45], exec
	s_cselect_b32 s21, s49, s55
	s_cselect_b32 s47, s48, s54
	s_and_b32 s22, s66, 0x3fffffff
	s_lshl_b64 s[8:9], s[22:23], 19
	v_readlane_b32 s38, v254, 35
	v_readlane_b32 s39, v254, 36
	s_add_u32 s50, s38, s8
	s_addc_u32 s51, s39, s9
	s_and_b64 s[8:9], s[44:45], exec
	s_cselect_b32 s22, s51, s57
	s_cselect_b32 s53, s50, s56
	s_add_u32 s54, s54, 0x40080
	s_addc_u32 s55, s55, 0
	s_add_u32 s67, s56, 0x100
	v_mov_b32_e32 v0, 0
	s_addc_u32 s68, s57, 0
	s_mov_b32 s69, -2
	s_waitcnt lgkmcnt(0)
	v_mov_b32_e32 v1, v0
	v_mov_b32_e32 v2, v0
	v_mov_b32_e32 v3, v0
	v_mov_b32_e32 v4, v0
	v_mov_b32_e32 v5, v0
	v_mov_b32_e32 v6, v0
	v_mov_b32_e32 v7, v0
	v_mov_b32_e32 v16, v0
	v_mov_b32_e32 v17, v0
	v_mov_b32_e32 v18, v0
	v_mov_b32_e32 v19, v0
	v_mov_b32_e32 v20, v0
	v_mov_b32_e32 v21, v0
	v_mov_b32_e32 v22, v0
	v_mov_b32_e32 v23, v0
	v_mov_b32_e32 v32, v0
	v_mov_b32_e32 v33, v0
	v_mov_b32_e32 v34, v0
	v_mov_b32_e32 v35, v0
	v_mov_b32_e32 v36, v0
	v_mov_b32_e32 v37, v0
	v_mov_b32_e32 v38, v0
	v_mov_b32_e32 v39, v0
	v_mov_b32_e32 v48, v0
	v_mov_b32_e32 v49, v0
	v_mov_b32_e32 v50, v0
	v_mov_b32_e32 v51, v0
	v_mov_b32_e32 v52, v0
	v_mov_b32_e32 v53, v0
	v_mov_b32_e32 v54, v0
	v_mov_b32_e32 v55, v0
	v_mov_b32_e32 v8, v0
	v_mov_b32_e32 v9, v0
	v_mov_b32_e32 v10, v0
	v_mov_b32_e32 v11, v0
	v_mov_b32_e32 v12, v0
	v_mov_b32_e32 v13, v0
	v_mov_b32_e32 v14, v0
	v_mov_b32_e32 v15, v0
	v_mov_b32_e32 v24, v0
	v_mov_b32_e32 v25, v0
	v_mov_b32_e32 v26, v0
	v_mov_b32_e32 v27, v0
	v_mov_b32_e32 v28, v0
	v_mov_b32_e32 v29, v0
	v_mov_b32_e32 v30, v0
	v_mov_b32_e32 v31, v0
	v_mov_b32_e32 v40, v0
	v_mov_b32_e32 v41, v0
	v_mov_b32_e32 v42, v0
	v_mov_b32_e32 v43, v0
	v_mov_b32_e32 v44, v0
	v_mov_b32_e32 v45, v0
	v_mov_b32_e32 v46, v0
	v_mov_b32_e32 v47, v0
	v_mov_b32_e32 v56, v0
	v_mov_b32_e32 v57, v0
	v_mov_b32_e32 v58, v0
	v_mov_b32_e32 v59, v0
	v_mov_b32_e32 v60, v0
	v_mov_b32_e32 v61, v0
	v_mov_b32_e32 v62, v0
	v_mov_b32_e32 v63, v0
	v_mov_b32_e32 v64, v0
	v_mov_b32_e32 v65, v0
	v_mov_b32_e32 v66, v0
	v_mov_b32_e32 v67, v0
	v_mov_b32_e32 v68, v0
	v_mov_b32_e32 v69, v0
	v_mov_b32_e32 v70, v0
	v_mov_b32_e32 v71, v0
	v_mov_b32_e32 v80, v0
	v_mov_b32_e32 v81, v0
	v_mov_b32_e32 v82, v0
	v_mov_b32_e32 v83, v0
	v_mov_b32_e32 v84, v0
	v_mov_b32_e32 v85, v0
	v_mov_b32_e32 v86, v0
	v_mov_b32_e32 v87, v0
	v_mov_b32_e32 v96, v0
	v_mov_b32_e32 v97, v0
	s_waitcnt vmcnt(0)
	v_mov_b32_e32 v98, v0
	v_mov_b32_e32 v99, v0
	v_mov_b32_e32 v100, v0
	v_mov_b32_e32 v101, v0
	v_mov_b32_e32 v102, v0
	v_mov_b32_e32 v103, v0
	v_mov_b32_e32 v112, v0
	v_mov_b32_e32 v113, v0
	v_mov_b32_e32 v114, v0
	v_mov_b32_e32 v115, v0
	v_mov_b32_e32 v116, v0
	v_mov_b32_e32 v117, v0
	v_mov_b32_e32 v118, v0
	v_mov_b32_e32 v119, v0
	v_mov_b32_e32 v72, v0
	v_mov_b32_e32 v73, v0
	v_mov_b32_e32 v74, v0
	v_mov_b32_e32 v75, v0
	v_mov_b32_e32 v76, v0
	v_mov_b32_e32 v77, v0
	v_mov_b32_e32 v78, v0
	v_mov_b32_e32 v79, v0
	v_mov_b32_e32 v88, v0
	v_mov_b32_e32 v89, v0
	v_mov_b32_e32 v90, v0
	v_mov_b32_e32 v91, v0
	v_mov_b32_e32 v92, v0
	v_mov_b32_e32 v93, v0
	v_mov_b32_e32 v94, v0
	v_mov_b32_e32 v95, v0
	v_mov_b32_e32 v104, v0
	v_mov_b32_e32 v105, v0
	v_mov_b32_e32 v106, v0
	v_mov_b32_e32 v107, v0
	v_mov_b32_e32 v108, v0
	v_mov_b32_e32 v109, v0
	v_mov_b32_e32 v110, v0
	v_mov_b32_e32 v111, v0
	v_mov_b32_e32 v120, v0
	v_mov_b32_e32 v121, v0
	v_mov_b32_e32 v122, v0
	v_mov_b32_e32 v123, v0
	v_mov_b32_e32 v124, v0
	v_mov_b32_e32 v125, v0
	v_mov_b32_e32 v126, v0
	v_mov_b32_e32 v127, v0
	s_branch .LBB0_691

; #define PG8_STAGE(bufoff, gbase, voff) do { _Pragma("unroll") for (int _i = 0; _i < 2; ++_i) \
;         __builtin_amdgcn_global_load_lds((const unsigned*)((const char*)(gbase) + (voff)[_i]), (LAS unsigned*)(lds + (bufoff) + ldsw + _i * 8192), 16, 0, 0); } while (0)
; #define PG8_LDA(dst, b, h) do { _Pragma("unroll") for (int m = 0; m < 4; ++m) _Pragma("unroll") for (int k = 0; k < 2; ++k) dst[m][k] = *(const LAS bf16x8*)(lds + PG8_SA(b, h) + aoff + m * 2048 + k * 1024); } while (0)
; #define PG8_LDB(dst, b, h) do { _Pragma("unroll") for (int n = 0; n < 2; ++n) _Pragma("unroll") for (int k = 0; k < 2; ++k) dst[n][k] = *(const LAS bf16x8*)(lds + PG8_SB(b, h) + boff + n * 2048 + k * 1024); } while (0)
; #define PG8_MMA(ai, bj, At, Bt) do { __builtin_amdgcn_s_setprio(1); _Pragma("unroll") for (int m = 0; m < 4; ++m) _Pragma("unroll") for (int n = 0; n < 2; ++n) _Pragma("unroll") for (int k = 0; k < 2; ++k) \
;         acc[ai][bj][m][n] = __builtin_amdgcn_mfma_f32_16x16x32_bf16(Bt[n][k], At[m][k], acc[ai][bj][m][n], 0, 0, 0); __builtin_amdgcn_s_setprio(0); } while (0)
; #define PG8_WAIT_V(n) asm volatile("s_waitcnt vmcnt(" #n ")" ::: "memory")
; #define PG8_WAIT_L(n) asm volatile("s_waitcnt lgkmcnt(" #n ")" ::: "memory")
; #define PG8_BAR __builtin_amdgcn_s_barrier()
; #define PG8_SCHED __builtin_amdgcn_sched_barrier(0)
; template <class GEO, class Epi>
; __device__ __forceinline__ void gemm_phase(LAS unsigned char* lds, const Gemm g, const StaticOrder& S, const Epi& E) {
;     ...
;             PG8_LDB(B0, 0, 0); PG8_LDB(B1, 0, 1); PG8_SCHED; PG8_LDA(At, 0, 0); PG8_STAGE(PG8_SA(1, 1), a1 + hstepA, voffA);
;             PG8_WAIT_V(8); PG8_WAIT_L(0); PG8_BAR; PG8_MMA(0, 0, At, B0); PG8_MMA(0, 1, At, B1); PG8_BAR; PG8_SCHED;
;             PG8_LDA(At, 0, 1); PG8_STAGE(PG8_SB(0, 0), b2, voffB); PG8_STAGE(PG8_SB(0, 1), b2 + hstepB, voffB); PG8_STAGE(PG8_SA(0, 0), a2, voffA);
;             PG8_WAIT_V(8); PG8_WAIT_L(0); PG8_BAR; PG8_MMA(1, 0, At, B0); PG8_MMA(1, 1, At, B1); PG8_BAR; PG8_SCHED;
.LBB0_691:
	ds_read_b128 v[144:147], v152
	ds_read_b128 v[156:159], v152 offset:1024
	ds_read_b128 v[166:169], v152 offset:2048
	ds_read_b128 v[170:173], v152 offset:3072
	ds_read_b128 v[174:177], v153
	ds_read_b128 v[178:181], v153 offset:1024
	ds_read_b128 v[182:185], v153 offset:2048
	ds_read_b128 v[186:189], v153 offset:3072
	s_add_u32 s8, s54, 0xfffc0080
	s_addc_u32 s9, s55, -1
	s_cmp_eq_u32 s69, 12
	s_cselect_b32 s59, s21, s9
	s_cselect_b32 s58, s47, s8
	s_cselect_b32 s57, s22, s68
	s_cselect_b32 s56, s53, s67
	v_lshl_add_u64 v[160:161], s[54:55], 0, v[136:137]
	s_add_i32 m0, s1, 0xc000
	ds_read_b128 v[190:193], v154
	ds_read_b128 v[194:197], v154 offset:1024
	ds_read_b128 v[198:201], v154 offset:2048
	ds_read_b128 v[202:205], v154 offset:3072
	ds_read_b128 v[212:215], v154 offset:4096
	ds_read_b128 v[216:219], v154 offset:5120
	ds_read_b128 v[220:223], v154 offset:6144
	ds_read_b128 v[224:227], v154 offset:7168
	global_load_lds_dwordx4 v[160:161], off
	v_lshl_add_u64 v[160:161], s[54:55], 0, v[138:139]
	s_add_i32 m0, s1, 0xe000
	s_nop 0
	global_load_lds_dwordx4 v[160:161], off
	s_waitcnt vmcnt(8)
	s_waitcnt lgkmcnt(0)
	s_barrier
	s_waitcnt lgkmcnt(0)
	v_mfma_f32_16x16x32_bf16 v[124:127], v[144:147], v[190:193], v[124:127]
	v_mfma_f32_16x16x32_bf16 v[120:123], v[166:169], v[190:193], v[120:123]
	v_mfma_f32_16x16x32_bf16 v[108:111], v[144:147], v[198:201], v[108:111]
	v_mfma_f32_16x16x32_bf16 v[104:107], v[166:169], v[198:201], v[104:107]
	v_mfma_f32_16x16x32_bf16 v[92:95], v[144:147], v[212:215], v[92:95]
	v_mfma_f32_16x16x32_bf16 v[88:91], v[166:169], v[212:215], v[88:91]
	v_mfma_f32_16x16x32_bf16 v[76:79], v[144:147], v[220:223], v[76:79]
	v_mfma_f32_16x16x32_bf16 v[72:75], v[166:169], v[220:223], v[72:75]
	v_mfma_f32_16x16x32_bf16 v[124:127], v[156:159], v[194:197], v[124:127]
	v_mfma_f32_16x16x32_bf16 v[120:123], v[170:173], v[194:197], v[120:123]
	v_mfma_f32_16x16x32_bf16 v[108:111], v[156:159], v[202:205], v[108:111]
	v_mfma_f32_16x16x32_bf16 v[104:107], v[170:173], v[202:205], v[104:107]
	v_mfma_f32_16x16x32_bf16 v[92:95], v[156:159], v[216:219], v[92:95]
	v_mfma_f32_16x16x32_bf16 v[88:91], v[170:173], v[216:219], v[88:91]
	v_mfma_f32_16x16x32_bf16 v[76:79], v[156:159], v[224:227], v[76:79]
	v_mfma_f32_16x16x32_bf16 v[72:75], v[170:173], v[224:227], v[72:75]
	v_mfma_f32_16x16x32_bf16 v[116:119], v[174:177], v[190:193], v[116:119]
	v_mfma_f32_16x16x32_bf16 v[112:115], v[182:185], v[190:193], v[112:115]
	v_mfma_f32_16x16x32_bf16 v[100:103], v[174:177], v[198:201], v[100:103]
	v_mfma_f32_16x16x32_bf16 v[96:99], v[182:185], v[198:201], v[96:99]
	v_mfma_f32_16x16x32_bf16 v[84:87], v[174:177], v[212:215], v[84:87]
	v_mfma_f32_16x16x32_bf16 v[80:83], v[182:185], v[212:215], v[80:83]
	v_mfma_f32_16x16x32_bf16 v[68:71], v[174:177], v[220:223], v[68:71]
	v_mfma_f32_16x16x32_bf16 v[64:67], v[182:185], v[220:223], v[64:67]
	v_mfma_f32_16x16x32_bf16 v[116:119], v[178:181], v[194:197], v[116:119]
	v_mfma_f32_16x16x32_bf16 v[112:115], v[186:189], v[194:197], v[112:115]
	v_mfma_f32_16x16x32_bf16 v[100:103], v[178:181], v[202:205], v[100:103]
	v_mfma_f32_16x16x32_bf16 v[96:99], v[186:189], v[202:205], v[96:99]
	v_mfma_f32_16x16x32_bf16 v[84:87], v[178:181], v[216:219], v[84:87]
	v_mfma_f32_16x16x32_bf16 v[80:83], v[186:189], v[216:219], v[80:83]
	v_mfma_f32_16x16x32_bf16 v[68:71], v[178:181], v[224:227], v[68:71]
	v_mfma_f32_16x16x32_bf16 v[64:67], v[186:189], v[224:227], v[64:67]
	s_barrier
	s_add_i32 s8, s63, s0
	v_lshl_add_u64 v[160:161], s[56:57], 0, v[130:131]
	s_mov_b32 m0, s8
	ds_read_b128 v[190:193], v154 offset:16384
	ds_read_b128 v[194:197], v154 offset:17408
	ds_read_b128 v[198:201], v154 offset:18432
	ds_read_b128 v[202:205], v154 offset:19456
	ds_read_b128 v[212:215], v154 offset:20480
	ds_read_b128 v[216:219], v154 offset:21504
	ds_read_b128 v[220:223], v154 offset:22528
	ds_read_b128 v[224:227], v154 offset:23552
	global_load_lds_dwordx4 v[160:161], off
	s_add_i32 m0, s8, 0x2000
	s_add_u32 s8, s56, 0x40000
	v_lshl_add_u64 v[206:207], s[56:57], 0, v[134:135]
	s_addc_u32 s9, s57, 0
	s_add_i32 s38, s64, s0
	global_load_lds_dwordx4 v[206:207], off
	v_lshl_add_u64 v[228:229], s[8:9], 0, v[130:131]
	s_mov_b32 m0, s38
	v_lshl_add_u64 v[230:231], s[58:59], 0, v[132:133]
	global_load_lds_dwordx4 v[228:229], off
	v_lshl_add_u64 v[228:229], s[8:9], 0, v[134:135]
	s_add_i32 m0, s38, 0x2000
	s_nop 0
	global_load_lds_dwordx4 v[228:229], off
	v_lshl_add_u64 v[228:229], s[58:59], 0, v[128:129]
	s_mov_b32 m0, s1
	s_nop 0
	global_load_lds_dwordx4 v[228:229], off
	s_mov_b32 m0, s4
	s_nop 0
	global_load_lds_dwordx4 v[230:231], off
	s_waitcnt vmcnt(8)
	s_waitcnt lgkmcnt(0)
	s_barrier
; #define PG8_STAGE(bufoff, gbase, voff) do { _Pragma("unroll") for (int _i = 0; _i < 2; ++_i) \
;         __builtin_amdgcn_global_load_lds((const unsigned*)((const char*)(gbase) + (voff)[_i]), (LAS unsigned*)(lds + (bufoff) + ldsw + _i * 8192), 16, 0, 0); } while (0)
; #define PG8_LDA(dst, b, h) do { _Pragma("unroll") for (int m = 0; m < 4; ++m) _Pragma("unroll") for (int k = 0; k < 2; ++k) dst[m][k] = *(const LAS bf16x8*)(lds + PG8_SA(b, h) + aoff + m * 2048 + k * 1024); } while (0)
; #define PG8_LDB(dst, b, h) do { _Pragma("unroll") for (int n = 0; n < 2; ++n) _Pragma("unroll") for (int k = 0; k < 2; ++k) dst[n][k] = *(const LAS bf16x8*)(lds + PG8_SB(b, h) + boff + n * 2048 + k * 1024); } while (0)
; #define PG8_MMA(ai, bj, At, Bt) do { __builtin_amdgcn_s_setprio(1); _Pragma("unroll") for (int m = 0; m < 4; ++m) _Pragma("unroll") for (int n = 0; n < 2; ++n) _Pragma("unroll") for (int k = 0; k < 2; ++k) \
;         acc[ai][bj][m][n] = __builtin_amdgcn_mfma_f32_16x16x32_bf16(Bt[n][k], At[m][k], acc[ai][bj][m][n], 0, 0, 0); __builtin_amdgcn_s_setprio(0); } while (0)
; #define PG8_WAIT_V(n) asm volatile("s_waitcnt vmcnt(" #n ")" ::: "memory")
; #define PG8_WAIT_L(n) asm volatile("s_waitcnt lgkmcnt(" #n ")" ::: "memory")
; #define PG8_BAR __builtin_amdgcn_s_barrier()
; #define PG8_SCHED __builtin_amdgcn_sched_barrier(0)
; template <class GEO, class Epi>
; __device__ __forceinline__ void gemm_phase(LAS unsigned char* lds, const Gemm g, const StaticOrder& S, const Epi& E) {
;     ...
;             PG8_WAIT_V(8); PG8_WAIT_L(0); PG8_BAR; PG8_MMA(1, 0, At, B0); PG8_MMA(1, 1, At, B1); PG8_BAR; PG8_SCHED;
;             PG8_LDB(B0, 1, 0); PG8_LDB(B1, 1, 1); PG8_SCHED; PG8_LDA(At, 1, 0); PG8_STAGE(PG8_SA(0, 1), a2 + hstepA, voffA);
;             PG8_WAIT_V(8); PG8_WAIT_L(0); PG8_BAR; PG8_MMA(0, 0, At, B0); PG8_MMA(0, 1, At, B1); PG8_BAR; PG8_SCHED;
	s_waitcnt lgkmcnt(0)
	v_mfma_f32_16x16x32_bf16 v[60:63], v[144:147], v[190:193], v[60:63]
	v_mfma_f32_16x16x32_bf16 v[56:59], v[166:169], v[190:193], v[56:59]
	v_mfma_f32_16x16x32_bf16 v[44:47], v[144:147], v[198:201], v[44:47]
	v_mfma_f32_16x16x32_bf16 v[40:43], v[166:169], v[198:201], v[40:43]
	v_mfma_f32_16x16x32_bf16 v[28:31], v[144:147], v[212:215], v[28:31]
	v_mfma_f32_16x16x32_bf16 v[24:27], v[166:169], v[212:215], v[24:27]
	v_mfma_f32_16x16x32_bf16 v[12:15], v[144:147], v[220:223], v[12:15]
	v_mfma_f32_16x16x32_bf16 v[8:11], v[166:169], v[220:223], v[8:11]
	v_mfma_f32_16x16x32_bf16 v[60:63], v[156:159], v[194:197], v[60:63]
	v_mfma_f32_16x16x32_bf16 v[56:59], v[170:173], v[194:197], v[56:59]
	v_mfma_f32_16x16x32_bf16 v[44:47], v[156:159], v[202:205], v[44:47]
	v_mfma_f32_16x16x32_bf16 v[40:43], v[170:173], v[202:205], v[40:43]
	v_mfma_f32_16x16x32_bf16 v[28:31], v[156:159], v[216:219], v[28:31]
	v_mfma_f32_16x16x32_bf16 v[24:27], v[170:173], v[216:219], v[24:27]
	v_mfma_f32_16x16x32_bf16 v[12:15], v[156:159], v[224:227], v[12:15]
	v_mfma_f32_16x16x32_bf16 v[8:11], v[170:173], v[224:227], v[8:11]
	v_mfma_f32_16x16x32_bf16 v[52:55], v[174:177], v[190:193], v[52:55]
	v_mfma_f32_16x16x32_bf16 v[48:51], v[182:185], v[190:193], v[48:51]
	v_mfma_f32_16x16x32_bf16 v[36:39], v[174:177], v[198:201], v[36:39]
	v_mfma_f32_16x16x32_bf16 v[32:35], v[182:185], v[198:201], v[32:35]
	v_mfma_f32_16x16x32_bf16 v[20:23], v[174:177], v[212:215], v[20:23]
	v_mfma_f32_16x16x32_bf16 v[16:19], v[182:185], v[212:215], v[16:19]
	v_mfma_f32_16x16x32_bf16 v[4:7], v[174:177], v[220:223], v[4:7]
	v_mfma_f32_16x16x32_bf16 v[0:3], v[182:185], v[220:223], v[0:3]
	v_mfma_f32_16x16x32_bf16 v[52:55], v[178:181], v[194:197], v[52:55]
	v_mfma_f32_16x16x32_bf16 v[48:51], v[186:189], v[194:197], v[48:51]
	v_mfma_f32_16x16x32_bf16 v[36:39], v[178:181], v[202:205], v[36:39]
	v_mfma_f32_16x16x32_bf16 v[32:35], v[186:189], v[202:205], v[32:35]
	v_mfma_f32_16x16x32_bf16 v[20:23], v[178:181], v[216:219], v[20:23]
	v_mfma_f32_16x16x32_bf16 v[16:19], v[186:189], v[216:219], v[16:19]
	v_mfma_f32_16x16x32_bf16 v[4:7], v[178:181], v[224:227], v[4:7]
	v_mfma_f32_16x16x32_bf16 v[0:3], v[186:189], v[224:227], v[0:3]
	s_barrier
	s_add_i32 s38, 0, 0x18000
	v_add_u32_e32 v155, s38, v149
	s_add_i32 s39, 0, 0x1c000
	ds_read_b128 v[144:147], v155
	ds_read_b128 v[156:159], v155 offset:1024
	ds_read_b128 v[166:169], v155 offset:2048
	ds_read_b128 v[170:173], v155 offset:3072
	v_add_u32_e32 v155, s39, v149
	ds_read_b128 v[174:177], v155
	ds_read_b128 v[178:181], v155 offset:1024
	ds_read_b128 v[182:185], v155 offset:2048
	ds_read_b128 v[186:189], v155 offset:3072
	s_add_u32 s8, s58, 0x40000
	s_addc_u32 s9, s59, 0
	s_mov_b32 m0, s5
	v_lshl_add_u64 v[232:233], s[8:9], 0, v[128:129]
	ds_read_b128 v[190:193], v154 offset:32768
	ds_read_b128 v[194:197], v154 offset:33792
	ds_read_b128 v[198:201], v154 offset:34816
	ds_read_b128 v[202:205], v154 offset:35840
	ds_read_b128 v[212:215], v154 offset:36864
	ds_read_b128 v[216:219], v154 offset:37888
	ds_read_b128 v[220:223], v154 offset:38912
	ds_read_b128 v[224:227], v154 offset:39936
	global_load_lds_dwordx4 v[232:233], off
	v_lshl_add_u64 v[232:233], s[8:9], 0, v[132:133]
	s_mov_b32 m0, s6
	s_nop 0
	global_load_lds_dwordx4 v[232:233], off
	s_waitcnt vmcnt(8)
	s_waitcnt lgkmcnt(0)
	s_barrier
	s_waitcnt lgkmcnt(0)
	v_mfma_f32_16x16x32_bf16 v[124:127], v[144:147], v[190:193], v[124:127]
	v_mfma_f32_16x16x32_bf16 v[120:123], v[166:169], v[190:193], v[120:123]
	v_mfma_f32_16x16x32_bf16 v[108:111], v[144:147], v[198:201], v[108:111]
	v_mfma_f32_16x16x32_bf16 v[104:107], v[166:169], v[198:201], v[104:107]
	v_mfma_f32_16x16x32_bf16 v[92:95], v[144:147], v[212:215], v[92:95]
	v_mfma_f32_16x16x32_bf16 v[88:91], v[166:169], v[212:215], v[88:91]
	v_mfma_f32_16x16x32_bf16 v[76:79], v[144:147], v[220:223], v[76:79]
	v_mfma_f32_16x16x32_bf16 v[72:75], v[166:169], v[220:223], v[72:75]
	v_mfma_f32_16x16x32_bf16 v[124:127], v[156:159], v[194:197], v[124:127]
	v_mfma_f32_16x16x32_bf16 v[120:123], v[170:173], v[194:197], v[120:123]
	v_mfma_f32_16x16x32_bf16 v[108:111], v[156:159], v[202:205], v[108:111]
	v_mfma_f32_16x16x32_bf16 v[104:107], v[170:173], v[202:205], v[104:107]
	v_mfma_f32_16x16x32_bf16 v[92:95], v[156:159], v[216:219], v[92:95]
	v_mfma_f32_16x16x32_bf16 v[88:91], v[170:173], v[216:219], v[88:91]
	v_mfma_f32_16x16x32_bf16 v[76:79], v[156:159], v[224:227], v[76:79]
	v_mfma_f32_16x16x32_bf16 v[72:75], v[170:173], v[224:227], v[72:75]
	v_mfma_f32_16x16x32_bf16 v[116:119], v[174:177], v[190:193], v[116:119]
	v_mfma_f32_16x16x32_bf16 v[112:115], v[182:185], v[190:193], v[112:115]
	v_mfma_f32_16x16x32_bf16 v[100:103], v[174:177], v[198:201], v[100:103]
	v_mfma_f32_16x16x32_bf16 v[96:99], v[182:185], v[198:201], v[96:99]
	v_mfma_f32_16x16x32_bf16 v[84:87], v[174:177], v[212:215], v[84:87]
	v_mfma_f32_16x16x32_bf16 v[80:83], v[182:185], v[212:215], v[80:83]
	v_mfma_f32_16x16x32_bf16 v[68:71], v[174:177], v[220:223], v[68:71]
	v_mfma_f32_16x16x32_bf16 v[64:67], v[182:185], v[220:223], v[64:67]
	v_mfma_f32_16x16x32_bf16 v[116:119], v[178:181], v[194:197], v[116:119]
	v_mfma_f32_16x16x32_bf16 v[112:115], v[186:189], v[194:197], v[112:115]
	v_mfma_f32_16x16x32_bf16 v[100:103], v[178:181], v[202:205], v[100:103]
	v_mfma_f32_16x16x32_bf16 v[96:99], v[186:189], v[202:205], v[96:99]
	v_mfma_f32_16x16x32_bf16 v[84:87], v[178:181], v[216:219], v[84:87]
	v_mfma_f32_16x16x32_bf16 v[80:83], v[186:189], v[216:219], v[80:83]
	v_mfma_f32_16x16x32_bf16 v[68:71], v[178:181], v[224:227], v[68:71]
	v_mfma_f32_16x16x32_bf16 v[64:67], v[186:189], v[224:227], v[64:67]
	s_barrier
; #define PG8_STAGE(bufoff, gbase, voff) do { _Pragma("unroll") for (int _i = 0; _i < 2; ++_i) \
;         __builtin_amdgcn_global_load_lds((const unsigned*)((const char*)(gbase) + (voff)[_i]), (LAS unsigned*)(lds + (bufoff) + ldsw + _i * 8192), 16, 0, 0); } while (0)
; #define PG8_LDA(dst, b, h) do { _Pragma("unroll") for (int m = 0; m < 4; ++m) _Pragma("unroll") for (int k = 0; k < 2; ++k) dst[m][k] = *(const LAS bf16x8*)(lds + PG8_SA(b, h) + aoff + m * 2048 + k * 1024); } while (0)
; #define PG8_MMA(ai, bj, At, Bt) do { __builtin_amdgcn_s_setprio(1); _Pragma("unroll") for (int m = 0; m < 4; ++m) _Pragma("unroll") for (int n = 0; n < 2; ++n) _Pragma("unroll") for (int k = 0; k < 2; ++k) \
;         acc[ai][bj][m][n] = __builtin_amdgcn_mfma_f32_16x16x32_bf16(Bt[n][k], At[m][k], acc[ai][bj][m][n], 0, 0, 0); __builtin_amdgcn_s_setprio(0); } while (0)
; #define PG8_WAIT_V(n) asm volatile("s_waitcnt vmcnt(" #n ")" ::: "memory")
; #define PG8_WAIT_L(n) asm volatile("s_waitcnt lgkmcnt(" #n ")" ::: "memory")
; #define PG8_BAR __builtin_amdgcn_s_barrier()
; #define PG8_SCHED __builtin_amdgcn_sched_barrier(0)
; template <class GEO, class Epi>
; __device__ __forceinline__ void gemm_phase(LAS unsigned char* lds, const Gemm g, const StaticOrder& S, const Epi& E) {
;     ...
;             PG8_LDA(At, 1, 1); PG8_STAGE(PG8_SB(1, 0), b3, voffB); PG8_STAGE(PG8_SB(1, 1), b3 + hstepB, voffB); PG8_STAGE(PG8_SA(1, 0), a3, voffA);
;             PG8_WAIT_V(8); PG8_WAIT_L(0); PG8_BAR; PG8_MMA(1, 0, At, B0); PG8_MMA(1, 1, At, B1); PG8_BAR; PG8_SCHED;
;         }
;         if (wr == 0) PG8_BAR;
	s_add_i32 s8, s38, s0
	v_lshl_add_u64 v[160:161], v[160:161], 0, s[30:31]
	s_mov_b32 m0, s8
	ds_read_b128 v[190:193], v154 offset:49152
	ds_read_b128 v[194:197], v154 offset:50176
	ds_read_b128 v[198:201], v154 offset:51200
	ds_read_b128 v[202:205], v154 offset:52224
	ds_read_b128 v[212:215], v154 offset:53248
	ds_read_b128 v[216:219], v154 offset:54272
	ds_read_b128 v[220:223], v154 offset:55296
	ds_read_b128 v[224:227], v154 offset:56320
	global_load_lds_dwordx4 v[160:161], off
	s_add_i32 m0, s8, 0x2000
	s_add_u32 s8, s56, 0x40080
	v_lshl_add_u64 v[160:161], v[206:207], 0, s[30:31]
	s_addc_u32 s9, s57, 0
	s_add_i32 s38, s39, s0
	global_load_lds_dwordx4 v[160:161], off
	v_lshl_add_u64 v[160:161], s[8:9], 0, v[130:131]
	s_mov_b32 m0, s38
	s_nop 0
	global_load_lds_dwordx4 v[160:161], off
	v_lshl_add_u64 v[160:161], s[8:9], 0, v[134:135]
	s_add_i32 m0, s38, 0x2000
	s_nop 0
	global_load_lds_dwordx4 v[160:161], off
	v_lshl_add_u64 v[160:161], v[228:229], 0, s[30:31]
	s_mov_b32 m0, s7
	s_nop 0
	global_load_lds_dwordx4 v[160:161], off
	v_lshl_add_u64 v[160:161], v[230:231], 0, s[30:31]
	s_mov_b32 m0, s12
	s_nop 0
	global_load_lds_dwordx4 v[160:161], off
	s_waitcnt vmcnt(8)
	s_waitcnt lgkmcnt(0)
	s_barrier
	s_waitcnt lgkmcnt(0)
	v_mfma_f32_16x16x32_bf16 v[60:63], v[144:147], v[190:193], v[60:63]
	v_mfma_f32_16x16x32_bf16 v[56:59], v[166:169], v[190:193], v[56:59]
	v_mfma_f32_16x16x32_bf16 v[44:47], v[144:147], v[198:201], v[44:47]
	v_mfma_f32_16x16x32_bf16 v[40:43], v[166:169], v[198:201], v[40:43]
	v_mfma_f32_16x16x32_bf16 v[28:31], v[144:147], v[212:215], v[28:31]
	v_mfma_f32_16x16x32_bf16 v[24:27], v[166:169], v[212:215], v[24:27]
	v_mfma_f32_16x16x32_bf16 v[12:15], v[144:147], v[220:223], v[12:15]
	v_mfma_f32_16x16x32_bf16 v[8:11], v[166:169], v[220:223], v[8:11]
	v_mfma_f32_16x16x32_bf16 v[60:63], v[156:159], v[194:197], v[60:63]
	v_mfma_f32_16x16x32_bf16 v[56:59], v[170:173], v[194:197], v[56:59]
	v_mfma_f32_16x16x32_bf16 v[44:47], v[156:159], v[202:205], v[44:47]
	v_mfma_f32_16x16x32_bf16 v[40:43], v[170:173], v[202:205], v[40:43]
	v_mfma_f32_16x16x32_bf16 v[28:31], v[156:159], v[216:219], v[28:31]
	v_mfma_f32_16x16x32_bf16 v[24:27], v[170:173], v[216:219], v[24:27]
	v_mfma_f32_16x16x32_bf16 v[12:15], v[156:159], v[224:227], v[12:15]
	v_mfma_f32_16x16x32_bf16 v[8:11], v[170:173], v[224:227], v[8:11]
	v_mfma_f32_16x16x32_bf16 v[52:55], v[174:177], v[190:193], v[52:55]
	v_mfma_f32_16x16x32_bf16 v[48:51], v[182:185], v[190:193], v[48:51]
	v_mfma_f32_16x16x32_bf16 v[36:39], v[174:177], v[198:201], v[36:39]
	v_mfma_f32_16x16x32_bf16 v[32:35], v[182:185], v[198:201], v[32:35]
	v_mfma_f32_16x16x32_bf16 v[20:23], v[174:177], v[212:215], v[20:23]
	v_mfma_f32_16x16x32_bf16 v[16:19], v[182:185], v[212:215], v[16:19]
	v_mfma_f32_16x16x32_bf16 v[4:7], v[174:177], v[220:223], v[4:7]
	v_mfma_f32_16x16x32_bf16 v[0:3], v[182:185], v[220:223], v[0:3]
	v_mfma_f32_16x16x32_bf16 v[52:55], v[178:181], v[194:197], v[52:55]
	v_mfma_f32_16x16x32_bf16 v[48:51], v[186:189], v[194:197], v[48:51]
	v_mfma_f32_16x16x32_bf16 v[36:39], v[178:181], v[202:205], v[36:39]
	v_mfma_f32_16x16x32_bf16 v[32:35], v[186:189], v[202:205], v[32:35]
	v_mfma_f32_16x16x32_bf16 v[20:23], v[178:181], v[216:219], v[20:23]
	v_mfma_f32_16x16x32_bf16 v[16:19], v[186:189], v[216:219], v[16:19]
	v_mfma_f32_16x16x32_bf16 v[4:7], v[178:181], v[224:227], v[4:7]
	v_mfma_f32_16x16x32_bf16 v[0:3], v[186:189], v[224:227], v[0:3]
	s_add_i32 s69, s69, 2
	s_add_u32 s54, s54, 0x100
	s_addc_u32 s55, s55, 0
	s_add_u32 s67, s67, 0x100
	s_addc_u32 s68, s68, 0
	s_cmp_gt_u32 s69, 13
	s_cbranch_scc0 .Lrot_2
	s_barrier
	s_and_b64 vcc, exec, s[34:35]
	s_cbranch_vccz .LBB0_694
	s_barrier

; template <class GEO, class Epi>
; __device__ __forceinline__ void gemm_phase(LAS unsigned char* lds, const Gemm g, const StaticOrder& S, const Epi& E) {
;     ...
;         const bool has_next = S.next(ui + 1, nxt);
;         const char* nA = has_next ? PG8_APTR(nxt) : cA; const char* nB = has_next ? PG8_BPTR(nxt) : cB;
; #pragma nounroll
;         for (int t = 0; t < nt; t += 2) {
;             const bool last = (t == nt - 2);
;             const char* a1 = cA + (size_t)(t + 1) * kstep;
;             const char* a2 = last ? nA : cA + (size_t)(t + 2) * kstep; const char* b2 = last ? nB : cB + (size_t)(t + 2) * kstep;
;     ...
; #pragma unroll
;         for (int a = 0; a < 2; ++a)
; #pragma unroll
;             for (int b = 0; b < 2; ++b)
; #pragma unroll
;                 for (int m = 0; m < 4; ++m)
; #pragma unroll
;                     for (int n = 0; n < 2; ++n) acc[a][b][m][n] = (f32x4){0.f, 0.f, 0.f, 0.f};
;         cur = nxt; cA = nA; cB = nB; ++ui;
.LBB0_778:
	s_ashr_i32 s47, s46, 31
	s_lshl_b64 s[8:9], s[46:47], 19
	s_add_u32 s48, s26, s8
	v_cmp_lt_i64_e64 s[42:43], s[42:43], v[144:145]
	s_addc_u32 s49, s27, s9
	s_and_b64 s[8:9], s[42:43], exec
	s_cselect_b32 s45, s49, s53
	s_cselect_b32 s47, s48, s52
	s_and_b32 s16, s64, 0x3fffffff
	s_lshl_b64 s[8:9], s[16:17], 19
	s_add_u32 s50, s70, s8
	s_addc_u32 s51, s71, s9
	s_and_b64 s[8:9], s[42:43], exec
	s_cselect_b32 s16, s51, s55
	s_cselect_b32 s66, s50, s54
	s_add_u32 s52, s52, 0x40080
	s_addc_u32 s53, s53, 0
	s_add_u32 s67, s54, 0x100
	v_mov_b32_e32 v0, 0
	s_addc_u32 s68, s55, 0
	s_mov_b32 s69, -2
	v_mov_b32_e32 v1, v0
	v_mov_b32_e32 v2, v0
	v_mov_b32_e32 v3, v0
	v_mov_b32_e32 v4, v0
	v_mov_b32_e32 v5, v0
	v_mov_b32_e32 v6, v0
	v_mov_b32_e32 v7, v0
	v_mov_b32_e32 v12, v0
	v_mov_b32_e32 v13, v0
	v_mov_b32_e32 v14, v0
	v_mov_b32_e32 v15, v0
	v_mov_b32_e32 v20, v0
	v_mov_b32_e32 v21, v0
	v_mov_b32_e32 v22, v0
	v_mov_b32_e32 v23, v0
	v_mov_b32_e32 v28, v0
	v_mov_b32_e32 v29, v0
	v_mov_b32_e32 v30, v0
	v_mov_b32_e32 v31, v0
	v_mov_b32_e32 v36, v0
	v_mov_b32_e32 v37, v0
	v_mov_b32_e32 v38, v0
	v_mov_b32_e32 v39, v0
	v_mov_b32_e32 v44, v0
	v_mov_b32_e32 v45, v0
	v_mov_b32_e32 v46, v0
	v_mov_b32_e32 v47, v0
	v_mov_b32_e32 v52, v0
	v_mov_b32_e32 v53, v0
	v_mov_b32_e32 v54, v0
	v_mov_b32_e32 v55, v0
	v_mov_b32_e32 v8, v0
	v_mov_b32_e32 v9, v0
	v_mov_b32_e32 v10, v0
	v_mov_b32_e32 v11, v0
	v_mov_b32_e32 v16, v0
	v_mov_b32_e32 v17, v0
	v_mov_b32_e32 v18, v0
	v_mov_b32_e32 v19, v0
	v_mov_b32_e32 v24, v0
	v_mov_b32_e32 v25, v0
	v_mov_b32_e32 v26, v0
	v_mov_b32_e32 v27, v0
	v_mov_b32_e32 v32, v0
	v_mov_b32_e32 v33, v0
	v_mov_b32_e32 v34, v0
	v_mov_b32_e32 v35, v0
	v_mov_b32_e32 v40, v0
	v_mov_b32_e32 v41, v0
	v_mov_b32_e32 v42, v0
	v_mov_b32_e32 v43, v0
	v_mov_b32_e32 v48, v0
	v_mov_b32_e32 v49, v0
	v_mov_b32_e32 v50, v0
	v_mov_b32_e32 v51, v0
	v_mov_b32_e32 v56, v0
	v_mov_b32_e32 v57, v0
	v_mov_b32_e32 v58, v0
	v_mov_b32_e32 v59, v0
	v_mov_b32_e32 v60, v0
	v_mov_b32_e32 v61, v0
	v_mov_b32_e32 v62, v0
	v_mov_b32_e32 v63, v0
	v_mov_b32_e32 v64, v0
	v_mov_b32_e32 v65, v0
	v_mov_b32_e32 v66, v0
	v_mov_b32_e32 v67, v0
	v_mov_b32_e32 v68, v0
	v_mov_b32_e32 v69, v0
	v_mov_b32_e32 v70, v0
	v_mov_b32_e32 v71, v0
	v_mov_b32_e32 v76, v0
	v_mov_b32_e32 v77, v0
	v_mov_b32_e32 v78, v0
	v_mov_b32_e32 v79, v0
	v_mov_b32_e32 v84, v0
	v_mov_b32_e32 v85, v0
	v_mov_b32_e32 v86, v0
	v_mov_b32_e32 v87, v0
	v_mov_b32_e32 v92, v0
	v_mov_b32_e32 v93, v0
	v_mov_b32_e32 v94, v0
	v_mov_b32_e32 v95, v0
	s_waitcnt vmcnt(0)
	v_mov_b32_e32 v100, v0
	v_mov_b32_e32 v101, v0
	v_mov_b32_e32 v102, v0
	v_mov_b32_e32 v103, v0
	v_mov_b32_e32 v108, v0
	v_mov_b32_e32 v109, v0
	v_mov_b32_e32 v110, v0
	v_mov_b32_e32 v111, v0
	v_mov_b32_e32 v116, v0
	v_mov_b32_e32 v117, v0
	v_mov_b32_e32 v118, v0
	v_mov_b32_e32 v119, v0
	v_mov_b32_e32 v72, v0
	v_mov_b32_e32 v73, v0
	v_mov_b32_e32 v74, v0
	v_mov_b32_e32 v75, v0
	v_mov_b32_e32 v80, v0
	v_mov_b32_e32 v81, v0
	v_mov_b32_e32 v82, v0
	v_mov_b32_e32 v83, v0
	v_mov_b32_e32 v88, v0
	v_mov_b32_e32 v89, v0
	v_mov_b32_e32 v90, v0
	v_mov_b32_e32 v91, v0
	v_mov_b32_e32 v96, v0
	v_mov_b32_e32 v97, v0
	v_mov_b32_e32 v98, v0
	v_mov_b32_e32 v99, v0
	v_mov_b32_e32 v104, v0
	v_mov_b32_e32 v105, v0
	v_mov_b32_e32 v106, v0
	v_mov_b32_e32 v107, v0
	v_mov_b32_e32 v112, v0
	v_mov_b32_e32 v113, v0
	v_mov_b32_e32 v114, v0
	v_mov_b32_e32 v115, v0
	v_mov_b32_e32 v120, v0
	v_mov_b32_e32 v121, v0
	v_mov_b32_e32 v122, v0
	v_mov_b32_e32 v123, v0
	v_mov_b32_e32 v124, v0
	v_mov_b32_e32 v125, v0
	v_mov_b32_e32 v126, v0
	v_mov_b32_e32 v127, v0
	s_branch .LBB0_779

; #define PG8_STAGE(bufoff, gbase, voff) do { _Pragma("unroll") for (int _i = 0; _i < 2; ++_i) \
;         __builtin_amdgcn_global_load_lds((const unsigned*)((const char*)(gbase) + (voff)[_i]), (LAS unsigned*)(lds + (bufoff) + ldsw + _i * 8192), 16, 0, 0); } while (0)
; #define PG8_LDA(dst, b, h) do { _Pragma("unroll") for (int m = 0; m < 4; ++m) _Pragma("unroll") for (int k = 0; k < 2; ++k) dst[m][k] = *(const LAS bf16x8*)(lds + PG8_SA(b, h) + aoff + m * 2048 + k * 1024); } while (0)
; #define PG8_LDB(dst, b, h) do { _Pragma("unroll") for (int n = 0; n < 2; ++n) _Pragma("unroll") for (int k = 0; k < 2; ++k) dst[n][k] = *(const LAS bf16x8*)(lds + PG8_SB(b, h) + boff + n * 2048 + k * 1024); } while (0)
; #define PG8_MMA(ai, bj, At, Bt) do { __builtin_amdgcn_s_setprio(1); _Pragma("unroll") for (int m = 0; m < 4; ++m) _Pragma("unroll") for (int n = 0; n < 2; ++n) _Pragma("unroll") for (int k = 0; k < 2; ++k) \
;         acc[ai][bj][m][n] = __builtin_amdgcn_mfma_f32_16x16x32_bf16(Bt[n][k], At[m][k], acc[ai][bj][m][n], 0, 0, 0); __builtin_amdgcn_s_setprio(0); } while (0)
; #define PG8_WAIT_V(n) asm volatile("s_waitcnt vmcnt(" #n ")" ::: "memory")
; #define PG8_WAIT_L(n) asm volatile("s_waitcnt lgkmcnt(" #n ")" ::: "memory")
; #define PG8_BAR __builtin_amdgcn_s_barrier()
; #define PG8_SCHED __builtin_amdgcn_sched_barrier(0)
; template <class GEO, class Epi>
; __device__ __forceinline__ void gemm_phase(LAS unsigned char* lds, const Gemm g, const StaticOrder& S, const Epi& E) {
;     ...
;             PG8_LDB(B0, 0, 0); PG8_LDB(B1, 0, 1); PG8_SCHED; PG8_LDA(At, 0, 0); PG8_STAGE(PG8_SA(1, 1), a1 + hstepA, voffA);
;             PG8_WAIT_V(8); PG8_WAIT_L(0); PG8_BAR; PG8_MMA(0, 0, At, B0); PG8_MMA(0, 1, At, B1); PG8_BAR; PG8_SCHED;
;             PG8_LDA(At, 0, 1); PG8_STAGE(PG8_SB(0, 0), b2, voffB); PG8_STAGE(PG8_SB(0, 1), b2 + hstepB, voffB); PG8_STAGE(PG8_SA(0, 0), a2, voffA);
;             PG8_WAIT_V(8); PG8_WAIT_L(0); PG8_BAR; PG8_MMA(1, 0, At, B0); PG8_MMA(1, 1, At, B1); PG8_BAR; PG8_SCHED;
.LBB0_779:
	ds_read_b128 v[148:151], v179
	ds_read_b128 v[152:155], v179 offset:1024
	ds_read_b128 v[156:159], v179 offset:2048
	ds_read_b128 v[166:169], v179 offset:3072
	ds_read_b128 v[186:189], v181
	ds_read_b128 v[190:193], v181 offset:1024
	ds_read_b128 v[194:197], v181 offset:2048
	ds_read_b128 v[198:201], v181 offset:3072
	s_add_u32 s8, s52, 0xfffc0080
	s_addc_u32 s9, s53, -1
	s_cmp_eq_u32 s69, 12
	s_cselect_b32 s57, s45, s9
	s_cselect_b32 s56, s47, s8
	s_cselect_b32 s55, s16, s68
	s_cselect_b32 s54, s66, s67
	v_lshl_add_u64 v[160:161], s[52:53], 0, v[140:141]
	s_add_i32 m0, s1, 0xc000
	ds_read_b128 v[202:205], v183
	ds_read_b128 v[212:215], v183 offset:1024
	ds_read_b128 v[216:219], v183 offset:2048
	ds_read_b128 v[220:223], v183 offset:3072
	ds_read_b128 v[224:227], v183 offset:4096
	ds_read_b128 v[228:231], v183 offset:5120
	ds_read_b128 v[232:235], v183 offset:6144
	ds_read_b128 v[236:239], v183 offset:7168
	global_load_lds_dwordx4 v[160:161], off
	v_lshl_add_u64 v[160:161], s[52:53], 0, v[142:143]
	s_add_i32 m0, s1, 0xe000
	s_nop 0
	global_load_lds_dwordx4 v[160:161], off
	s_waitcnt vmcnt(8)
	s_waitcnt lgkmcnt(0)
	s_barrier
	s_waitcnt lgkmcnt(0)
	v_mfma_f32_16x16x32_bf16 v[124:127], v[148:151], v[202:205], v[124:127]
	v_mfma_f32_16x16x32_bf16 v[120:123], v[156:159], v[202:205], v[120:123]
	v_mfma_f32_16x16x32_bf16 v[112:115], v[148:151], v[216:219], v[112:115]
	v_mfma_f32_16x16x32_bf16 v[104:107], v[156:159], v[216:219], v[104:107]
	v_mfma_f32_16x16x32_bf16 v[96:99], v[148:151], v[224:227], v[96:99]
	v_mfma_f32_16x16x32_bf16 v[88:91], v[156:159], v[224:227], v[88:91]
	v_mfma_f32_16x16x32_bf16 v[80:83], v[148:151], v[232:235], v[80:83]
	v_mfma_f32_16x16x32_bf16 v[72:75], v[156:159], v[232:235], v[72:75]
	v_mfma_f32_16x16x32_bf16 v[124:127], v[152:155], v[212:215], v[124:127]
	v_mfma_f32_16x16x32_bf16 v[120:123], v[166:169], v[212:215], v[120:123]
	v_mfma_f32_16x16x32_bf16 v[112:115], v[152:155], v[220:223], v[112:115]
	v_mfma_f32_16x16x32_bf16 v[104:107], v[166:169], v[220:223], v[104:107]
	v_mfma_f32_16x16x32_bf16 v[96:99], v[152:155], v[228:231], v[96:99]
	v_mfma_f32_16x16x32_bf16 v[88:91], v[166:169], v[228:231], v[88:91]
	v_mfma_f32_16x16x32_bf16 v[80:83], v[152:155], v[236:239], v[80:83]
	v_mfma_f32_16x16x32_bf16 v[72:75], v[166:169], v[236:239], v[72:75]
	v_mfma_f32_16x16x32_bf16 v[116:119], v[186:189], v[202:205], v[116:119]
	v_mfma_f32_16x16x32_bf16 v[108:111], v[194:197], v[202:205], v[108:111]
	v_mfma_f32_16x16x32_bf16 v[100:103], v[186:189], v[216:219], v[100:103]
	v_mfma_f32_16x16x32_bf16 v[92:95], v[194:197], v[216:219], v[92:95]
	v_mfma_f32_16x16x32_bf16 v[84:87], v[186:189], v[224:227], v[84:87]
	v_mfma_f32_16x16x32_bf16 v[76:79], v[194:197], v[224:227], v[76:79]
	v_mfma_f32_16x16x32_bf16 v[68:71], v[186:189], v[232:235], v[68:71]
	v_mfma_f32_16x16x32_bf16 v[64:67], v[194:197], v[232:235], v[64:67]
	v_mfma_f32_16x16x32_bf16 v[116:119], v[190:193], v[212:215], v[116:119]
	v_mfma_f32_16x16x32_bf16 v[108:111], v[198:201], v[212:215], v[108:111]
	v_mfma_f32_16x16x32_bf16 v[100:103], v[190:193], v[220:223], v[100:103]
	v_mfma_f32_16x16x32_bf16 v[92:95], v[198:201], v[220:223], v[92:95]
	v_mfma_f32_16x16x32_bf16 v[84:87], v[190:193], v[228:231], v[84:87]
	v_mfma_f32_16x16x32_bf16 v[76:79], v[198:201], v[228:231], v[76:79]
	v_mfma_f32_16x16x32_bf16 v[68:71], v[190:193], v[236:239], v[68:71]
	v_mfma_f32_16x16x32_bf16 v[64:67], v[198:201], v[236:239], v[64:67]
	s_barrier
	s_add_i32 s8, s60, s0
	v_lshl_add_u64 v[160:161], s[54:55], 0, v[130:131]
	s_mov_b32 m0, s8
	ds_read_b128 v[202:205], v183 offset:16384
	ds_read_b128 v[212:215], v183 offset:17408
	ds_read_b128 v[216:219], v183 offset:18432
	ds_read_b128 v[220:223], v183 offset:19456
	ds_read_b128 v[224:227], v183 offset:20480
	ds_read_b128 v[228:231], v183 offset:21504
	ds_read_b128 v[232:235], v183 offset:22528
	ds_read_b128 v[236:239], v183 offset:23552
	global_load_lds_dwordx4 v[160:161], off
	s_add_i32 m0, s8, 0x2000
	s_add_u32 s8, s54, 0x40000
	v_lshl_add_u64 v[170:171], s[54:55], 0, v[134:135]
	s_addc_u32 s9, s55, 0
	s_add_i32 s38, s61, s0
	global_load_lds_dwordx4 v[170:171], off
	v_lshl_add_u64 v[206:207], s[8:9], 0, v[130:131]
	s_mov_b32 m0, s38
	v_lshl_add_u64 v[240:241], s[56:57], 0, v[132:133]
	global_load_lds_dwordx4 v[206:207], off
	v_lshl_add_u64 v[206:207], s[8:9], 0, v[134:135]
	s_add_i32 m0, s38, 0x2000
	s_nop 0
	global_load_lds_dwordx4 v[206:207], off
	v_lshl_add_u64 v[206:207], s[56:57], 0, v[128:129]
	s_mov_b32 m0, s1
	s_nop 0
	global_load_lds_dwordx4 v[206:207], off
	s_mov_b32 m0, s4
	s_nop 0
	global_load_lds_dwordx4 v[240:241], off
	s_waitcnt vmcnt(8)
	s_waitcnt lgkmcnt(0)
	s_barrier
; #define PG8_STAGE(bufoff, gbase, voff) do { _Pragma("unroll") for (int _i = 0; _i < 2; ++_i) \
;         __builtin_amdgcn_global_load_lds((const unsigned*)((const char*)(gbase) + (voff)[_i]), (LAS unsigned*)(lds + (bufoff) + ldsw + _i * 8192), 16, 0, 0); } while (0)
; #define PG8_LDA(dst, b, h) do { _Pragma("unroll") for (int m = 0; m < 4; ++m) _Pragma("unroll") for (int k = 0; k < 2; ++k) dst[m][k] = *(const LAS bf16x8*)(lds + PG8_SA(b, h) + aoff + m * 2048 + k * 1024); } while (0)
; #define PG8_LDB(dst, b, h) do { _Pragma("unroll") for (int n = 0; n < 2; ++n) _Pragma("unroll") for (int k = 0; k < 2; ++k) dst[n][k] = *(const LAS bf16x8*)(lds + PG8_SB(b, h) + boff + n * 2048 + k * 1024); } while (0)
; #define PG8_MMA(ai, bj, At, Bt) do { __builtin_amdgcn_s_setprio(1); _Pragma("unroll") for (int m = 0; m < 4; ++m) _Pragma("unroll") for (int n = 0; n < 2; ++n) _Pragma("unroll") for (int k = 0; k < 2; ++k) \
;         acc[ai][bj][m][n] = __builtin_amdgcn_mfma_f32_16x16x32_bf16(Bt[n][k], At[m][k], acc[ai][bj][m][n], 0, 0, 0); __builtin_amdgcn_s_setprio(0); } while (0)
; #define PG8_WAIT_V(n) asm volatile("s_waitcnt vmcnt(" #n ")" ::: "memory")
; #define PG8_WAIT_L(n) asm volatile("s_waitcnt lgkmcnt(" #n ")" ::: "memory")
; #define PG8_BAR __builtin_amdgcn_s_barrier()
; #define PG8_SCHED __builtin_amdgcn_sched_barrier(0)
; template <class GEO, class Epi>
; __device__ __forceinline__ void gemm_phase(LAS unsigned char* lds, const Gemm g, const StaticOrder& S, const Epi& E) {
;     ...
;             PG8_WAIT_V(8); PG8_WAIT_L(0); PG8_BAR; PG8_MMA(1, 0, At, B0); PG8_MMA(1, 1, At, B1); PG8_BAR; PG8_SCHED;
;             PG8_LDB(B0, 1, 0); PG8_LDB(B1, 1, 1); PG8_SCHED; PG8_LDA(At, 1, 0); PG8_STAGE(PG8_SA(0, 1), a2 + hstepA, voffA);
;             PG8_WAIT_V(8); PG8_WAIT_L(0); PG8_BAR; PG8_MMA(0, 0, At, B0); PG8_MMA(0, 1, At, B1); PG8_BAR; PG8_SCHED;
	s_waitcnt lgkmcnt(0)
	v_mfma_f32_16x16x32_bf16 v[60:63], v[148:151], v[202:205], v[60:63]
	v_mfma_f32_16x16x32_bf16 v[56:59], v[156:159], v[202:205], v[56:59]
	v_mfma_f32_16x16x32_bf16 v[48:51], v[148:151], v[216:219], v[48:51]
	v_mfma_f32_16x16x32_bf16 v[40:43], v[156:159], v[216:219], v[40:43]
	v_mfma_f32_16x16x32_bf16 v[32:35], v[148:151], v[224:227], v[32:35]
	v_mfma_f32_16x16x32_bf16 v[24:27], v[156:159], v[224:227], v[24:27]
	v_mfma_f32_16x16x32_bf16 v[16:19], v[148:151], v[232:235], v[16:19]
	v_mfma_f32_16x16x32_bf16 v[8:11], v[156:159], v[232:235], v[8:11]
	v_mfma_f32_16x16x32_bf16 v[60:63], v[152:155], v[212:215], v[60:63]
	v_mfma_f32_16x16x32_bf16 v[56:59], v[166:169], v[212:215], v[56:59]
	v_mfma_f32_16x16x32_bf16 v[48:51], v[152:155], v[220:223], v[48:51]
	v_mfma_f32_16x16x32_bf16 v[40:43], v[166:169], v[220:223], v[40:43]
	v_mfma_f32_16x16x32_bf16 v[32:35], v[152:155], v[228:231], v[32:35]
	v_mfma_f32_16x16x32_bf16 v[24:27], v[166:169], v[228:231], v[24:27]
	v_mfma_f32_16x16x32_bf16 v[16:19], v[152:155], v[236:239], v[16:19]
	v_mfma_f32_16x16x32_bf16 v[8:11], v[166:169], v[236:239], v[8:11]
	v_mfma_f32_16x16x32_bf16 v[52:55], v[186:189], v[202:205], v[52:55]
	v_mfma_f32_16x16x32_bf16 v[44:47], v[194:197], v[202:205], v[44:47]
	v_mfma_f32_16x16x32_bf16 v[36:39], v[186:189], v[216:219], v[36:39]
	v_mfma_f32_16x16x32_bf16 v[28:31], v[194:197], v[216:219], v[28:31]
	v_mfma_f32_16x16x32_bf16 v[20:23], v[186:189], v[224:227], v[20:23]
	v_mfma_f32_16x16x32_bf16 v[12:15], v[194:197], v[224:227], v[12:15]
	v_mfma_f32_16x16x32_bf16 v[4:7], v[186:189], v[232:235], v[4:7]
	v_mfma_f32_16x16x32_bf16 v[0:3], v[194:197], v[232:235], v[0:3]
	v_mfma_f32_16x16x32_bf16 v[52:55], v[190:193], v[212:215], v[52:55]
	v_mfma_f32_16x16x32_bf16 v[44:47], v[198:201], v[212:215], v[44:47]
	v_mfma_f32_16x16x32_bf16 v[36:39], v[190:193], v[220:223], v[36:39]
	v_mfma_f32_16x16x32_bf16 v[28:31], v[198:201], v[220:223], v[28:31]
	v_mfma_f32_16x16x32_bf16 v[20:23], v[190:193], v[228:231], v[20:23]
	v_mfma_f32_16x16x32_bf16 v[12:15], v[198:201], v[228:231], v[12:15]
	v_mfma_f32_16x16x32_bf16 v[4:7], v[190:193], v[236:239], v[4:7]
	v_mfma_f32_16x16x32_bf16 v[0:3], v[198:201], v[236:239], v[0:3]
	s_barrier
	s_add_i32 s38, 0, 0x18000
	s_add_i32 s39, 0, 0x1c000
	v_add_u32_e32 v166, s38, v175
	v_add_u32_e32 v172, s39, v175
	ds_read_b128 v[148:151], v166
	ds_read_b128 v[152:155], v166 offset:1024
	ds_read_b128 v[156:159], v166 offset:2048
	ds_read_b128 v[166:169], v166 offset:3072
	ds_read_b128 v[186:189], v172
	ds_read_b128 v[190:193], v172 offset:1024
	ds_read_b128 v[194:197], v172 offset:2048
	ds_read_b128 v[198:201], v172 offset:3072
	s_add_u32 s8, s56, 0x40000
	s_addc_u32 s9, s57, 0
	s_mov_b32 m0, s5
	v_lshl_add_u64 v[242:243], s[8:9], 0, v[128:129]
	ds_read_b128 v[202:205], v183 offset:32768
	ds_read_b128 v[212:215], v183 offset:33792
	ds_read_b128 v[216:219], v183 offset:34816
	ds_read_b128 v[220:223], v183 offset:35840
	ds_read_b128 v[224:227], v183 offset:36864
	ds_read_b128 v[228:231], v183 offset:37888
	ds_read_b128 v[232:235], v183 offset:38912
	ds_read_b128 v[236:239], v183 offset:39936
	global_load_lds_dwordx4 v[242:243], off
	v_lshl_add_u64 v[242:243], s[8:9], 0, v[132:133]
	s_mov_b32 m0, s6
	s_nop 0
	global_load_lds_dwordx4 v[242:243], off
	s_waitcnt vmcnt(8)
	s_waitcnt lgkmcnt(0)
	s_barrier
	s_waitcnt lgkmcnt(0)
	v_mfma_f32_16x16x32_bf16 v[124:127], v[148:151], v[202:205], v[124:127]
	v_mfma_f32_16x16x32_bf16 v[120:123], v[156:159], v[202:205], v[120:123]
	v_mfma_f32_16x16x32_bf16 v[112:115], v[148:151], v[216:219], v[112:115]
	v_mfma_f32_16x16x32_bf16 v[104:107], v[156:159], v[216:219], v[104:107]
	v_mfma_f32_16x16x32_bf16 v[96:99], v[148:151], v[224:227], v[96:99]
	v_mfma_f32_16x16x32_bf16 v[88:91], v[156:159], v[224:227], v[88:91]
	v_mfma_f32_16x16x32_bf16 v[80:83], v[148:151], v[232:235], v[80:83]
	v_mfma_f32_16x16x32_bf16 v[72:75], v[156:159], v[232:235], v[72:75]
	v_mfma_f32_16x16x32_bf16 v[124:127], v[152:155], v[212:215], v[124:127]
	v_mfma_f32_16x16x32_bf16 v[120:123], v[166:169], v[212:215], v[120:123]
	v_mfma_f32_16x16x32_bf16 v[112:115], v[152:155], v[220:223], v[112:115]
	v_mfma_f32_16x16x32_bf16 v[104:107], v[166:169], v[220:223], v[104:107]
	v_mfma_f32_16x16x32_bf16 v[96:99], v[152:155], v[228:231], v[96:99]
	v_mfma_f32_16x16x32_bf16 v[88:91], v[166:169], v[228:231], v[88:91]
	v_mfma_f32_16x16x32_bf16 v[80:83], v[152:155], v[236:239], v[80:83]
	v_mfma_f32_16x16x32_bf16 v[72:75], v[166:169], v[236:239], v[72:75]
	v_mfma_f32_16x16x32_bf16 v[116:119], v[186:189], v[202:205], v[116:119]
	v_mfma_f32_16x16x32_bf16 v[108:111], v[194:197], v[202:205], v[108:111]
	v_mfma_f32_16x16x32_bf16 v[100:103], v[186:189], v[216:219], v[100:103]
	v_mfma_f32_16x16x32_bf16 v[92:95], v[194:197], v[216:219], v[92:95]
	v_mfma_f32_16x16x32_bf16 v[84:87], v[186:189], v[224:227], v[84:87]
	v_mfma_f32_16x16x32_bf16 v[76:79], v[194:197], v[224:227], v[76:79]
	v_mfma_f32_16x16x32_bf16 v[68:71], v[186:189], v[232:235], v[68:71]
	v_mfma_f32_16x16x32_bf16 v[64:67], v[194:197], v[232:235], v[64:67]
	v_mfma_f32_16x16x32_bf16 v[116:119], v[190:193], v[212:215], v[116:119]
	v_mfma_f32_16x16x32_bf16 v[108:111], v[198:201], v[212:215], v[108:111]
	v_mfma_f32_16x16x32_bf16 v[100:103], v[190:193], v[220:223], v[100:103]
	v_mfma_f32_16x16x32_bf16 v[92:95], v[198:201], v[220:223], v[92:95]
	v_mfma_f32_16x16x32_bf16 v[84:87], v[190:193], v[228:231], v[84:87]
	v_mfma_f32_16x16x32_bf16 v[76:79], v[198:201], v[228:231], v[76:79]
	v_mfma_f32_16x16x32_bf16 v[68:71], v[190:193], v[236:239], v[68:71]
	v_mfma_f32_16x16x32_bf16 v[64:67], v[198:201], v[236:239], v[64:67]
	s_barrier
; #define PG8_STAGE(bufoff, gbase, voff) do { _Pragma("unroll") for (int _i = 0; _i < 2; ++_i) \
;         __builtin_amdgcn_global_load_lds((const unsigned*)((const char*)(gbase) + (voff)[_i]), (LAS unsigned*)(lds + (bufoff) + ldsw + _i * 8192), 16, 0, 0); } while (0)
; #define PG8_LDA(dst, b, h) do { _Pragma("unroll") for (int m = 0; m < 4; ++m) _Pragma("unroll") for (int k = 0; k < 2; ++k) dst[m][k] = *(const LAS bf16x8*)(lds + PG8_SA(b, h) + aoff + m * 2048 + k * 1024); } while (0)
; #define PG8_MMA(ai, bj, At, Bt) do { __builtin_amdgcn_s_setprio(1); _Pragma("unroll") for (int m = 0; m < 4; ++m) _Pragma("unroll") for (int n = 0; n < 2; ++n) _Pragma("unroll") for (int k = 0; k < 2; ++k) \
;         acc[ai][bj][m][n] = __builtin_amdgcn_mfma_f32_16x16x32_bf16(Bt[n][k], At[m][k], acc[ai][bj][m][n], 0, 0, 0); __builtin_amdgcn_s_setprio(0); } while (0)
; #define PG8_WAIT_V(n) asm volatile("s_waitcnt vmcnt(" #n ")" ::: "memory")
; #define PG8_WAIT_L(n) asm volatile("s_waitcnt lgkmcnt(" #n ")" ::: "memory")
; #define PG8_BAR __builtin_amdgcn_s_barrier()
; #define PG8_SCHED __builtin_amdgcn_sched_barrier(0)
;     DI void operator()(Acc& acc, const Unit& u, int wr, int wc, int fr, int fq, LAS unsigned char* lds) const {
;     ...
;             for (int m = 0; m < 4; ++m) { const int row = u.pm * BM + ai * HALF + wr * 64 + m * 16 + fr;
;                 float rs = 1.0f; if (sumsq) { const f32x4 q4 = *(const f32x4*)(sumsq + (size_t)row * 4); rs = rsqrtf(((q4.x + q4.y) + (q4.z + q4.w)) * (1.0f / DM) + EPS); } float ss = 0.f;
; template <class GEO, class Epi>
; __device__ __forceinline__ void gemm_phase(LAS unsigned char* lds, const Gemm g, const StaticOrder& S, const Epi& E) {
;     ...
;             PG8_LDA(At, 1, 1); PG8_STAGE(PG8_SB(1, 0), b3, voffB); PG8_STAGE(PG8_SB(1, 1), b3 + hstepB, voffB); PG8_STAGE(PG8_SA(1, 0), a3, voffA);
;             PG8_WAIT_V(8); PG8_WAIT_L(0); PG8_BAR; PG8_MMA(1, 0, At, B0); PG8_MMA(1, 1, At, B1); PG8_BAR; PG8_SCHED;
;         }
;         if (wr == 0) PG8_BAR;
	s_add_i32 s8, s38, s0
	v_lshl_add_u64 v[160:161], v[160:161], 0, s[28:29]
	s_mov_b32 m0, s8
	ds_read_b128 v[202:205], v183 offset:49152
	ds_read_b128 v[212:215], v183 offset:50176
	ds_read_b128 v[216:219], v183 offset:51200
	ds_read_b128 v[220:223], v183 offset:52224
	ds_read_b128 v[224:227], v183 offset:53248
	ds_read_b128 v[228:231], v183 offset:54272
	ds_read_b128 v[232:235], v183 offset:55296
	ds_read_b128 v[236:239], v183 offset:56320
	global_load_lds_dwordx4 v[160:161], off
	s_add_i32 m0, s8, 0x2000
	s_add_u32 s8, s54, 0x40080
	v_lshl_add_u64 v[160:161], v[170:171], 0, s[28:29]
	s_addc_u32 s9, s55, 0
	s_add_i32 s38, s39, s0
	global_load_lds_dwordx4 v[160:161], off
	v_lshl_add_u64 v[160:161], s[8:9], 0, v[130:131]
	s_mov_b32 m0, s38
	s_nop 0
	global_load_lds_dwordx4 v[160:161], off
	v_lshl_add_u64 v[160:161], s[8:9], 0, v[134:135]
	s_add_i32 m0, s38, 0x2000
	s_nop 0
	global_load_lds_dwordx4 v[160:161], off
	v_lshl_add_u64 v[160:161], v[206:207], 0, s[28:29]
	s_mov_b32 m0, s7
	s_nop 0
	global_load_lds_dwordx4 v[160:161], off
	v_lshl_add_u64 v[160:161], v[240:241], 0, s[28:29]
	s_mov_b32 m0, s12
	s_nop 0
	global_load_lds_dwordx4 v[160:161], off
	s_waitcnt vmcnt(8)
	s_waitcnt lgkmcnt(0)
	s_barrier
	s_waitcnt lgkmcnt(0)
	v_mfma_f32_16x16x32_bf16 v[60:63], v[148:151], v[202:205], v[60:63]
	v_mfma_f32_16x16x32_bf16 v[56:59], v[156:159], v[202:205], v[56:59]
	v_mfma_f32_16x16x32_bf16 v[48:51], v[148:151], v[216:219], v[48:51]
	v_mfma_f32_16x16x32_bf16 v[40:43], v[156:159], v[216:219], v[40:43]
	v_mfma_f32_16x16x32_bf16 v[32:35], v[148:151], v[224:227], v[32:35]
	v_mfma_f32_16x16x32_bf16 v[24:27], v[156:159], v[224:227], v[24:27]
	v_mfma_f32_16x16x32_bf16 v[16:19], v[148:151], v[232:235], v[16:19]
	v_mfma_f32_16x16x32_bf16 v[8:11], v[156:159], v[232:235], v[8:11]
	v_mfma_f32_16x16x32_bf16 v[60:63], v[152:155], v[212:215], v[60:63]
	v_mfma_f32_16x16x32_bf16 v[56:59], v[166:169], v[212:215], v[56:59]
	v_mfma_f32_16x16x32_bf16 v[48:51], v[152:155], v[220:223], v[48:51]
	v_mfma_f32_16x16x32_bf16 v[40:43], v[166:169], v[220:223], v[40:43]
	v_mfma_f32_16x16x32_bf16 v[32:35], v[152:155], v[228:231], v[32:35]
	v_mfma_f32_16x16x32_bf16 v[24:27], v[166:169], v[228:231], v[24:27]
	v_mfma_f32_16x16x32_bf16 v[16:19], v[152:155], v[236:239], v[16:19]
	v_mfma_f32_16x16x32_bf16 v[8:11], v[166:169], v[236:239], v[8:11]
	v_mfma_f32_16x16x32_bf16 v[52:55], v[186:189], v[202:205], v[52:55]
	v_mfma_f32_16x16x32_bf16 v[44:47], v[194:197], v[202:205], v[44:47]
	v_mfma_f32_16x16x32_bf16 v[36:39], v[186:189], v[216:219], v[36:39]
	v_mfma_f32_16x16x32_bf16 v[28:31], v[194:197], v[216:219], v[28:31]
	v_mfma_f32_16x16x32_bf16 v[20:23], v[186:189], v[224:227], v[20:23]
	v_mfma_f32_16x16x32_bf16 v[12:15], v[194:197], v[224:227], v[12:15]
	v_mfma_f32_16x16x32_bf16 v[4:7], v[186:189], v[232:235], v[4:7]
	v_mfma_f32_16x16x32_bf16 v[0:3], v[194:197], v[232:235], v[0:3]
	v_mfma_f32_16x16x32_bf16 v[52:55], v[190:193], v[212:215], v[52:55]
	v_mfma_f32_16x16x32_bf16 v[44:47], v[198:201], v[212:215], v[44:47]
	v_mfma_f32_16x16x32_bf16 v[36:39], v[190:193], v[220:223], v[36:39]
	v_mfma_f32_16x16x32_bf16 v[28:31], v[198:201], v[220:223], v[28:31]
	v_mfma_f32_16x16x32_bf16 v[20:23], v[190:193], v[228:231], v[20:23]
	v_mfma_f32_16x16x32_bf16 v[12:15], v[198:201], v[228:231], v[12:15]
	v_mfma_f32_16x16x32_bf16 v[4:7], v[190:193], v[236:239], v[4:7]
	v_mfma_f32_16x16x32_bf16 v[0:3], v[198:201], v[236:239], v[0:3]
	s_add_i32 s69, s69, 2
	s_add_u32 s52, s52, 0x100
	s_addc_u32 s53, s53, 0
	s_add_u32 s67, s67, 0x100
	s_addc_u32 s68, s68, 0
	s_cmp_gt_u32 s69, 13
	s_cbranch_scc0 .Lrot_3
	s_barrier
	v_lshl_add_u32 v244, s44, 8, v173
	v_ashrrev_i32_e32 v245, 31, v244
	v_lshl_add_u64 v[244:245], v[244:245], 4, s[76:77]
	global_load_dwordx4 v[212:215], v[244:245], off
	global_load_dwordx4 v[216:219], v[244:245], off offset:256
	global_load_dwordx4 v[220:223], v[244:245], off offset:512
	global_load_dwordx4 v[224:227], v[244:245], off offset:768
	global_load_dwordx4 v[228:231], v[244:245], off offset:2048
	global_load_dwordx4 v[232:235], v[244:245], off offset:2304
	global_load_dwordx4 v[236:239], v[244:245], off offset:2560
	global_load_dwordx4 v[240:243], v[244:245], off offset:2816
	s_and_b64 vcc, exec, s[30:31]
	s_cbranch_vccz .LBB0_782
	s_barrier

; template <class GEO, class Epi>
; __device__ __forceinline__ void gemm_phase(LAS unsigned char* lds, const Gemm g, const StaticOrder& S, const Epi& E) {
;     ...
;         const bool has_next = S.next(ui + 1, nxt);
;         const char* nA = has_next ? PG8_APTR(nxt) : cA; const char* nB = has_next ? PG8_BPTR(nxt) : cB;
; #pragma nounroll
;         for (int t = 0; t < nt; t += 2) {
;             const bool last = (t == nt - 2);
;             const char* a1 = cA + (size_t)(t + 1) * kstep;
;             const char* a2 = last ? nA : cA + (size_t)(t + 2) * kstep; const char* b2 = last ? nB : cB + (size_t)(t + 2) * kstep;
;     ...
; #pragma unroll
;         for (int a = 0; a < 2; ++a)
; #pragma unroll
;             for (int b = 0; b < 2; ++b)
; #pragma unroll
;                 for (int m = 0; m < 4; ++m)
; #pragma unroll
;                     for (int n = 0; n < 2; ++n) acc[a][b][m][n] = (f32x4){0.f, 0.f, 0.f, 0.f};
;         cur = nxt; cA = nA; cB = nB; ++ui;
.LBB0_988:
	s_ashr_i32 s47, s46, 31
	s_lshl_b64 s[38:39], s[46:47], 19
	s_add_u32 s48, s16, s38
	s_addc_u32 s49, s17, s39
	s_and_b64 s[38:39], s[44:45], exec
	s_cselect_b32 s15, s49, s53
	s_cselect_b32 s23, s48, s52
	s_ashr_i32 s38, s46, 5
	s_and_b32 s28, s64, 0x3fffffff
	s_ashr_i32 s39, s38, 31
	s_lshl_b64 s[38:39], s[38:39], 11
	s_lshl_b64 s[50:51], s[28:29], 21
	s_add_u32 s28, s24, s50
	s_addc_u32 s47, s25, s51
	s_add_u32 s50, s28, s38
	s_addc_u32 s51, s47, s39
	s_and_b64 s[38:39], s[44:45], exec
	s_cselect_b32 s28, s51, s55
	s_cselect_b32 s47, s50, s54
	s_add_u32 s52, s52, 0x40080
	s_addc_u32 s53, s53, 0
	s_add_u32 s65, s54, 0x100
	v_mov_b32_e32 v0, 0
	s_addc_u32 s66, s55, 0
	s_mov_b32 s67, -2
	s_waitcnt lgkmcnt(0)
	v_mov_b32_e32 v1, v0
	v_mov_b32_e32 v2, v0
	v_mov_b32_e32 v3, v0
	v_mov_b32_e32 v4, v0
	v_mov_b32_e32 v5, v0
	v_mov_b32_e32 v6, v0
	v_mov_b32_e32 v7, v0
	v_mov_b32_e32 v16, v0
	v_mov_b32_e32 v17, v0
	v_mov_b32_e32 v18, v0
	v_mov_b32_e32 v19, v0
	v_mov_b32_e32 v20, v0
	v_mov_b32_e32 v21, v0
	v_mov_b32_e32 v22, v0
	v_mov_b32_e32 v23, v0
	v_mov_b32_e32 v32, v0
	v_mov_b32_e32 v33, v0
	v_mov_b32_e32 v34, v0
	v_mov_b32_e32 v35, v0
	v_mov_b32_e32 v36, v0
	v_mov_b32_e32 v37, v0
	v_mov_b32_e32 v38, v0
	v_mov_b32_e32 v39, v0
	v_mov_b32_e32 v48, v0
	v_mov_b32_e32 v49, v0
	v_mov_b32_e32 v50, v0
	v_mov_b32_e32 v51, v0
	v_mov_b32_e32 v52, v0
	v_mov_b32_e32 v53, v0
	v_mov_b32_e32 v54, v0
	v_mov_b32_e32 v55, v0
	v_mov_b32_e32 v8, v0
	v_mov_b32_e32 v9, v0
	v_mov_b32_e32 v10, v0
	v_mov_b32_e32 v11, v0
	v_mov_b32_e32 v12, v0
	v_mov_b32_e32 v13, v0
	v_mov_b32_e32 v14, v0
	v_mov_b32_e32 v15, v0
	v_mov_b32_e32 v24, v0
	v_mov_b32_e32 v25, v0
	v_mov_b32_e32 v26, v0
	v_mov_b32_e32 v27, v0
	v_mov_b32_e32 v28, v0
	v_mov_b32_e32 v29, v0
	v_mov_b32_e32 v30, v0
	v_mov_b32_e32 v31, v0
	v_mov_b32_e32 v40, v0
	v_mov_b32_e32 v41, v0
	v_mov_b32_e32 v42, v0
	v_mov_b32_e32 v43, v0
	v_mov_b32_e32 v44, v0
	v_mov_b32_e32 v45, v0
	v_mov_b32_e32 v46, v0
	v_mov_b32_e32 v47, v0
	v_mov_b32_e32 v56, v0
	v_mov_b32_e32 v57, v0
	v_mov_b32_e32 v58, v0
	v_mov_b32_e32 v59, v0
	v_mov_b32_e32 v60, v0
	v_mov_b32_e32 v61, v0
	v_mov_b32_e32 v62, v0
	v_mov_b32_e32 v63, v0
	v_mov_b32_e32 v64, v0
	v_mov_b32_e32 v65, v0
	v_mov_b32_e32 v66, v0
	v_mov_b32_e32 v67, v0
	v_mov_b32_e32 v68, v0
	v_mov_b32_e32 v69, v0
	v_mov_b32_e32 v70, v0
	v_mov_b32_e32 v71, v0
	v_mov_b32_e32 v80, v0
	v_mov_b32_e32 v81, v0
	v_mov_b32_e32 v82, v0
	v_mov_b32_e32 v83, v0
	v_mov_b32_e32 v84, v0
	v_mov_b32_e32 v85, v0
	v_mov_b32_e32 v86, v0
	v_mov_b32_e32 v87, v0
	v_mov_b32_e32 v96, v0
	v_mov_b32_e32 v97, v0
	v_mov_b32_e32 v98, v0
	v_mov_b32_e32 v99, v0
	v_mov_b32_e32 v100, v0
	v_mov_b32_e32 v101, v0
	v_mov_b32_e32 v102, v0
	v_mov_b32_e32 v103, v0
	v_mov_b32_e32 v112, v0
	v_mov_b32_e32 v113, v0
	v_mov_b32_e32 v114, v0
	v_mov_b32_e32 v115, v0
	v_mov_b32_e32 v116, v0
	v_mov_b32_e32 v117, v0
	v_mov_b32_e32 v118, v0
	v_mov_b32_e32 v119, v0
	v_mov_b32_e32 v72, v0
	v_mov_b32_e32 v73, v0
	v_mov_b32_e32 v74, v0
	v_mov_b32_e32 v75, v0
	v_mov_b32_e32 v76, v0
	v_mov_b32_e32 v77, v0
	v_mov_b32_e32 v78, v0
	v_mov_b32_e32 v79, v0
	v_mov_b32_e32 v88, v0
	v_mov_b32_e32 v89, v0
	v_mov_b32_e32 v90, v0
	v_mov_b32_e32 v91, v0
	v_mov_b32_e32 v92, v0
	v_mov_b32_e32 v93, v0
	v_mov_b32_e32 v94, v0
	v_mov_b32_e32 v95, v0
	v_mov_b32_e32 v104, v0
	v_mov_b32_e32 v105, v0
	v_mov_b32_e32 v106, v0
	v_mov_b32_e32 v107, v0
	v_mov_b32_e32 v108, v0
	v_mov_b32_e32 v109, v0
	v_mov_b32_e32 v110, v0
	v_mov_b32_e32 v111, v0
	v_mov_b32_e32 v120, v0
	v_mov_b32_e32 v121, v0
	v_mov_b32_e32 v122, v0
	v_mov_b32_e32 v123, v0
	v_mov_b32_e32 v124, v0
	v_mov_b32_e32 v125, v0
	v_mov_b32_e32 v126, v0
	v_mov_b32_e32 v127, v0
	s_branch .LBB0_989

; #define PG8_STAGE(bufoff, gbase, voff) do { _Pragma("unroll") for (int _i = 0; _i < 2; ++_i) \
;         __builtin_amdgcn_global_load_lds((const unsigned*)((const char*)(gbase) + (voff)[_i]), (LAS unsigned*)(lds + (bufoff) + ldsw + _i * 8192), 16, 0, 0); } while (0)
; #define PG8_LDA(dst, b, h) do { _Pragma("unroll") for (int m = 0; m < 4; ++m) _Pragma("unroll") for (int k = 0; k < 2; ++k) dst[m][k] = *(const LAS bf16x8*)(lds + PG8_SA(b, h) + aoff + m * 2048 + k * 1024); } while (0)
; #define PG8_LDB(dst, b, h) do { _Pragma("unroll") for (int n = 0; n < 2; ++n) _Pragma("unroll") for (int k = 0; k < 2; ++k) dst[n][k] = *(const LAS bf16x8*)(lds + PG8_SB(b, h) + boff + n * 2048 + k * 1024); } while (0)
; #define PG8_MMA(ai, bj, At, Bt) do { __builtin_amdgcn_s_setprio(1); _Pragma("unroll") for (int m = 0; m < 4; ++m) _Pragma("unroll") for (int n = 0; n < 2; ++n) _Pragma("unroll") for (int k = 0; k < 2; ++k) \
;         acc[ai][bj][m][n] = __builtin_amdgcn_mfma_f32_16x16x32_bf16(Bt[n][k], At[m][k], acc[ai][bj][m][n], 0, 0, 0); __builtin_amdgcn_s_setprio(0); } while (0)
; #define PG8_WAIT_V(n) asm volatile("s_waitcnt vmcnt(" #n ")" ::: "memory")
; #define PG8_WAIT_L(n) asm volatile("s_waitcnt lgkmcnt(" #n ")" ::: "memory")
; #define PG8_BAR __builtin_amdgcn_s_barrier()
; #define PG8_SCHED __builtin_amdgcn_sched_barrier(0)
; template <class GEO, class Epi>
; __device__ __forceinline__ void gemm_phase(LAS unsigned char* lds, const Gemm g, const StaticOrder& S, const Epi& E) {
;     ...
;             PG8_LDB(B0, 0, 0); PG8_LDB(B1, 0, 1); PG8_SCHED; PG8_LDA(At, 0, 0); PG8_STAGE(PG8_SA(1, 1), a1 + hstepA, voffA);
;             PG8_WAIT_V(8); PG8_WAIT_L(0); PG8_BAR; PG8_MMA(0, 0, At, B0); PG8_MMA(0, 1, At, B1); PG8_BAR; PG8_SCHED;
;             PG8_LDA(At, 0, 1); PG8_STAGE(PG8_SB(0, 0), b2, voffB); PG8_STAGE(PG8_SB(0, 1), b2 + hstepB, voffB); PG8_STAGE(PG8_SA(0, 0), a2, voffA);
;             PG8_WAIT_V(8); PG8_WAIT_L(0); PG8_BAR; PG8_MMA(1, 0, At, B0); PG8_MMA(1, 1, At, B1); PG8_BAR; PG8_SCHED;
.LBB0_989:
	ds_read_b128 v[144:147], v152
	ds_read_b128 v[156:159], v152 offset:1024
	ds_read_b128 v[166:169], v152 offset:2048
	ds_read_b128 v[170:173], v152 offset:3072
	ds_read_b128 v[174:177], v153
	ds_read_b128 v[178:181], v153 offset:1024
	ds_read_b128 v[182:185], v153 offset:2048
	ds_read_b128 v[186:189], v153 offset:3072
	s_add_u32 s38, s52, 0xfffc0080
	s_addc_u32 s39, s53, -1
	s_cmp_eq_u32 s67, 12
	s_cselect_b32 s57, s15, s39
	s_cselect_b32 s56, s23, s38
	s_cselect_b32 s55, s28, s66
	s_cselect_b32 s54, s47, s65
	v_lshl_add_u64 v[160:161], s[52:53], 0, v[136:137]
	s_add_i32 m0, s1, 0xc000
	ds_read_b128 v[190:193], v154
	ds_read_b128 v[194:197], v154 offset:1024
	ds_read_b128 v[198:201], v154 offset:2048
	ds_read_b128 v[202:205], v154 offset:3072
	ds_read_b128 v[212:215], v154 offset:4096
	ds_read_b128 v[216:219], v154 offset:5120
	ds_read_b128 v[220:223], v154 offset:6144
	ds_read_b128 v[224:227], v154 offset:7168
	global_load_lds_dwordx4 v[160:161], off
	v_lshl_add_u64 v[160:161], s[52:53], 0, v[138:139]
	s_add_i32 m0, s1, 0xe000
	s_nop 0
	global_load_lds_dwordx4 v[160:161], off
	s_waitcnt vmcnt(8)
	s_waitcnt lgkmcnt(0)
	s_barrier
	s_waitcnt lgkmcnt(0)
	v_mfma_f32_16x16x32_bf16 v[124:127], v[144:147], v[190:193], v[124:127]
	v_mfma_f32_16x16x32_bf16 v[120:123], v[166:169], v[190:193], v[120:123]
	v_mfma_f32_16x16x32_bf16 v[108:111], v[144:147], v[198:201], v[108:111]
	v_mfma_f32_16x16x32_bf16 v[104:107], v[166:169], v[198:201], v[104:107]
	v_mfma_f32_16x16x32_bf16 v[92:95], v[144:147], v[212:215], v[92:95]
	v_mfma_f32_16x16x32_bf16 v[88:91], v[166:169], v[212:215], v[88:91]
	v_mfma_f32_16x16x32_bf16 v[76:79], v[144:147], v[220:223], v[76:79]
	v_mfma_f32_16x16x32_bf16 v[72:75], v[166:169], v[220:223], v[72:75]
	v_mfma_f32_16x16x32_bf16 v[124:127], v[156:159], v[194:197], v[124:127]
	v_mfma_f32_16x16x32_bf16 v[120:123], v[170:173], v[194:197], v[120:123]
	v_mfma_f32_16x16x32_bf16 v[108:111], v[156:159], v[202:205], v[108:111]
	v_mfma_f32_16x16x32_bf16 v[104:107], v[170:173], v[202:205], v[104:107]
	v_mfma_f32_16x16x32_bf16 v[92:95], v[156:159], v[216:219], v[92:95]
	v_mfma_f32_16x16x32_bf16 v[88:91], v[170:173], v[216:219], v[88:91]
	v_mfma_f32_16x16x32_bf16 v[76:79], v[156:159], v[224:227], v[76:79]
	v_mfma_f32_16x16x32_bf16 v[72:75], v[170:173], v[224:227], v[72:75]
	v_mfma_f32_16x16x32_bf16 v[116:119], v[174:177], v[190:193], v[116:119]
	v_mfma_f32_16x16x32_bf16 v[112:115], v[182:185], v[190:193], v[112:115]
	v_mfma_f32_16x16x32_bf16 v[100:103], v[174:177], v[198:201], v[100:103]
	v_mfma_f32_16x16x32_bf16 v[96:99], v[182:185], v[198:201], v[96:99]
	v_mfma_f32_16x16x32_bf16 v[84:87], v[174:177], v[212:215], v[84:87]
	v_mfma_f32_16x16x32_bf16 v[80:83], v[182:185], v[212:215], v[80:83]
	v_mfma_f32_16x16x32_bf16 v[68:71], v[174:177], v[220:223], v[68:71]
	v_mfma_f32_16x16x32_bf16 v[64:67], v[182:185], v[220:223], v[64:67]
	v_mfma_f32_16x16x32_bf16 v[116:119], v[178:181], v[194:197], v[116:119]
	v_mfma_f32_16x16x32_bf16 v[112:115], v[186:189], v[194:197], v[112:115]
	v_mfma_f32_16x16x32_bf16 v[100:103], v[178:181], v[202:205], v[100:103]
	v_mfma_f32_16x16x32_bf16 v[96:99], v[186:189], v[202:205], v[96:99]
	v_mfma_f32_16x16x32_bf16 v[84:87], v[178:181], v[216:219], v[84:87]
	v_mfma_f32_16x16x32_bf16 v[80:83], v[186:189], v[216:219], v[80:83]
	v_mfma_f32_16x16x32_bf16 v[68:71], v[178:181], v[224:227], v[68:71]
	v_mfma_f32_16x16x32_bf16 v[64:67], v[186:189], v[224:227], v[64:67]
	s_barrier
	s_add_i32 s38, s61, s0
	v_lshl_add_u64 v[160:161], s[54:55], 0, v[130:131]
	s_mov_b32 m0, s38
	ds_read_b128 v[190:193], v154 offset:16384
	ds_read_b128 v[194:197], v154 offset:17408
	ds_read_b128 v[198:201], v154 offset:18432
	ds_read_b128 v[202:205], v154 offset:19456
	ds_read_b128 v[212:215], v154 offset:20480
	ds_read_b128 v[216:219], v154 offset:21504
	ds_read_b128 v[220:223], v154 offset:22528
	ds_read_b128 v[224:227], v154 offset:23552
	global_load_lds_dwordx4 v[160:161], off
	s_add_i32 m0, s38, 0x2000
	s_add_u32 s38, s54, 0x100000
	v_lshl_add_u64 v[206:207], s[54:55], 0, v[134:135]
	s_addc_u32 s39, s55, 0
	s_add_i32 s68, s62, s0
	global_load_lds_dwordx4 v[206:207], off
	v_lshl_add_u64 v[228:229], s[38:39], 0, v[130:131]
	s_mov_b32 m0, s68
	v_lshl_add_u64 v[230:231], s[56:57], 0, v[132:133]
	global_load_lds_dwordx4 v[228:229], off
	v_lshl_add_u64 v[228:229], s[38:39], 0, v[134:135]
	s_add_i32 m0, s68, 0x2000
	s_nop 0
	global_load_lds_dwordx4 v[228:229], off
	v_lshl_add_u64 v[228:229], s[56:57], 0, v[128:129]
	s_mov_b32 m0, s1
	s_nop 0
	global_load_lds_dwordx4 v[228:229], off
	s_mov_b32 m0, s4
	s_nop 0
	global_load_lds_dwordx4 v[230:231], off
	s_waitcnt vmcnt(8)
	s_waitcnt lgkmcnt(0)
	s_barrier
; #define PG8_STAGE(bufoff, gbase, voff) do { _Pragma("unroll") for (int _i = 0; _i < 2; ++_i) \
;         __builtin_amdgcn_global_load_lds((const unsigned*)((const char*)(gbase) + (voff)[_i]), (LAS unsigned*)(lds + (bufoff) + ldsw + _i * 8192), 16, 0, 0); } while (0)
; #define PG8_LDA(dst, b, h) do { _Pragma("unroll") for (int m = 0; m < 4; ++m) _Pragma("unroll") for (int k = 0; k < 2; ++k) dst[m][k] = *(const LAS bf16x8*)(lds + PG8_SA(b, h) + aoff + m * 2048 + k * 1024); } while (0)
; #define PG8_LDB(dst, b, h) do { _Pragma("unroll") for (int n = 0; n < 2; ++n) _Pragma("unroll") for (int k = 0; k < 2; ++k) dst[n][k] = *(const LAS bf16x8*)(lds + PG8_SB(b, h) + boff + n * 2048 + k * 1024); } while (0)
; #define PG8_MMA(ai, bj, At, Bt) do { __builtin_amdgcn_s_setprio(1); _Pragma("unroll") for (int m = 0; m < 4; ++m) _Pragma("unroll") for (int n = 0; n < 2; ++n) _Pragma("unroll") for (int k = 0; k < 2; ++k) \
;         acc[ai][bj][m][n] = __builtin_amdgcn_mfma_f32_16x16x32_bf16(Bt[n][k], At[m][k], acc[ai][bj][m][n], 0, 0, 0); __builtin_amdgcn_s_setprio(0); } while (0)
; #define PG8_WAIT_V(n) asm volatile("s_waitcnt vmcnt(" #n ")" ::: "memory")
; #define PG8_WAIT_L(n) asm volatile("s_waitcnt lgkmcnt(" #n ")" ::: "memory")
; #define PG8_BAR __builtin_amdgcn_s_barrier()
; #define PG8_SCHED __builtin_amdgcn_sched_barrier(0)
; template <class GEO, class Epi>
; __device__ __forceinline__ void gemm_phase(LAS unsigned char* lds, const Gemm g, const StaticOrder& S, const Epi& E) {
;     ...
;             PG8_WAIT_V(8); PG8_WAIT_L(0); PG8_BAR; PG8_MMA(1, 0, At, B0); PG8_MMA(1, 1, At, B1); PG8_BAR; PG8_SCHED;
;             PG8_LDB(B0, 1, 0); PG8_LDB(B1, 1, 1); PG8_SCHED; PG8_LDA(At, 1, 0); PG8_STAGE(PG8_SA(0, 1), a2 + hstepA, voffA);
;             PG8_WAIT_V(8); PG8_WAIT_L(0); PG8_BAR; PG8_MMA(0, 0, At, B0); PG8_MMA(0, 1, At, B1); PG8_BAR; PG8_SCHED;
	s_waitcnt lgkmcnt(0)
	v_mfma_f32_16x16x32_bf16 v[60:63], v[144:147], v[190:193], v[60:63]
	v_mfma_f32_16x16x32_bf16 v[56:59], v[166:169], v[190:193], v[56:59]
	v_mfma_f32_16x16x32_bf16 v[44:47], v[144:147], v[198:201], v[44:47]
	v_mfma_f32_16x16x32_bf16 v[40:43], v[166:169], v[198:201], v[40:43]
	v_mfma_f32_16x16x32_bf16 v[28:31], v[144:147], v[212:215], v[28:31]
	v_mfma_f32_16x16x32_bf16 v[24:27], v[166:169], v[212:215], v[24:27]
	v_mfma_f32_16x16x32_bf16 v[12:15], v[144:147], v[220:223], v[12:15]
	v_mfma_f32_16x16x32_bf16 v[8:11], v[166:169], v[220:223], v[8:11]
	v_mfma_f32_16x16x32_bf16 v[60:63], v[156:159], v[194:197], v[60:63]
	v_mfma_f32_16x16x32_bf16 v[56:59], v[170:173], v[194:197], v[56:59]
	v_mfma_f32_16x16x32_bf16 v[44:47], v[156:159], v[202:205], v[44:47]
	v_mfma_f32_16x16x32_bf16 v[40:43], v[170:173], v[202:205], v[40:43]
	v_mfma_f32_16x16x32_bf16 v[28:31], v[156:159], v[216:219], v[28:31]
	v_mfma_f32_16x16x32_bf16 v[24:27], v[170:173], v[216:219], v[24:27]
	v_mfma_f32_16x16x32_bf16 v[12:15], v[156:159], v[224:227], v[12:15]
	v_mfma_f32_16x16x32_bf16 v[8:11], v[170:173], v[224:227], v[8:11]
	v_mfma_f32_16x16x32_bf16 v[52:55], v[174:177], v[190:193], v[52:55]
	v_mfma_f32_16x16x32_bf16 v[48:51], v[182:185], v[190:193], v[48:51]
	v_mfma_f32_16x16x32_bf16 v[36:39], v[174:177], v[198:201], v[36:39]
	v_mfma_f32_16x16x32_bf16 v[32:35], v[182:185], v[198:201], v[32:35]
	v_mfma_f32_16x16x32_bf16 v[20:23], v[174:177], v[212:215], v[20:23]
	v_mfma_f32_16x16x32_bf16 v[16:19], v[182:185], v[212:215], v[16:19]
	v_mfma_f32_16x16x32_bf16 v[4:7], v[174:177], v[220:223], v[4:7]
	v_mfma_f32_16x16x32_bf16 v[0:3], v[182:185], v[220:223], v[0:3]
	v_mfma_f32_16x16x32_bf16 v[52:55], v[178:181], v[194:197], v[52:55]
	v_mfma_f32_16x16x32_bf16 v[48:51], v[186:189], v[194:197], v[48:51]
	v_mfma_f32_16x16x32_bf16 v[36:39], v[178:181], v[202:205], v[36:39]
	v_mfma_f32_16x16x32_bf16 v[32:35], v[186:189], v[202:205], v[32:35]
	v_mfma_f32_16x16x32_bf16 v[20:23], v[178:181], v[216:219], v[20:23]
	v_mfma_f32_16x16x32_bf16 v[16:19], v[186:189], v[216:219], v[16:19]
	v_mfma_f32_16x16x32_bf16 v[4:7], v[178:181], v[224:227], v[4:7]
	v_mfma_f32_16x16x32_bf16 v[0:3], v[186:189], v[224:227], v[0:3]
	s_barrier
	s_add_i32 s68, 0, 0x18000
	v_add_u32_e32 v155, s68, v149
	s_add_i32 s69, 0, 0x1c000
	ds_read_b128 v[144:147], v155
	ds_read_b128 v[156:159], v155 offset:1024
	ds_read_b128 v[166:169], v155 offset:2048
	ds_read_b128 v[170:173], v155 offset:3072
	v_add_u32_e32 v155, s69, v149
	ds_read_b128 v[174:177], v155
	ds_read_b128 v[178:181], v155 offset:1024
	ds_read_b128 v[182:185], v155 offset:2048
	ds_read_b128 v[186:189], v155 offset:3072
	s_add_u32 s38, s56, 0x40000
	s_addc_u32 s39, s57, 0
	s_mov_b32 m0, s5
	v_lshl_add_u64 v[232:233], s[38:39], 0, v[128:129]
	ds_read_b128 v[190:193], v154 offset:32768
	ds_read_b128 v[194:197], v154 offset:33792
	ds_read_b128 v[198:201], v154 offset:34816
	ds_read_b128 v[202:205], v154 offset:35840
	ds_read_b128 v[212:215], v154 offset:36864
	ds_read_b128 v[216:219], v154 offset:37888
	ds_read_b128 v[220:223], v154 offset:38912
	ds_read_b128 v[224:227], v154 offset:39936
	global_load_lds_dwordx4 v[232:233], off
	v_lshl_add_u64 v[232:233], s[38:39], 0, v[132:133]
	s_mov_b32 m0, s6
	s_nop 0
	global_load_lds_dwordx4 v[232:233], off
	s_waitcnt vmcnt(8)
	s_waitcnt lgkmcnt(0)
	s_barrier
	s_waitcnt lgkmcnt(0)
	v_mfma_f32_16x16x32_bf16 v[124:127], v[144:147], v[190:193], v[124:127]
	v_mfma_f32_16x16x32_bf16 v[120:123], v[166:169], v[190:193], v[120:123]
	v_mfma_f32_16x16x32_bf16 v[108:111], v[144:147], v[198:201], v[108:111]
	v_mfma_f32_16x16x32_bf16 v[104:107], v[166:169], v[198:201], v[104:107]
	v_mfma_f32_16x16x32_bf16 v[92:95], v[144:147], v[212:215], v[92:95]
	v_mfma_f32_16x16x32_bf16 v[88:91], v[166:169], v[212:215], v[88:91]
	v_mfma_f32_16x16x32_bf16 v[76:79], v[144:147], v[220:223], v[76:79]
	v_mfma_f32_16x16x32_bf16 v[72:75], v[166:169], v[220:223], v[72:75]
	v_mfma_f32_16x16x32_bf16 v[124:127], v[156:159], v[194:197], v[124:127]
	v_mfma_f32_16x16x32_bf16 v[120:123], v[170:173], v[194:197], v[120:123]
	v_mfma_f32_16x16x32_bf16 v[108:111], v[156:159], v[202:205], v[108:111]
	v_mfma_f32_16x16x32_bf16 v[104:107], v[170:173], v[202:205], v[104:107]
	v_mfma_f32_16x16x32_bf16 v[92:95], v[156:159], v[216:219], v[92:95]
	v_mfma_f32_16x16x32_bf16 v[88:91], v[170:173], v[216:219], v[88:91]
	v_mfma_f32_16x16x32_bf16 v[76:79], v[156:159], v[224:227], v[76:79]
	v_mfma_f32_16x16x32_bf16 v[72:75], v[170:173], v[224:227], v[72:75]
	v_mfma_f32_16x16x32_bf16 v[116:119], v[174:177], v[190:193], v[116:119]
	v_mfma_f32_16x16x32_bf16 v[112:115], v[182:185], v[190:193], v[112:115]
	v_mfma_f32_16x16x32_bf16 v[100:103], v[174:177], v[198:201], v[100:103]
	v_mfma_f32_16x16x32_bf16 v[96:99], v[182:185], v[198:201], v[96:99]
	v_mfma_f32_16x16x32_bf16 v[84:87], v[174:177], v[212:215], v[84:87]
	v_mfma_f32_16x16x32_bf16 v[80:83], v[182:185], v[212:215], v[80:83]
	v_mfma_f32_16x16x32_bf16 v[68:71], v[174:177], v[220:223], v[68:71]
	v_mfma_f32_16x16x32_bf16 v[64:67], v[182:185], v[220:223], v[64:67]
	v_mfma_f32_16x16x32_bf16 v[116:119], v[178:181], v[194:197], v[116:119]
	v_mfma_f32_16x16x32_bf16 v[112:115], v[186:189], v[194:197], v[112:115]
	v_mfma_f32_16x16x32_bf16 v[100:103], v[178:181], v[202:205], v[100:103]
	v_mfma_f32_16x16x32_bf16 v[96:99], v[186:189], v[202:205], v[96:99]
	v_mfma_f32_16x16x32_bf16 v[84:87], v[178:181], v[216:219], v[84:87]
	v_mfma_f32_16x16x32_bf16 v[80:83], v[186:189], v[216:219], v[80:83]
	v_mfma_f32_16x16x32_bf16 v[68:71], v[178:181], v[224:227], v[68:71]
	v_mfma_f32_16x16x32_bf16 v[64:67], v[186:189], v[224:227], v[64:67]
	s_barrier
; #define PG8_STAGE(bufoff, gbase, voff) do { _Pragma("unroll") for (int _i = 0; _i < 2; ++_i) \
;         __builtin_amdgcn_global_load_lds((const unsigned*)((const char*)(gbase) + (voff)[_i]), (LAS unsigned*)(lds + (bufoff) + ldsw + _i * 8192), 16, 0, 0); } while (0)
; #define PG8_LDA(dst, b, h) do { _Pragma("unroll") for (int m = 0; m < 4; ++m) _Pragma("unroll") for (int k = 0; k < 2; ++k) dst[m][k] = *(const LAS bf16x8*)(lds + PG8_SA(b, h) + aoff + m * 2048 + k * 1024); } while (0)
; #define PG8_MMA(ai, bj, At, Bt) do { __builtin_amdgcn_s_setprio(1); _Pragma("unroll") for (int m = 0; m < 4; ++m) _Pragma("unroll") for (int n = 0; n < 2; ++n) _Pragma("unroll") for (int k = 0; k < 2; ++k) \
;         acc[ai][bj][m][n] = __builtin_amdgcn_mfma_f32_16x16x32_bf16(Bt[n][k], At[m][k], acc[ai][bj][m][n], 0, 0, 0); __builtin_amdgcn_s_setprio(0); } while (0)
; #define PG8_WAIT_V(n) asm volatile("s_waitcnt vmcnt(" #n ")" ::: "memory")
; #define PG8_WAIT_L(n) asm volatile("s_waitcnt lgkmcnt(" #n ")" ::: "memory")
; #define PG8_BAR __builtin_amdgcn_s_barrier()
; #define PG8_SCHED __builtin_amdgcn_sched_barrier(0)
; template <class GEO, class Epi>
; __device__ __forceinline__ void gemm_phase(LAS unsigned char* lds, const Gemm g, const StaticOrder& S, const Epi& E) {
;     ...
;             PG8_LDA(At, 1, 1); PG8_STAGE(PG8_SB(1, 0), b3, voffB); PG8_STAGE(PG8_SB(1, 1), b3 + hstepB, voffB); PG8_STAGE(PG8_SA(1, 0), a3, voffA);
;             PG8_WAIT_V(8); PG8_WAIT_L(0); PG8_BAR; PG8_MMA(1, 0, At, B0); PG8_MMA(1, 1, At, B1); PG8_BAR; PG8_SCHED;
;         }
;         if (wr == 0) PG8_BAR;
	s_add_i32 s38, s68, s0
	v_lshl_add_u64 v[160:161], v[160:161], 0, s[34:35]
	s_mov_b32 m0, s38
	ds_read_b128 v[190:193], v154 offset:49152
	ds_read_b128 v[194:197], v154 offset:50176
	ds_read_b128 v[198:201], v154 offset:51200
	ds_read_b128 v[202:205], v154 offset:52224
	ds_read_b128 v[212:215], v154 offset:53248
	ds_read_b128 v[216:219], v154 offset:54272
	ds_read_b128 v[220:223], v154 offset:55296
	ds_read_b128 v[224:227], v154 offset:56320
	global_load_lds_dwordx4 v[160:161], off
	s_add_i32 m0, s38, 0x2000
	s_add_u32 s38, s54, 0x100080
	v_lshl_add_u64 v[160:161], v[206:207], 0, s[34:35]
	s_addc_u32 s39, s55, 0
	s_add_i32 s54, s69, s0
	global_load_lds_dwordx4 v[160:161], off
	v_lshl_add_u64 v[160:161], s[38:39], 0, v[130:131]
	s_mov_b32 m0, s54
	s_nop 0
	global_load_lds_dwordx4 v[160:161], off
	v_lshl_add_u64 v[160:161], s[38:39], 0, v[134:135]
	s_add_i32 m0, s54, 0x2000
	s_nop 0
	global_load_lds_dwordx4 v[160:161], off
	v_lshl_add_u64 v[160:161], v[228:229], 0, s[34:35]
	s_mov_b32 m0, s7
	s_nop 0
	global_load_lds_dwordx4 v[160:161], off
	v_lshl_add_u64 v[160:161], v[230:231], 0, s[34:35]
	s_mov_b32 m0, s12
	s_nop 0
	global_load_lds_dwordx4 v[160:161], off
	s_waitcnt vmcnt(8)
	s_waitcnt lgkmcnt(0)
	s_barrier
	s_waitcnt lgkmcnt(0)
	v_mfma_f32_16x16x32_bf16 v[60:63], v[144:147], v[190:193], v[60:63]
	v_mfma_f32_16x16x32_bf16 v[56:59], v[166:169], v[190:193], v[56:59]
	v_mfma_f32_16x16x32_bf16 v[44:47], v[144:147], v[198:201], v[44:47]
	v_mfma_f32_16x16x32_bf16 v[40:43], v[166:169], v[198:201], v[40:43]
	v_mfma_f32_16x16x32_bf16 v[28:31], v[144:147], v[212:215], v[28:31]
	v_mfma_f32_16x16x32_bf16 v[24:27], v[166:169], v[212:215], v[24:27]
	v_mfma_f32_16x16x32_bf16 v[12:15], v[144:147], v[220:223], v[12:15]
	v_mfma_f32_16x16x32_bf16 v[8:11], v[166:169], v[220:223], v[8:11]
	v_mfma_f32_16x16x32_bf16 v[60:63], v[156:159], v[194:197], v[60:63]
	v_mfma_f32_16x16x32_bf16 v[56:59], v[170:173], v[194:197], v[56:59]
	v_mfma_f32_16x16x32_bf16 v[44:47], v[156:159], v[202:205], v[44:47]
	v_mfma_f32_16x16x32_bf16 v[40:43], v[170:173], v[202:205], v[40:43]
	v_mfma_f32_16x16x32_bf16 v[28:31], v[156:159], v[216:219], v[28:31]
	v_mfma_f32_16x16x32_bf16 v[24:27], v[170:173], v[216:219], v[24:27]
	v_mfma_f32_16x16x32_bf16 v[12:15], v[156:159], v[224:227], v[12:15]
	v_mfma_f32_16x16x32_bf16 v[8:11], v[170:173], v[224:227], v[8:11]
	v_mfma_f32_16x16x32_bf16 v[52:55], v[174:177], v[190:193], v[52:55]
	v_mfma_f32_16x16x32_bf16 v[48:51], v[182:185], v[190:193], v[48:51]
	v_mfma_f32_16x16x32_bf16 v[36:39], v[174:177], v[198:201], v[36:39]
	v_mfma_f32_16x16x32_bf16 v[32:35], v[182:185], v[198:201], v[32:35]
	v_mfma_f32_16x16x32_bf16 v[20:23], v[174:177], v[212:215], v[20:23]
	v_mfma_f32_16x16x32_bf16 v[16:19], v[182:185], v[212:215], v[16:19]
	v_mfma_f32_16x16x32_bf16 v[4:7], v[174:177], v[220:223], v[4:7]
	v_mfma_f32_16x16x32_bf16 v[0:3], v[182:185], v[220:223], v[0:3]
	v_mfma_f32_16x16x32_bf16 v[52:55], v[178:181], v[194:197], v[52:55]
	v_mfma_f32_16x16x32_bf16 v[48:51], v[186:189], v[194:197], v[48:51]
	v_mfma_f32_16x16x32_bf16 v[36:39], v[178:181], v[202:205], v[36:39]
	v_mfma_f32_16x16x32_bf16 v[32:35], v[186:189], v[202:205], v[32:35]
	v_mfma_f32_16x16x32_bf16 v[20:23], v[178:181], v[216:219], v[20:23]
	v_mfma_f32_16x16x32_bf16 v[16:19], v[186:189], v[216:219], v[16:19]
	v_mfma_f32_16x16x32_bf16 v[4:7], v[178:181], v[224:227], v[4:7]
	v_mfma_f32_16x16x32_bf16 v[0:3], v[186:189], v[224:227], v[0:3]
	s_add_i32 s67, s67, 2
	s_add_u32 s52, s52, 0x100
	s_addc_u32 s53, s53, 0
	s_add_u32 s65, s65, 0x100
	s_addc_u32 s66, s66, 0
	s_cmp_gt_u32 s67, 13
	s_cbranch_scc0 .Lrot_4
	s_barrier
	s_and_b64 vcc, exec, s[20:21]
	s_cbranch_vccz .LBB0_992
	s_barrier

; template <class GEO, class Epi>
; __device__ __forceinline__ void gemm_phase(LAS unsigned char* lds, const Gemm g, const StaticOrder& S, const Epi& E) {
;     ...
;         const bool has_next = S.next(ui + 1, nxt);
;         const char* nA = has_next ? PG8_APTR(nxt) : cA; const char* nB = has_next ? PG8_BPTR(nxt) : cB;
; #pragma nounroll
;         for (int t = 0; t < nt; t += 2) {
;             const bool last = (t == nt - 2);
;             const char* a1 = cA + (size_t)(t + 1) * kstep;
;             const char* a2 = last ? nA : cA + (size_t)(t + 2) * kstep; const char* b2 = last ? nB : cB + (size_t)(t + 2) * kstep;
;     ...
; #pragma unroll
;         for (int a = 0; a < 2; ++a)
; #pragma unroll
;             for (int b = 0; b < 2; ++b)
; #pragma unroll
;                 for (int m = 0; m < 4; ++m)
; #pragma unroll
;                     for (int n = 0; n < 2; ++n) acc[a][b][m][n] = (f32x4){0.f, 0.f, 0.f, 0.f};
;         cur = nxt; cA = nA; cB = nB; ++ui;
.LBB0_1074:
	s_ashr_i32 s31, s30, 31
	s_lshl_b64 s[34:35], s[30:31], 19
	s_add_u32 s34, s26, s34
	s_addc_u32 s35, s27, s35
	s_and_b64 s[38:39], s[40:41], exec
	s_cselect_b32 s21, s35, s23
	s_cselect_b32 s31, s34, s22
	s_and_b32 s14, s36, 0x3fffffff
	s_lshl_b64 s[38:39], s[14:15], 19
	s_add_u32 s42, s76, s38
	s_addc_u32 s43, s77, s39
	s_and_b64 s[38:39], s[40:41], exec
	s_cselect_b32 s14, s43, s45
	s_cselect_b32 s48, s42, s44
	s_add_u32 s22, s22, 0x40080
	s_addc_u32 s23, s23, 0
	s_add_u32 s49, s44, 0x100
	v_mov_b32_e32 v0, 0
	s_addc_u32 s50, s45, 0
	s_mov_b32 s51, -2
	v_mov_b32_e32 v1, v0
	v_mov_b32_e32 v2, v0
	v_mov_b32_e32 v3, v0
	v_mov_b32_e32 v4, v0
	v_mov_b32_e32 v5, v0
	v_mov_b32_e32 v6, v0
	v_mov_b32_e32 v7, v0
	v_mov_b32_e32 v16, v0
	v_mov_b32_e32 v17, v0
	v_mov_b32_e32 v18, v0
	v_mov_b32_e32 v19, v0
	v_mov_b32_e32 v20, v0
	v_mov_b32_e32 v21, v0
	v_mov_b32_e32 v22, v0
	v_mov_b32_e32 v23, v0
	v_mov_b32_e32 v32, v0
	v_mov_b32_e32 v33, v0
	v_mov_b32_e32 v34, v0
	v_mov_b32_e32 v35, v0
	v_mov_b32_e32 v36, v0
	v_mov_b32_e32 v37, v0
	v_mov_b32_e32 v38, v0
	v_mov_b32_e32 v39, v0
	v_mov_b32_e32 v48, v0
	v_mov_b32_e32 v49, v0
	v_mov_b32_e32 v50, v0
	v_mov_b32_e32 v51, v0
	v_mov_b32_e32 v52, v0
	v_mov_b32_e32 v53, v0
	v_mov_b32_e32 v54, v0
	v_mov_b32_e32 v55, v0
	v_mov_b32_e32 v8, v0
	v_mov_b32_e32 v9, v0
	v_mov_b32_e32 v10, v0
	v_mov_b32_e32 v11, v0
	v_mov_b32_e32 v12, v0
	v_mov_b32_e32 v13, v0
	v_mov_b32_e32 v14, v0
	v_mov_b32_e32 v15, v0
	v_mov_b32_e32 v24, v0
	v_mov_b32_e32 v25, v0
	v_mov_b32_e32 v26, v0
	v_mov_b32_e32 v27, v0
	v_mov_b32_e32 v28, v0
	v_mov_b32_e32 v29, v0
	v_mov_b32_e32 v30, v0
	v_mov_b32_e32 v31, v0
	v_mov_b32_e32 v40, v0
	v_mov_b32_e32 v41, v0
	v_mov_b32_e32 v42, v0
	v_mov_b32_e32 v43, v0
	v_mov_b32_e32 v44, v0
	v_mov_b32_e32 v45, v0
	v_mov_b32_e32 v46, v0
	v_mov_b32_e32 v47, v0
	v_mov_b32_e32 v56, v0
	v_mov_b32_e32 v57, v0
	v_mov_b32_e32 v58, v0
	v_mov_b32_e32 v59, v0
	v_mov_b32_e32 v60, v0
	v_mov_b32_e32 v61, v0
	v_mov_b32_e32 v62, v0
	v_mov_b32_e32 v63, v0
	v_mov_b32_e32 v64, v0
	v_mov_b32_e32 v65, v0
	v_mov_b32_e32 v66, v0
	v_mov_b32_e32 v67, v0
	v_mov_b32_e32 v68, v0
	v_mov_b32_e32 v69, v0
	v_mov_b32_e32 v70, v0
	v_mov_b32_e32 v71, v0
	v_mov_b32_e32 v80, v0
	v_mov_b32_e32 v81, v0
	v_mov_b32_e32 v82, v0
	v_mov_b32_e32 v83, v0
	v_mov_b32_e32 v84, v0
	v_mov_b32_e32 v85, v0
	v_mov_b32_e32 v86, v0
	v_mov_b32_e32 v87, v0
	v_mov_b32_e32 v96, v0
	v_mov_b32_e32 v97, v0
	v_mov_b32_e32 v98, v0
	v_mov_b32_e32 v99, v0
	v_mov_b32_e32 v100, v0
	v_mov_b32_e32 v101, v0
	v_mov_b32_e32 v102, v0
	v_mov_b32_e32 v103, v0
	v_mov_b32_e32 v112, v0
	v_mov_b32_e32 v113, v0
	v_mov_b32_e32 v114, v0
	v_mov_b32_e32 v115, v0
	v_mov_b32_e32 v116, v0
	v_mov_b32_e32 v117, v0
	v_mov_b32_e32 v118, v0
	v_mov_b32_e32 v119, v0
	v_mov_b32_e32 v72, v0
	v_mov_b32_e32 v73, v0
	v_mov_b32_e32 v74, v0
	v_mov_b32_e32 v75, v0
	v_mov_b32_e32 v76, v0
	v_mov_b32_e32 v77, v0
	v_mov_b32_e32 v78, v0
	v_mov_b32_e32 v79, v0
	v_mov_b32_e32 v88, v0
	v_mov_b32_e32 v89, v0
	v_mov_b32_e32 v90, v0
	v_mov_b32_e32 v91, v0
	v_mov_b32_e32 v92, v0
	v_mov_b32_e32 v93, v0
	v_mov_b32_e32 v94, v0
	v_mov_b32_e32 v95, v0
	v_mov_b32_e32 v104, v0
	v_mov_b32_e32 v105, v0
	v_mov_b32_e32 v106, v0
	v_mov_b32_e32 v107, v0
	v_mov_b32_e32 v108, v0
	v_mov_b32_e32 v109, v0
	v_mov_b32_e32 v110, v0
	v_mov_b32_e32 v111, v0
	v_mov_b32_e32 v120, v0
	v_mov_b32_e32 v121, v0
	v_mov_b32_e32 v122, v0
	v_mov_b32_e32 v123, v0
	v_mov_b32_e32 v124, v0
	v_mov_b32_e32 v125, v0
	v_mov_b32_e32 v126, v0
	v_mov_b32_e32 v127, v0
	s_branch .LBB0_1075

; #define PG8_STAGE(bufoff, gbase, voff) do { _Pragma("unroll") for (int _i = 0; _i < 2; ++_i) \
;         __builtin_amdgcn_global_load_lds((const unsigned*)((const char*)(gbase) + (voff)[_i]), (LAS unsigned*)(lds + (bufoff) + ldsw + _i * 8192), 16, 0, 0); } while (0)
; #define PG8_LDA(dst, b, h) do { _Pragma("unroll") for (int m = 0; m < 4; ++m) _Pragma("unroll") for (int k = 0; k < 2; ++k) dst[m][k] = *(const LAS bf16x8*)(lds + PG8_SA(b, h) + aoff + m * 2048 + k * 1024); } while (0)
; #define PG8_LDB(dst, b, h) do { _Pragma("unroll") for (int n = 0; n < 2; ++n) _Pragma("unroll") for (int k = 0; k < 2; ++k) dst[n][k] = *(const LAS bf16x8*)(lds + PG8_SB(b, h) + boff + n * 2048 + k * 1024); } while (0)
; #define PG8_MMA(ai, bj, At, Bt) do { __builtin_amdgcn_s_setprio(1); _Pragma("unroll") for (int m = 0; m < 4; ++m) _Pragma("unroll") for (int n = 0; n < 2; ++n) _Pragma("unroll") for (int k = 0; k < 2; ++k) \
;         acc[ai][bj][m][n] = __builtin_amdgcn_mfma_f32_16x16x32_bf16(Bt[n][k], At[m][k], acc[ai][bj][m][n], 0, 0, 0); __builtin_amdgcn_s_setprio(0); } while (0)
; #define PG8_WAIT_V(n) asm volatile("s_waitcnt vmcnt(" #n ")" ::: "memory")
; #define PG8_WAIT_L(n) asm volatile("s_waitcnt lgkmcnt(" #n ")" ::: "memory")
; #define PG8_BAR __builtin_amdgcn_s_barrier()
; #define PG8_SCHED __builtin_amdgcn_sched_barrier(0)
; template <class GEO, class Epi>
; __device__ __forceinline__ void gemm_phase(LAS unsigned char* lds, const Gemm g, const StaticOrder& S, const Epi& E) {
;     ...
;             PG8_LDB(B0, 0, 0); PG8_LDB(B1, 0, 1); PG8_SCHED; PG8_LDA(At, 0, 0); PG8_STAGE(PG8_SA(1, 1), a1 + hstepA, voffA);
;             PG8_WAIT_V(8); PG8_WAIT_L(0); PG8_BAR; PG8_MMA(0, 0, At, B0); PG8_MMA(0, 1, At, B1); PG8_BAR; PG8_SCHED;
;             PG8_LDA(At, 0, 1); PG8_STAGE(PG8_SB(0, 0), b2, voffB); PG8_STAGE(PG8_SB(0, 1), b2 + hstepB, voffB); PG8_STAGE(PG8_SA(0, 0), a2, voffA);
;             PG8_WAIT_V(8); PG8_WAIT_L(0); PG8_BAR; PG8_MMA(1, 0, At, B0); PG8_MMA(1, 1, At, B1); PG8_BAR; PG8_SCHED;
.LBB0_1075:
	ds_read_b128 v[144:147], v151
	ds_read_b128 v[156:159], v151 offset:1024
	ds_read_b128 v[166:169], v151 offset:2048
	ds_read_b128 v[170:173], v151 offset:3072
	ds_read_b128 v[174:177], v152
	ds_read_b128 v[178:181], v152 offset:1024
	ds_read_b128 v[182:185], v152 offset:2048
	ds_read_b128 v[186:189], v152 offset:3072
	s_add_u32 s38, s22, 0xfffc0080
	s_addc_u32 s39, s23, -1
	s_cmp_eq_u32 s51, 12
	s_cselect_b32 s47, s21, s39
	s_cselect_b32 s46, s31, s38
	s_cselect_b32 s45, s14, s50
	s_cselect_b32 s44, s48, s49
	v_lshl_add_u64 v[160:161], s[22:23], 0, v[136:137]
	s_add_i32 m0, s1, 0xc000
	ds_read_b128 v[190:193], v153
	ds_read_b128 v[194:197], v153 offset:1024
	ds_read_b128 v[198:201], v153 offset:2048
	ds_read_b128 v[202:205], v153 offset:3072
	ds_read_b128 v[210:213], v153 offset:4096
	ds_read_b128 v[214:217], v153 offset:5120
	ds_read_b128 v[218:221], v153 offset:6144
	ds_read_b128 v[222:225], v153 offset:7168
	global_load_lds_dwordx4 v[160:161], off
	v_lshl_add_u64 v[160:161], s[22:23], 0, v[138:139]
	s_add_i32 m0, s1, 0xe000
	s_nop 0
	global_load_lds_dwordx4 v[160:161], off
	s_waitcnt vmcnt(8)
	s_waitcnt lgkmcnt(0)
	s_barrier
	s_waitcnt lgkmcnt(0)
	v_mfma_f32_16x16x32_bf16 v[124:127], v[144:147], v[190:193], v[124:127]
	v_mfma_f32_16x16x32_bf16 v[120:123], v[166:169], v[190:193], v[120:123]
	v_mfma_f32_16x16x32_bf16 v[108:111], v[144:147], v[198:201], v[108:111]
	v_mfma_f32_16x16x32_bf16 v[104:107], v[166:169], v[198:201], v[104:107]
	v_mfma_f32_16x16x32_bf16 v[92:95], v[144:147], v[210:213], v[92:95]
	v_mfma_f32_16x16x32_bf16 v[88:91], v[166:169], v[210:213], v[88:91]
	v_mfma_f32_16x16x32_bf16 v[76:79], v[144:147], v[218:221], v[76:79]
	v_mfma_f32_16x16x32_bf16 v[72:75], v[166:169], v[218:221], v[72:75]
	v_mfma_f32_16x16x32_bf16 v[124:127], v[156:159], v[194:197], v[124:127]
	v_mfma_f32_16x16x32_bf16 v[120:123], v[170:173], v[194:197], v[120:123]
	v_mfma_f32_16x16x32_bf16 v[108:111], v[156:159], v[202:205], v[108:111]
	v_mfma_f32_16x16x32_bf16 v[104:107], v[170:173], v[202:205], v[104:107]
	v_mfma_f32_16x16x32_bf16 v[92:95], v[156:159], v[214:217], v[92:95]
	v_mfma_f32_16x16x32_bf16 v[88:91], v[170:173], v[214:217], v[88:91]
	v_mfma_f32_16x16x32_bf16 v[76:79], v[156:159], v[222:225], v[76:79]
	v_mfma_f32_16x16x32_bf16 v[72:75], v[170:173], v[222:225], v[72:75]
	v_mfma_f32_16x16x32_bf16 v[116:119], v[174:177], v[190:193], v[116:119]
	v_mfma_f32_16x16x32_bf16 v[112:115], v[182:185], v[190:193], v[112:115]
	v_mfma_f32_16x16x32_bf16 v[100:103], v[174:177], v[198:201], v[100:103]
	v_mfma_f32_16x16x32_bf16 v[96:99], v[182:185], v[198:201], v[96:99]
	v_mfma_f32_16x16x32_bf16 v[84:87], v[174:177], v[210:213], v[84:87]
	v_mfma_f32_16x16x32_bf16 v[80:83], v[182:185], v[210:213], v[80:83]
	v_mfma_f32_16x16x32_bf16 v[68:71], v[174:177], v[218:221], v[68:71]
	v_mfma_f32_16x16x32_bf16 v[64:67], v[182:185], v[218:221], v[64:67]
	v_mfma_f32_16x16x32_bf16 v[116:119], v[178:181], v[194:197], v[116:119]
	v_mfma_f32_16x16x32_bf16 v[112:115], v[186:189], v[194:197], v[112:115]
	v_mfma_f32_16x16x32_bf16 v[100:103], v[178:181], v[202:205], v[100:103]
	v_mfma_f32_16x16x32_bf16 v[96:99], v[186:189], v[202:205], v[96:99]
	v_mfma_f32_16x16x32_bf16 v[84:87], v[178:181], v[214:217], v[84:87]
	v_mfma_f32_16x16x32_bf16 v[80:83], v[186:189], v[214:217], v[80:83]
	v_mfma_f32_16x16x32_bf16 v[68:71], v[178:181], v[222:225], v[68:71]
	v_mfma_f32_16x16x32_bf16 v[64:67], v[186:189], v[222:225], v[64:67]
	s_barrier
	s_add_i32 s38, s13, s0
	v_lshl_add_u64 v[160:161], s[44:45], 0, v[132:133]
	s_mov_b32 m0, s38
	ds_read_b128 v[190:193], v153 offset:16384
	ds_read_b128 v[194:197], v153 offset:17408
	ds_read_b128 v[198:201], v153 offset:18432
	ds_read_b128 v[202:205], v153 offset:19456
	ds_read_b128 v[210:213], v153 offset:20480
	ds_read_b128 v[214:217], v153 offset:21504
	ds_read_b128 v[218:221], v153 offset:22528
	ds_read_b128 v[222:225], v153 offset:23552
	global_load_lds_dwordx4 v[160:161], off
	s_add_i32 m0, s38, 0x2000
	s_add_u32 s38, s44, 0x40000
	v_lshl_add_u64 v[206:207], s[44:45], 0, v[128:129]
	s_addc_u32 s39, s45, 0
	s_add_i32 s52, s18, s0
	global_load_lds_dwordx4 v[206:207], off
	v_lshl_add_u64 v[226:227], s[38:39], 0, v[132:133]
	s_mov_b32 m0, s52
	v_lshl_add_u64 v[228:229], s[46:47], 0, v[130:131]
	global_load_lds_dwordx4 v[226:227], off
	v_lshl_add_u64 v[226:227], s[38:39], 0, v[128:129]
	s_add_i32 m0, s52, 0x2000
	s_nop 0
	global_load_lds_dwordx4 v[226:227], off
	v_lshl_add_u64 v[226:227], s[46:47], 0, v[134:135]
	s_mov_b32 m0, s1
	s_nop 0
	global_load_lds_dwordx4 v[226:227], off
	s_mov_b32 m0, s4
	s_nop 0
	global_load_lds_dwordx4 v[228:229], off
	s_waitcnt vmcnt(8)
	s_waitcnt lgkmcnt(0)
	s_barrier
; #define PG8_STAGE(bufoff, gbase, voff) do { _Pragma("unroll") for (int _i = 0; _i < 2; ++_i) \
;         __builtin_amdgcn_global_load_lds((const unsigned*)((const char*)(gbase) + (voff)[_i]), (LAS unsigned*)(lds + (bufoff) + ldsw + _i * 8192), 16, 0, 0); } while (0)
; #define PG8_LDA(dst, b, h) do { _Pragma("unroll") for (int m = 0; m < 4; ++m) _Pragma("unroll") for (int k = 0; k < 2; ++k) dst[m][k] = *(const LAS bf16x8*)(lds + PG8_SA(b, h) + aoff + m * 2048 + k * 1024); } while (0)
; #define PG8_LDB(dst, b, h) do { _Pragma("unroll") for (int n = 0; n < 2; ++n) _Pragma("unroll") for (int k = 0; k < 2; ++k) dst[n][k] = *(const LAS bf16x8*)(lds + PG8_SB(b, h) + boff + n * 2048 + k * 1024); } while (0)
; #define PG8_MMA(ai, bj, At, Bt) do { __builtin_amdgcn_s_setprio(1); _Pragma("unroll") for (int m = 0; m < 4; ++m) _Pragma("unroll") for (int n = 0; n < 2; ++n) _Pragma("unroll") for (int k = 0; k < 2; ++k) \
;         acc[ai][bj][m][n] = __builtin_amdgcn_mfma_f32_16x16x32_bf16(Bt[n][k], At[m][k], acc[ai][bj][m][n], 0, 0, 0); __builtin_amdgcn_s_setprio(0); } while (0)
; #define PG8_WAIT_V(n) asm volatile("s_waitcnt vmcnt(" #n ")" ::: "memory")
; #define PG8_WAIT_L(n) asm volatile("s_waitcnt lgkmcnt(" #n ")" ::: "memory")
; #define PG8_BAR __builtin_amdgcn_s_barrier()
; #define PG8_SCHED __builtin_amdgcn_sched_barrier(0)
; template <class GEO, class Epi>
; __device__ __forceinline__ void gemm_phase(LAS unsigned char* lds, const Gemm g, const StaticOrder& S, const Epi& E) {
;     ...
;             PG8_WAIT_V(8); PG8_WAIT_L(0); PG8_BAR; PG8_MMA(1, 0, At, B0); PG8_MMA(1, 1, At, B1); PG8_BAR; PG8_SCHED;
;             PG8_LDB(B0, 1, 0); PG8_LDB(B1, 1, 1); PG8_SCHED; PG8_LDA(At, 1, 0); PG8_STAGE(PG8_SA(0, 1), a2 + hstepA, voffA);
;             PG8_WAIT_V(8); PG8_WAIT_L(0); PG8_BAR; PG8_MMA(0, 0, At, B0); PG8_MMA(0, 1, At, B1); PG8_BAR; PG8_SCHED;
	s_waitcnt lgkmcnt(0)
	v_mfma_f32_16x16x32_bf16 v[60:63], v[144:147], v[190:193], v[60:63]
	v_mfma_f32_16x16x32_bf16 v[56:59], v[166:169], v[190:193], v[56:59]
	v_mfma_f32_16x16x32_bf16 v[44:47], v[144:147], v[198:201], v[44:47]
	v_mfma_f32_16x16x32_bf16 v[40:43], v[166:169], v[198:201], v[40:43]
	v_mfma_f32_16x16x32_bf16 v[28:31], v[144:147], v[210:213], v[28:31]
	v_mfma_f32_16x16x32_bf16 v[24:27], v[166:169], v[210:213], v[24:27]
	v_mfma_f32_16x16x32_bf16 v[12:15], v[144:147], v[218:221], v[12:15]
	v_mfma_f32_16x16x32_bf16 v[8:11], v[166:169], v[218:221], v[8:11]
	v_mfma_f32_16x16x32_bf16 v[60:63], v[156:159], v[194:197], v[60:63]
	v_mfma_f32_16x16x32_bf16 v[56:59], v[170:173], v[194:197], v[56:59]
	v_mfma_f32_16x16x32_bf16 v[44:47], v[156:159], v[202:205], v[44:47]
	v_mfma_f32_16x16x32_bf16 v[40:43], v[170:173], v[202:205], v[40:43]
	v_mfma_f32_16x16x32_bf16 v[28:31], v[156:159], v[214:217], v[28:31]
	v_mfma_f32_16x16x32_bf16 v[24:27], v[170:173], v[214:217], v[24:27]
	v_mfma_f32_16x16x32_bf16 v[12:15], v[156:159], v[222:225], v[12:15]
	v_mfma_f32_16x16x32_bf16 v[8:11], v[170:173], v[222:225], v[8:11]
	v_mfma_f32_16x16x32_bf16 v[52:55], v[174:177], v[190:193], v[52:55]
	v_mfma_f32_16x16x32_bf16 v[48:51], v[182:185], v[190:193], v[48:51]
	v_mfma_f32_16x16x32_bf16 v[36:39], v[174:177], v[198:201], v[36:39]
	v_mfma_f32_16x16x32_bf16 v[32:35], v[182:185], v[198:201], v[32:35]
	v_mfma_f32_16x16x32_bf16 v[20:23], v[174:177], v[210:213], v[20:23]
	v_mfma_f32_16x16x32_bf16 v[16:19], v[182:185], v[210:213], v[16:19]
	v_mfma_f32_16x16x32_bf16 v[4:7], v[174:177], v[218:221], v[4:7]
	v_mfma_f32_16x16x32_bf16 v[0:3], v[182:185], v[218:221], v[0:3]
	v_mfma_f32_16x16x32_bf16 v[52:55], v[178:181], v[194:197], v[52:55]
	v_mfma_f32_16x16x32_bf16 v[48:51], v[186:189], v[194:197], v[48:51]
	v_mfma_f32_16x16x32_bf16 v[36:39], v[178:181], v[202:205], v[36:39]
	v_mfma_f32_16x16x32_bf16 v[32:35], v[186:189], v[202:205], v[32:35]
	v_mfma_f32_16x16x32_bf16 v[20:23], v[178:181], v[214:217], v[20:23]
	v_mfma_f32_16x16x32_bf16 v[16:19], v[186:189], v[214:217], v[16:19]
	v_mfma_f32_16x16x32_bf16 v[4:7], v[178:181], v[222:225], v[4:7]
	v_mfma_f32_16x16x32_bf16 v[0:3], v[186:189], v[222:225], v[0:3]
	s_barrier
	s_add_i32 s52, 0, 0x18000
	v_add_u32_e32 v155, s52, v149
	s_add_i32 s53, 0, 0x1c000
	ds_read_b128 v[144:147], v155
	ds_read_b128 v[156:159], v155 offset:1024
	ds_read_b128 v[166:169], v155 offset:2048
	ds_read_b128 v[170:173], v155 offset:3072
	v_add_u32_e32 v155, s53, v149
	ds_read_b128 v[174:177], v155
	ds_read_b128 v[178:181], v155 offset:1024
	ds_read_b128 v[182:185], v155 offset:2048
	ds_read_b128 v[186:189], v155 offset:3072
	s_add_u32 s38, s46, 0x40000
	s_addc_u32 s39, s47, 0
	s_mov_b32 m0, s5
	v_lshl_add_u64 v[230:231], s[38:39], 0, v[134:135]
	ds_read_b128 v[190:193], v153 offset:32768
	ds_read_b128 v[194:197], v153 offset:33792
	ds_read_b128 v[198:201], v153 offset:34816
	ds_read_b128 v[202:205], v153 offset:35840
	ds_read_b128 v[210:213], v153 offset:36864
	ds_read_b128 v[214:217], v153 offset:37888
	ds_read_b128 v[218:221], v153 offset:38912
	ds_read_b128 v[222:225], v153 offset:39936
	global_load_lds_dwordx4 v[230:231], off
	v_lshl_add_u64 v[230:231], s[38:39], 0, v[130:131]
	s_mov_b32 m0, s6
	s_nop 0
	global_load_lds_dwordx4 v[230:231], off
	s_waitcnt vmcnt(8)
	s_waitcnt lgkmcnt(0)
	s_barrier
	s_waitcnt lgkmcnt(0)
	v_mfma_f32_16x16x32_bf16 v[124:127], v[144:147], v[190:193], v[124:127]
	v_mfma_f32_16x16x32_bf16 v[120:123], v[166:169], v[190:193], v[120:123]
	v_mfma_f32_16x16x32_bf16 v[108:111], v[144:147], v[198:201], v[108:111]
	v_mfma_f32_16x16x32_bf16 v[104:107], v[166:169], v[198:201], v[104:107]
	v_mfma_f32_16x16x32_bf16 v[92:95], v[144:147], v[210:213], v[92:95]
	v_mfma_f32_16x16x32_bf16 v[88:91], v[166:169], v[210:213], v[88:91]
	v_mfma_f32_16x16x32_bf16 v[76:79], v[144:147], v[218:221], v[76:79]
	v_mfma_f32_16x16x32_bf16 v[72:75], v[166:169], v[218:221], v[72:75]
	v_mfma_f32_16x16x32_bf16 v[124:127], v[156:159], v[194:197], v[124:127]
	v_mfma_f32_16x16x32_bf16 v[120:123], v[170:173], v[194:197], v[120:123]
	v_mfma_f32_16x16x32_bf16 v[108:111], v[156:159], v[202:205], v[108:111]
	v_mfma_f32_16x16x32_bf16 v[104:107], v[170:173], v[202:205], v[104:107]
	v_mfma_f32_16x16x32_bf16 v[92:95], v[156:159], v[214:217], v[92:95]
	v_mfma_f32_16x16x32_bf16 v[88:91], v[170:173], v[214:217], v[88:91]
	v_mfma_f32_16x16x32_bf16 v[76:79], v[156:159], v[222:225], v[76:79]
	v_mfma_f32_16x16x32_bf16 v[72:75], v[170:173], v[222:225], v[72:75]
	v_mfma_f32_16x16x32_bf16 v[116:119], v[174:177], v[190:193], v[116:119]
	v_mfma_f32_16x16x32_bf16 v[112:115], v[182:185], v[190:193], v[112:115]
	v_mfma_f32_16x16x32_bf16 v[100:103], v[174:177], v[198:201], v[100:103]
	v_mfma_f32_16x16x32_bf16 v[96:99], v[182:185], v[198:201], v[96:99]
	v_mfma_f32_16x16x32_bf16 v[84:87], v[174:177], v[210:213], v[84:87]
	v_mfma_f32_16x16x32_bf16 v[80:83], v[182:185], v[210:213], v[80:83]
	v_mfma_f32_16x16x32_bf16 v[68:71], v[174:177], v[218:221], v[68:71]
	v_mfma_f32_16x16x32_bf16 v[64:67], v[182:185], v[218:221], v[64:67]
	v_mfma_f32_16x16x32_bf16 v[116:119], v[178:181], v[194:197], v[116:119]
	v_mfma_f32_16x16x32_bf16 v[112:115], v[186:189], v[194:197], v[112:115]
	v_mfma_f32_16x16x32_bf16 v[100:103], v[178:181], v[202:205], v[100:103]
	v_mfma_f32_16x16x32_bf16 v[96:99], v[186:189], v[202:205], v[96:99]
	v_mfma_f32_16x16x32_bf16 v[84:87], v[178:181], v[214:217], v[84:87]
	v_mfma_f32_16x16x32_bf16 v[80:83], v[186:189], v[214:217], v[80:83]
	v_mfma_f32_16x16x32_bf16 v[68:71], v[178:181], v[222:225], v[68:71]
	v_mfma_f32_16x16x32_bf16 v[64:67], v[186:189], v[222:225], v[64:67]
	s_barrier
; #define PG8_STAGE(bufoff, gbase, voff) do { _Pragma("unroll") for (int _i = 0; _i < 2; ++_i) \
;         __builtin_amdgcn_global_load_lds((const unsigned*)((const char*)(gbase) + (voff)[_i]), (LAS unsigned*)(lds + (bufoff) + ldsw + _i * 8192), 16, 0, 0); } while (0)
; #define PG8_LDA(dst, b, h) do { _Pragma("unroll") for (int m = 0; m < 4; ++m) _Pragma("unroll") for (int k = 0; k < 2; ++k) dst[m][k] = *(const LAS bf16x8*)(lds + PG8_SA(b, h) + aoff + m * 2048 + k * 1024); } while (0)
; #define PG8_MMA(ai, bj, At, Bt) do { __builtin_amdgcn_s_setprio(1); _Pragma("unroll") for (int m = 0; m < 4; ++m) _Pragma("unroll") for (int n = 0; n < 2; ++n) _Pragma("unroll") for (int k = 0; k < 2; ++k) \
;         acc[ai][bj][m][n] = __builtin_amdgcn_mfma_f32_16x16x32_bf16(Bt[n][k], At[m][k], acc[ai][bj][m][n], 0, 0, 0); __builtin_amdgcn_s_setprio(0); } while (0)
; #define PG8_WAIT_V(n) asm volatile("s_waitcnt vmcnt(" #n ")" ::: "memory")
; #define PG8_WAIT_L(n) asm volatile("s_waitcnt lgkmcnt(" #n ")" ::: "memory")
; #define PG8_BAR __builtin_amdgcn_s_barrier()
; #define PG8_SCHED __builtin_amdgcn_sched_barrier(0)
;     DI void operator()(Acc& acc, const Unit& u, int wr, int wc, int fr, int fq, LAS unsigned char*) const {
;     ...
;             for (int m = 0; m < 4; ++m) { const int row = u.pm * BM + ai * HALF + wr * 64 + m * 16 + fr; bf16_t* rowp = O + (size_t)row * ldc + col0;
;                 float rs = 1.0f; if (HAS_RS) { const f32x4 q4 = *(const f32x4*)(sumsq + (size_t)row * 4); rs = rsqrtf(((q4.x + q4.y) + (q4.z + q4.w)) * (1.0f / DM) + EPS); }
; template <class GEO, class Epi>
; __device__ __forceinline__ void gemm_phase(LAS unsigned char* lds, const Gemm g, const StaticOrder& S, const Epi& E) {
;     ...
;             PG8_LDA(At, 1, 1); PG8_STAGE(PG8_SB(1, 0), b3, voffB); PG8_STAGE(PG8_SB(1, 1), b3 + hstepB, voffB); PG8_STAGE(PG8_SA(1, 0), a3, voffA);
;             PG8_WAIT_V(8); PG8_WAIT_L(0); PG8_BAR; PG8_MMA(1, 0, At, B0); PG8_MMA(1, 1, At, B1); PG8_BAR; PG8_SCHED;
;         }
;         if (wr == 0) PG8_BAR;
	s_add_i32 s38, s52, s0
	v_lshl_add_u64 v[160:161], v[160:161], 0, s[24:25]
	s_mov_b32 m0, s38
	ds_read_b128 v[190:193], v153 offset:49152
	ds_read_b128 v[194:197], v153 offset:50176
	ds_read_b128 v[198:201], v153 offset:51200
	ds_read_b128 v[202:205], v153 offset:52224
	ds_read_b128 v[210:213], v153 offset:53248
	ds_read_b128 v[214:217], v153 offset:54272
	ds_read_b128 v[218:221], v153 offset:55296
	ds_read_b128 v[222:225], v153 offset:56320
	global_load_lds_dwordx4 v[160:161], off
	s_add_i32 m0, s38, 0x2000
	s_add_u32 s38, s44, 0x40080
	v_lshl_add_u64 v[160:161], v[206:207], 0, s[24:25]
	s_addc_u32 s39, s45, 0
	s_add_i32 s44, s53, s0
	global_load_lds_dwordx4 v[160:161], off
	v_lshl_add_u64 v[160:161], s[38:39], 0, v[132:133]
	s_mov_b32 m0, s44
	s_nop 0
	global_load_lds_dwordx4 v[160:161], off
	v_lshl_add_u64 v[160:161], s[38:39], 0, v[128:129]
	s_add_i32 m0, s44, 0x2000
	s_nop 0
	global_load_lds_dwordx4 v[160:161], off
	v_lshl_add_u64 v[160:161], v[226:227], 0, s[24:25]
	s_mov_b32 m0, s7
	s_nop 0
	global_load_lds_dwordx4 v[160:161], off
	v_lshl_add_u64 v[160:161], v[228:229], 0, s[24:25]
	s_mov_b32 m0, s12
	s_nop 0
	global_load_lds_dwordx4 v[160:161], off
	s_waitcnt vmcnt(8)
	s_waitcnt lgkmcnt(0)
	s_barrier
	s_waitcnt lgkmcnt(0)
	v_mfma_f32_16x16x32_bf16 v[60:63], v[144:147], v[190:193], v[60:63]
	v_mfma_f32_16x16x32_bf16 v[56:59], v[166:169], v[190:193], v[56:59]
	v_mfma_f32_16x16x32_bf16 v[44:47], v[144:147], v[198:201], v[44:47]
	v_mfma_f32_16x16x32_bf16 v[40:43], v[166:169], v[198:201], v[40:43]
	v_mfma_f32_16x16x32_bf16 v[28:31], v[144:147], v[210:213], v[28:31]
	v_mfma_f32_16x16x32_bf16 v[24:27], v[166:169], v[210:213], v[24:27]
	v_mfma_f32_16x16x32_bf16 v[12:15], v[144:147], v[218:221], v[12:15]
	v_mfma_f32_16x16x32_bf16 v[8:11], v[166:169], v[218:221], v[8:11]
	v_mfma_f32_16x16x32_bf16 v[60:63], v[156:159], v[194:197], v[60:63]
	v_mfma_f32_16x16x32_bf16 v[56:59], v[170:173], v[194:197], v[56:59]
	v_mfma_f32_16x16x32_bf16 v[44:47], v[156:159], v[202:205], v[44:47]
	v_mfma_f32_16x16x32_bf16 v[40:43], v[170:173], v[202:205], v[40:43]
	v_mfma_f32_16x16x32_bf16 v[28:31], v[156:159], v[214:217], v[28:31]
	v_mfma_f32_16x16x32_bf16 v[24:27], v[170:173], v[214:217], v[24:27]
	v_mfma_f32_16x16x32_bf16 v[12:15], v[156:159], v[222:225], v[12:15]
	v_mfma_f32_16x16x32_bf16 v[8:11], v[170:173], v[222:225], v[8:11]
	v_mfma_f32_16x16x32_bf16 v[52:55], v[174:177], v[190:193], v[52:55]
	v_mfma_f32_16x16x32_bf16 v[48:51], v[182:185], v[190:193], v[48:51]
	v_mfma_f32_16x16x32_bf16 v[36:39], v[174:177], v[198:201], v[36:39]
	v_mfma_f32_16x16x32_bf16 v[32:35], v[182:185], v[198:201], v[32:35]
	v_mfma_f32_16x16x32_bf16 v[20:23], v[174:177], v[210:213], v[20:23]
	v_mfma_f32_16x16x32_bf16 v[16:19], v[182:185], v[210:213], v[16:19]
	v_mfma_f32_16x16x32_bf16 v[4:7], v[174:177], v[218:221], v[4:7]
	v_mfma_f32_16x16x32_bf16 v[0:3], v[182:185], v[218:221], v[0:3]
	v_mfma_f32_16x16x32_bf16 v[52:55], v[178:181], v[194:197], v[52:55]
	v_mfma_f32_16x16x32_bf16 v[48:51], v[186:189], v[194:197], v[48:51]
	v_mfma_f32_16x16x32_bf16 v[36:39], v[178:181], v[202:205], v[36:39]
	v_mfma_f32_16x16x32_bf16 v[32:35], v[186:189], v[202:205], v[32:35]
	v_mfma_f32_16x16x32_bf16 v[20:23], v[178:181], v[214:217], v[20:23]
	v_mfma_f32_16x16x32_bf16 v[16:19], v[186:189], v[214:217], v[16:19]
	v_mfma_f32_16x16x32_bf16 v[4:7], v[178:181], v[222:225], v[4:7]
	v_mfma_f32_16x16x32_bf16 v[0:3], v[186:189], v[222:225], v[0:3]
	s_add_i32 s51, s51, 2
	s_add_u32 s22, s22, 0x100
	s_addc_u32 s23, s23, 0
	s_add_u32 s49, s49, 0x100
	s_addc_u32 s50, s50, 0
	s_cmp_gt_u32 s51, 13
	s_cbranch_scc0 .Lrot_5
	s_barrier
	v_lshl_add_u32 v144, s20, 8, v148
	v_lshl_or_b32 v146, s37, 8, v150
	v_ashrrev_i32_e32 v145, 31, v144
	v_ashrrev_i32_e32 v147, 31, v146
	v_lshl_add_u64 v[156:157], v[144:145], 4, s[8:9]
	global_load_dwordx4 v[166:169], v[156:157], off offset:2048
	global_load_dwordx4 v[170:173], v[156:157], off offset:2304
	global_load_dwordx4 v[174:177], v[156:157], off offset:2560
	global_load_dwordx4 v[178:181], v[156:157], off offset:2816
	s_and_b64 vcc, exec, s[28:29]
	s_cbranch_vccz .LBB0_1078
	s_barrier

; template <class GEO, class Epi>
; __device__ __forceinline__ void gemm_phase(LAS unsigned char* lds, const Gemm g, const StaticOrder& S, const Epi& E) {
;     ...
;         const bool has_next = S.next(ui + 1, nxt);
;         const char* nA = has_next ? PG8_APTR(nxt) : cA; const char* nB = has_next ? PG8_BPTR(nxt) : cB;
;     ...
; #pragma unroll
;         for (int a = 0; a < 2; ++a)
; #pragma unroll
;             for (int b = 0; b < 2; ++b)
; #pragma unroll
;                 for (int m = 0; m < 4; ++m)
; #pragma unroll
;                     for (int n = 0; n < 2; ++n) acc[a][b][m][n] = (f32x4){0.f, 0.f, 0.f, 0.f};
;         cur = nxt; cA = nA; cB = nB; ++ui;
.LBB0_1147:
	s_ashr_i32 s15, s14, 31
	s_lshl_b64 s[16:17], s[14:15], 21
	s_add_u32 s16, s96, s16
	s_addc_u32 s17, s97, s17
	s_and_b64 s[18:19], s[0:1], exec
	s_cselect_b32 s15, s17, s23
	s_cselect_b32 s42, s16, s22
	s_and_b32 s4, s40, 0x3fffffff
	s_lshl_b64 s[18:19], s[4:5], 21
	s_add_u32 s18, s70, s18
	s_addc_u32 s19, s71, s19
	s_and_b64 s[28:29], s[0:1], exec
	s_cselect_b32 s4, s19, s25
	s_cselect_b32 s43, s18, s24
	s_add_u32 s22, s22, 0x100080
	s_addc_u32 s23, s23, 0
	s_add_u32 s44, s24, 0x100
	v_mov_b32_e32 v0, 0
	s_addc_u32 s45, s25, 0
	s_mov_b32 s46, -2
	v_mov_b32_e32 v1, v0
	v_mov_b32_e32 v2, v0
	v_mov_b32_e32 v3, v0
	v_mov_b32_e32 v4, v0
	v_mov_b32_e32 v5, v0
	v_mov_b32_e32 v6, v0
	v_mov_b32_e32 v7, v0
	v_mov_b32_e32 v16, v0
	v_mov_b32_e32 v17, v0
	v_mov_b32_e32 v18, v0
	v_mov_b32_e32 v19, v0
	v_mov_b32_e32 v20, v0
	v_mov_b32_e32 v21, v0
	v_mov_b32_e32 v22, v0
	v_mov_b32_e32 v23, v0
	v_mov_b32_e32 v32, v0
	v_mov_b32_e32 v33, v0
	v_mov_b32_e32 v34, v0
	v_mov_b32_e32 v35, v0
	v_mov_b32_e32 v36, v0
	v_mov_b32_e32 v37, v0
	v_mov_b32_e32 v38, v0
	v_mov_b32_e32 v39, v0
	v_mov_b32_e32 v48, v0
	v_mov_b32_e32 v49, v0
	v_mov_b32_e32 v50, v0
	v_mov_b32_e32 v51, v0
	v_mov_b32_e32 v52, v0
	v_mov_b32_e32 v53, v0
	v_mov_b32_e32 v54, v0
	v_mov_b32_e32 v55, v0
	v_mov_b32_e32 v8, v0
	v_mov_b32_e32 v9, v0
	v_mov_b32_e32 v10, v0
	v_mov_b32_e32 v11, v0
	v_mov_b32_e32 v12, v0
	v_mov_b32_e32 v13, v0
	v_mov_b32_e32 v14, v0
	v_mov_b32_e32 v15, v0
	v_mov_b32_e32 v24, v0
	v_mov_b32_e32 v25, v0
	v_mov_b32_e32 v26, v0
	v_mov_b32_e32 v27, v0
	v_mov_b32_e32 v28, v0
	v_mov_b32_e32 v29, v0
	v_mov_b32_e32 v30, v0
	v_mov_b32_e32 v31, v0
	v_mov_b32_e32 v40, v0
	v_mov_b32_e32 v41, v0
	v_mov_b32_e32 v42, v0
	v_mov_b32_e32 v43, v0
	v_mov_b32_e32 v44, v0
	v_mov_b32_e32 v45, v0
	v_mov_b32_e32 v46, v0
	v_mov_b32_e32 v47, v0
	v_mov_b32_e32 v56, v0
	v_mov_b32_e32 v57, v0
	v_mov_b32_e32 v58, v0
	v_mov_b32_e32 v59, v0
	v_mov_b32_e32 v60, v0
	v_mov_b32_e32 v61, v0
	v_mov_b32_e32 v62, v0
	v_mov_b32_e32 v63, v0
	v_mov_b32_e32 v64, v0
	v_mov_b32_e32 v65, v0
	v_mov_b32_e32 v66, v0
	v_mov_b32_e32 v67, v0
	v_mov_b32_e32 v68, v0
	v_mov_b32_e32 v69, v0
	v_mov_b32_e32 v70, v0
	v_mov_b32_e32 v71, v0
	v_mov_b32_e32 v80, v0
	v_mov_b32_e32 v81, v0
	v_mov_b32_e32 v82, v0
	v_mov_b32_e32 v83, v0
	v_mov_b32_e32 v84, v0
	v_mov_b32_e32 v85, v0
	v_mov_b32_e32 v86, v0
	v_mov_b32_e32 v87, v0
	v_mov_b32_e32 v96, v0
	v_mov_b32_e32 v97, v0
	v_mov_b32_e32 v98, v0
	v_mov_b32_e32 v99, v0
	v_mov_b32_e32 v100, v0
	v_mov_b32_e32 v101, v0
	v_mov_b32_e32 v102, v0
	v_mov_b32_e32 v103, v0
	v_mov_b32_e32 v112, v0
	v_mov_b32_e32 v113, v0
	v_mov_b32_e32 v114, v0
	v_mov_b32_e32 v115, v0
	v_mov_b32_e32 v116, v0
	v_mov_b32_e32 v117, v0
	v_mov_b32_e32 v118, v0
	v_mov_b32_e32 v119, v0
	v_mov_b32_e32 v72, v0
	v_mov_b32_e32 v73, v0
	v_mov_b32_e32 v74, v0
	v_mov_b32_e32 v75, v0
	v_mov_b32_e32 v76, v0
	v_mov_b32_e32 v77, v0
	v_mov_b32_e32 v78, v0
	v_mov_b32_e32 v79, v0
	v_mov_b32_e32 v88, v0
	v_mov_b32_e32 v89, v0
	v_mov_b32_e32 v90, v0
	v_mov_b32_e32 v91, v0
	v_mov_b32_e32 v92, v0
	v_mov_b32_e32 v93, v0
	v_mov_b32_e32 v94, v0
	v_mov_b32_e32 v95, v0
	v_mov_b32_e32 v104, v0
	v_mov_b32_e32 v105, v0
	v_mov_b32_e32 v106, v0
	v_mov_b32_e32 v107, v0
	v_mov_b32_e32 v108, v0
	v_mov_b32_e32 v109, v0
	v_mov_b32_e32 v110, v0
	v_mov_b32_e32 v111, v0
	v_mov_b32_e32 v120, v0
	v_mov_b32_e32 v121, v0
	v_mov_b32_e32 v122, v0
	v_mov_b32_e32 v123, v0
	v_mov_b32_e32 v124, v0
	v_mov_b32_e32 v125, v0
	v_mov_b32_e32 v126, v0
	v_mov_b32_e32 v127, v0
	s_branch .LBB0_1148

; #define PG8_STAGE(bufoff, gbase, voff) do { _Pragma("unroll") for (int _i = 0; _i < 2; ++_i) \
;         __builtin_amdgcn_global_load_lds((const unsigned*)((const char*)(gbase) + (voff)[_i]), (LAS unsigned*)(lds + (bufoff) + ldsw + _i * 8192), 16, 0, 0); } while (0)
; #define PG8_LDA(dst, b, h) do { _Pragma("unroll") for (int m = 0; m < 4; ++m) _Pragma("unroll") for (int k = 0; k < 2; ++k) dst[m][k] = *(const LAS bf16x8*)(lds + PG8_SA(b, h) + aoff + m * 2048 + k * 1024); } while (0)
; #define PG8_LDB(dst, b, h) do { _Pragma("unroll") for (int n = 0; n < 2; ++n) _Pragma("unroll") for (int k = 0; k < 2; ++k) dst[n][k] = *(const LAS bf16x8*)(lds + PG8_SB(b, h) + boff + n * 2048 + k * 1024); } while (0)
; #define PG8_MMA(ai, bj, At, Bt) do { __builtin_amdgcn_s_setprio(1); _Pragma("unroll") for (int m = 0; m < 4; ++m) _Pragma("unroll") for (int n = 0; n < 2; ++n) _Pragma("unroll") for (int k = 0; k < 2; ++k) \
;         acc[ai][bj][m][n] = __builtin_amdgcn_mfma_f32_16x16x32_bf16(Bt[n][k], At[m][k], acc[ai][bj][m][n], 0, 0, 0); __builtin_amdgcn_s_setprio(0); } while (0)
; #define PG8_WAIT_V(n) asm volatile("s_waitcnt vmcnt(" #n ")" ::: "memory")
; #define PG8_WAIT_L(n) asm volatile("s_waitcnt lgkmcnt(" #n ")" ::: "memory")
; #define PG8_BAR __builtin_amdgcn_s_barrier()
; #define PG8_SCHED __builtin_amdgcn_sched_barrier(0)
; template <class GEO, class Epi>
; __device__ __forceinline__ void gemm_phase(LAS unsigned char* lds, const Gemm g, const StaticOrder& S, const Epi& E) {
;     ...
;             const bool last = (t == nt - 2);
;             const char* a1 = cA + (size_t)(t + 1) * kstep;
;             const char* a2 = last ? nA : cA + (size_t)(t + 2) * kstep; const char* b2 = last ? nB : cB + (size_t)(t + 2) * kstep;
;             const char* a3 = a2 + kstep; const char* b3 = b2 + kstep;
;             PG8_LDB(B0, 0, 0); PG8_LDB(B1, 0, 1); PG8_SCHED; PG8_LDA(At, 0, 0); PG8_STAGE(PG8_SA(1, 1), a1 + hstepA, voffA);
;             PG8_WAIT_V(8); PG8_WAIT_L(0); PG8_BAR; PG8_MMA(0, 0, At, B0); PG8_MMA(0, 1, At, B1); PG8_BAR; PG8_SCHED;
;             PG8_LDA(At, 0, 1); PG8_STAGE(PG8_SB(0, 0), b2, voffB); PG8_STAGE(PG8_SB(0, 1), b2 + hstepB, voffB); PG8_STAGE(PG8_SA(0, 0), a2, voffA);
.LBB0_1148:
	ds_read_b128 v[144:147], v151
	ds_read_b128 v[154:157], v151 offset:1024
	ds_read_b128 v[158:161], v151 offset:2048
	ds_read_b128 v[162:165], v151 offset:3072
	ds_read_b128 v[166:169], v152
	ds_read_b128 v[170:173], v152 offset:1024
	ds_read_b128 v[174:177], v152 offset:2048
	ds_read_b128 v[178:181], v152 offset:3072
	s_add_u32 s24, s22, 0xfff00080
	s_addc_u32 s25, s23, -1
	s_cmp_eq_u32 s46, 60
	s_cselect_b32 s29, s15, s25
	s_cselect_b32 s28, s42, s24
	s_cselect_b32 s25, s4, s45
	s_cselect_b32 s24, s43, s44
	v_lshl_add_u64 v[214:215], s[22:23], 0, v[136:137]
	s_add_i32 m0, s21, 0xc000
	ds_read_b128 v[182:185], v153
	ds_read_b128 v[186:189], v153 offset:1024
	ds_read_b128 v[190:193], v153 offset:2048
	ds_read_b128 v[194:197], v153 offset:3072
	ds_read_b128 v[198:201], v153 offset:4096
	ds_read_b128 v[202:205], v153 offset:5120
	ds_read_b128 v[206:209], v153 offset:6144
	ds_read_b128 v[210:213], v153 offset:7168
	global_load_lds_dwordx4 v[214:215], off
	v_lshl_add_u64 v[214:215], s[22:23], 0, v[138:139]
	s_add_i32 m0, s21, 0xe000
	s_nop 0
	global_load_lds_dwordx4 v[214:215], off
	s_waitcnt vmcnt(8)
	s_waitcnt lgkmcnt(0)
	s_barrier
	s_waitcnt lgkmcnt(0)
	v_mfma_f32_16x16x32_bf16 v[124:127], v[144:147], v[182:185], v[124:127]
	v_mfma_f32_16x16x32_bf16 v[120:123], v[158:161], v[182:185], v[120:123]
	v_mfma_f32_16x16x32_bf16 v[108:111], v[144:147], v[190:193], v[108:111]
	v_mfma_f32_16x16x32_bf16 v[104:107], v[158:161], v[190:193], v[104:107]
	v_mfma_f32_16x16x32_bf16 v[92:95], v[144:147], v[198:201], v[92:95]
	v_mfma_f32_16x16x32_bf16 v[88:91], v[158:161], v[198:201], v[88:91]
	v_mfma_f32_16x16x32_bf16 v[76:79], v[144:147], v[206:209], v[76:79]
	v_mfma_f32_16x16x32_bf16 v[72:75], v[158:161], v[206:209], v[72:75]
	v_mfma_f32_16x16x32_bf16 v[124:127], v[154:157], v[186:189], v[124:127]
	v_mfma_f32_16x16x32_bf16 v[120:123], v[162:165], v[186:189], v[120:123]
	v_mfma_f32_16x16x32_bf16 v[108:111], v[154:157], v[194:197], v[108:111]
	v_mfma_f32_16x16x32_bf16 v[104:107], v[162:165], v[194:197], v[104:107]
	v_mfma_f32_16x16x32_bf16 v[92:95], v[154:157], v[202:205], v[92:95]
	v_mfma_f32_16x16x32_bf16 v[88:91], v[162:165], v[202:205], v[88:91]
	v_mfma_f32_16x16x32_bf16 v[76:79], v[154:157], v[210:213], v[76:79]
	v_mfma_f32_16x16x32_bf16 v[72:75], v[162:165], v[210:213], v[72:75]
	v_mfma_f32_16x16x32_bf16 v[116:119], v[166:169], v[182:185], v[116:119]
	v_mfma_f32_16x16x32_bf16 v[112:115], v[174:177], v[182:185], v[112:115]
	v_mfma_f32_16x16x32_bf16 v[100:103], v[166:169], v[190:193], v[100:103]
	v_mfma_f32_16x16x32_bf16 v[96:99], v[174:177], v[190:193], v[96:99]
	v_mfma_f32_16x16x32_bf16 v[84:87], v[166:169], v[198:201], v[84:87]
	v_mfma_f32_16x16x32_bf16 v[80:83], v[174:177], v[198:201], v[80:83]
	v_mfma_f32_16x16x32_bf16 v[68:71], v[166:169], v[206:209], v[68:71]
	v_mfma_f32_16x16x32_bf16 v[64:67], v[174:177], v[206:209], v[64:67]
	v_mfma_f32_16x16x32_bf16 v[116:119], v[170:173], v[186:189], v[116:119]
	v_mfma_f32_16x16x32_bf16 v[112:115], v[178:181], v[186:189], v[112:115]
	v_mfma_f32_16x16x32_bf16 v[100:103], v[170:173], v[194:197], v[100:103]
	v_mfma_f32_16x16x32_bf16 v[96:99], v[178:181], v[194:197], v[96:99]
	v_mfma_f32_16x16x32_bf16 v[84:87], v[170:173], v[202:205], v[84:87]
	v_mfma_f32_16x16x32_bf16 v[80:83], v[178:181], v[202:205], v[80:83]
	v_mfma_f32_16x16x32_bf16 v[68:71], v[170:173], v[210:213], v[68:71]
	v_mfma_f32_16x16x32_bf16 v[64:67], v[178:181], v[210:213], v[64:67]
	s_barrier
	s_add_i32 s47, s37, s30
	v_lshl_add_u64 v[214:215], s[24:25], 0, v[130:131]
	s_mov_b32 m0, s47
	ds_read_b128 v[182:185], v153 offset:16384
	ds_read_b128 v[186:189], v153 offset:17408
	ds_read_b128 v[190:193], v153 offset:18432
	ds_read_b128 v[194:197], v153 offset:19456
	ds_read_b128 v[198:201], v153 offset:20480
	ds_read_b128 v[202:205], v153 offset:21504
	ds_read_b128 v[206:209], v153 offset:22528
	ds_read_b128 v[210:213], v153 offset:23552
	global_load_lds_dwordx4 v[214:215], off
	s_add_i32 m0, s47, 0x2000
	s_add_u32 s48, s24, 0x100000
	v_lshl_add_u64 v[216:217], s[24:25], 0, v[134:135]
	s_addc_u32 s49, s25, 0
	s_add_i32 s47, s38, s30
	global_load_lds_dwordx4 v[216:217], off
	v_lshl_add_u64 v[218:219], s[48:49], 0, v[130:131]
	s_mov_b32 m0, s47
	v_lshl_add_u64 v[220:221], s[28:29], 0, v[132:133]
	global_load_lds_dwordx4 v[218:219], off
	v_lshl_add_u64 v[218:219], s[48:49], 0, v[134:135]
	s_add_i32 m0, s47, 0x2000
	s_nop 0
	global_load_lds_dwordx4 v[218:219], off
	v_lshl_add_u64 v[218:219], s[28:29], 0, v[128:129]
	s_mov_b32 m0, s21
	s_nop 0
	global_load_lds_dwordx4 v[218:219], off
	s_mov_b32 m0, s31
	s_nop 0
	global_load_lds_dwordx4 v[220:221], off
	s_waitcnt vmcnt(8)
	s_waitcnt lgkmcnt(0)
	s_barrier
; #define PG8_STAGE(bufoff, gbase, voff) do { _Pragma("unroll") for (int _i = 0; _i < 2; ++_i) \
;         __builtin_amdgcn_global_load_lds((const unsigned*)((const char*)(gbase) + (voff)[_i]), (LAS unsigned*)(lds + (bufoff) + ldsw + _i * 8192), 16, 0, 0); } while (0)
; #define PG8_LDA(dst, b, h) do { _Pragma("unroll") for (int m = 0; m < 4; ++m) _Pragma("unroll") for (int k = 0; k < 2; ++k) dst[m][k] = *(const LAS bf16x8*)(lds + PG8_SA(b, h) + aoff + m * 2048 + k * 1024); } while (0)
; #define PG8_LDB(dst, b, h) do { _Pragma("unroll") for (int n = 0; n < 2; ++n) _Pragma("unroll") for (int k = 0; k < 2; ++k) dst[n][k] = *(const LAS bf16x8*)(lds + PG8_SB(b, h) + boff + n * 2048 + k * 1024); } while (0)
; #define PG8_MMA(ai, bj, At, Bt) do { __builtin_amdgcn_s_setprio(1); _Pragma("unroll") for (int m = 0; m < 4; ++m) _Pragma("unroll") for (int n = 0; n < 2; ++n) _Pragma("unroll") for (int k = 0; k < 2; ++k) \
;         acc[ai][bj][m][n] = __builtin_amdgcn_mfma_f32_16x16x32_bf16(Bt[n][k], At[m][k], acc[ai][bj][m][n], 0, 0, 0); __builtin_amdgcn_s_setprio(0); } while (0)
; #define PG8_WAIT_V(n) asm volatile("s_waitcnt vmcnt(" #n ")" ::: "memory")
; #define PG8_WAIT_L(n) asm volatile("s_waitcnt lgkmcnt(" #n ")" ::: "memory")
; #define PG8_BAR __builtin_amdgcn_s_barrier()
; #define PG8_SCHED __builtin_amdgcn_sched_barrier(0)
; template <class GEO, class Epi>
; __device__ __forceinline__ void gemm_phase(LAS unsigned char* lds, const Gemm g, const StaticOrder& S, const Epi& E) {
;     ...
;             PG8_WAIT_V(8); PG8_WAIT_L(0); PG8_BAR; PG8_MMA(1, 0, At, B0); PG8_MMA(1, 1, At, B1); PG8_BAR; PG8_SCHED;
;             PG8_LDB(B0, 1, 0); PG8_LDB(B1, 1, 1); PG8_SCHED; PG8_LDA(At, 1, 0); PG8_STAGE(PG8_SA(0, 1), a2 + hstepA, voffA);
;             PG8_WAIT_V(8); PG8_WAIT_L(0); PG8_BAR; PG8_MMA(0, 0, At, B0); PG8_MMA(0, 1, At, B1); PG8_BAR; PG8_SCHED;
	s_waitcnt lgkmcnt(0)
	v_mfma_f32_16x16x32_bf16 v[60:63], v[144:147], v[182:185], v[60:63]
	v_mfma_f32_16x16x32_bf16 v[56:59], v[158:161], v[182:185], v[56:59]
	v_mfma_f32_16x16x32_bf16 v[44:47], v[144:147], v[190:193], v[44:47]
	v_mfma_f32_16x16x32_bf16 v[40:43], v[158:161], v[190:193], v[40:43]
	v_mfma_f32_16x16x32_bf16 v[28:31], v[144:147], v[198:201], v[28:31]
	v_mfma_f32_16x16x32_bf16 v[24:27], v[158:161], v[198:201], v[24:27]
	v_mfma_f32_16x16x32_bf16 v[12:15], v[144:147], v[206:209], v[12:15]
	v_mfma_f32_16x16x32_bf16 v[8:11], v[158:161], v[206:209], v[8:11]
	v_mfma_f32_16x16x32_bf16 v[60:63], v[154:157], v[186:189], v[60:63]
	v_mfma_f32_16x16x32_bf16 v[56:59], v[162:165], v[186:189], v[56:59]
	v_mfma_f32_16x16x32_bf16 v[44:47], v[154:157], v[194:197], v[44:47]
	v_mfma_f32_16x16x32_bf16 v[40:43], v[162:165], v[194:197], v[40:43]
	v_mfma_f32_16x16x32_bf16 v[28:31], v[154:157], v[202:205], v[28:31]
	v_mfma_f32_16x16x32_bf16 v[24:27], v[162:165], v[202:205], v[24:27]
	v_mfma_f32_16x16x32_bf16 v[12:15], v[154:157], v[210:213], v[12:15]
	v_mfma_f32_16x16x32_bf16 v[8:11], v[162:165], v[210:213], v[8:11]
	v_mfma_f32_16x16x32_bf16 v[52:55], v[166:169], v[182:185], v[52:55]
	v_mfma_f32_16x16x32_bf16 v[48:51], v[174:177], v[182:185], v[48:51]
	v_mfma_f32_16x16x32_bf16 v[36:39], v[166:169], v[190:193], v[36:39]
	v_mfma_f32_16x16x32_bf16 v[32:35], v[174:177], v[190:193], v[32:35]
	v_mfma_f32_16x16x32_bf16 v[20:23], v[166:169], v[198:201], v[20:23]
	v_mfma_f32_16x16x32_bf16 v[16:19], v[174:177], v[198:201], v[16:19]
	v_mfma_f32_16x16x32_bf16 v[4:7], v[166:169], v[206:209], v[4:7]
	v_mfma_f32_16x16x32_bf16 v[0:3], v[174:177], v[206:209], v[0:3]
	v_mfma_f32_16x16x32_bf16 v[52:55], v[170:173], v[186:189], v[52:55]
	v_mfma_f32_16x16x32_bf16 v[48:51], v[178:181], v[186:189], v[48:51]
	v_mfma_f32_16x16x32_bf16 v[36:39], v[170:173], v[194:197], v[36:39]
	v_mfma_f32_16x16x32_bf16 v[32:35], v[178:181], v[194:197], v[32:35]
	v_mfma_f32_16x16x32_bf16 v[20:23], v[170:173], v[202:205], v[20:23]
	v_mfma_f32_16x16x32_bf16 v[16:19], v[178:181], v[202:205], v[16:19]
	v_mfma_f32_16x16x32_bf16 v[4:7], v[170:173], v[210:213], v[4:7]
	v_mfma_f32_16x16x32_bf16 v[0:3], v[178:181], v[210:213], v[0:3]
	s_barrier
	s_add_i32 s47, 0, 0x18000
	s_add_i32 s48, 0, 0x1c000
	v_add_u32_e32 v162, s47, v149
	v_add_u32_e32 v178, s48, v149
	ds_read_b128 v[144:147], v162
	ds_read_b128 v[154:157], v162 offset:1024
	ds_read_b128 v[158:161], v162 offset:2048
	ds_read_b128 v[162:165], v162 offset:3072
	ds_read_b128 v[166:169], v178
	ds_read_b128 v[170:173], v178 offset:1024
	ds_read_b128 v[174:177], v178 offset:2048
	ds_read_b128 v[178:181], v178 offset:3072
	s_add_u32 s28, s28, 0x100000
	s_addc_u32 s29, s29, 0
	s_mov_b32 m0, s33
	v_lshl_add_u64 v[222:223], s[28:29], 0, v[128:129]
	ds_read_b128 v[182:185], v153 offset:32768
	ds_read_b128 v[186:189], v153 offset:33792
	ds_read_b128 v[190:193], v153 offset:34816
	ds_read_b128 v[194:197], v153 offset:35840
	ds_read_b128 v[198:201], v153 offset:36864
	ds_read_b128 v[202:205], v153 offset:37888
	ds_read_b128 v[206:209], v153 offset:38912
	ds_read_b128 v[210:213], v153 offset:39936
	global_load_lds_dwordx4 v[222:223], off
	v_lshl_add_u64 v[222:223], s[28:29], 0, v[132:133]
	s_mov_b32 m0, s34
	s_nop 0
	global_load_lds_dwordx4 v[222:223], off
	s_waitcnt vmcnt(8)
	s_waitcnt lgkmcnt(0)
	s_barrier
	s_waitcnt lgkmcnt(0)
	v_mfma_f32_16x16x32_bf16 v[124:127], v[144:147], v[182:185], v[124:127]
	v_mfma_f32_16x16x32_bf16 v[120:123], v[158:161], v[182:185], v[120:123]
	v_mfma_f32_16x16x32_bf16 v[108:111], v[144:147], v[190:193], v[108:111]
	v_mfma_f32_16x16x32_bf16 v[104:107], v[158:161], v[190:193], v[104:107]
	v_mfma_f32_16x16x32_bf16 v[92:95], v[144:147], v[198:201], v[92:95]
	v_mfma_f32_16x16x32_bf16 v[88:91], v[158:161], v[198:201], v[88:91]
	v_mfma_f32_16x16x32_bf16 v[76:79], v[144:147], v[206:209], v[76:79]
	v_mfma_f32_16x16x32_bf16 v[72:75], v[158:161], v[206:209], v[72:75]
	v_mfma_f32_16x16x32_bf16 v[124:127], v[154:157], v[186:189], v[124:127]
	v_mfma_f32_16x16x32_bf16 v[120:123], v[162:165], v[186:189], v[120:123]
	v_mfma_f32_16x16x32_bf16 v[108:111], v[154:157], v[194:197], v[108:111]
	v_mfma_f32_16x16x32_bf16 v[104:107], v[162:165], v[194:197], v[104:107]
	v_mfma_f32_16x16x32_bf16 v[92:95], v[154:157], v[202:205], v[92:95]
	v_mfma_f32_16x16x32_bf16 v[88:91], v[162:165], v[202:205], v[88:91]
	v_mfma_f32_16x16x32_bf16 v[76:79], v[154:157], v[210:213], v[76:79]
	v_mfma_f32_16x16x32_bf16 v[72:75], v[162:165], v[210:213], v[72:75]
	v_mfma_f32_16x16x32_bf16 v[116:119], v[166:169], v[182:185], v[116:119]
	v_mfma_f32_16x16x32_bf16 v[112:115], v[174:177], v[182:185], v[112:115]
	v_mfma_f32_16x16x32_bf16 v[100:103], v[166:169], v[190:193], v[100:103]
	v_mfma_f32_16x16x32_bf16 v[96:99], v[174:177], v[190:193], v[96:99]
	v_mfma_f32_16x16x32_bf16 v[84:87], v[166:169], v[198:201], v[84:87]
	v_mfma_f32_16x16x32_bf16 v[80:83], v[174:177], v[198:201], v[80:83]
	v_mfma_f32_16x16x32_bf16 v[68:71], v[166:169], v[206:209], v[68:71]
	v_mfma_f32_16x16x32_bf16 v[64:67], v[174:177], v[206:209], v[64:67]
	v_mfma_f32_16x16x32_bf16 v[116:119], v[170:173], v[186:189], v[116:119]
	v_mfma_f32_16x16x32_bf16 v[112:115], v[178:181], v[186:189], v[112:115]
	v_mfma_f32_16x16x32_bf16 v[100:103], v[170:173], v[194:197], v[100:103]
	v_mfma_f32_16x16x32_bf16 v[96:99], v[178:181], v[194:197], v[96:99]
	v_mfma_f32_16x16x32_bf16 v[84:87], v[170:173], v[202:205], v[84:87]
	v_mfma_f32_16x16x32_bf16 v[80:83], v[178:181], v[202:205], v[80:83]
	v_mfma_f32_16x16x32_bf16 v[68:71], v[170:173], v[210:213], v[68:71]
	v_mfma_f32_16x16x32_bf16 v[64:67], v[178:181], v[210:213], v[64:67]
	s_barrier
; DI float bflo(unsigned w) { return __uint_as_float(w << 16); }
; DI float bfhi(unsigned w) { return __uint_as_float(w & 0xffff0000u); }
; #define PG8_STAGE(bufoff, gbase, voff) do { _Pragma("unroll") for (int _i = 0; _i < 2; ++_i) \
;         __builtin_amdgcn_global_load_lds((const unsigned*)((const char*)(gbase) + (voff)[_i]), (LAS unsigned*)(lds + (bufoff) + ldsw + _i * 8192), 16, 0, 0); } while (0)
; #define PG8_LDA(dst, b, h) do { _Pragma("unroll") for (int m = 0; m < 4; ++m) _Pragma("unroll") for (int k = 0; k < 2; ++k) dst[m][k] = *(const LAS bf16x8*)(lds + PG8_SA(b, h) + aoff + m * 2048 + k * 1024); } while (0)
; #define PG8_MMA(ai, bj, At, Bt) do { __builtin_amdgcn_s_setprio(1); _Pragma("unroll") for (int m = 0; m < 4; ++m) _Pragma("unroll") for (int n = 0; n < 2; ++n) _Pragma("unroll") for (int k = 0; k < 2; ++k) \
;         acc[ai][bj][m][n] = __builtin_amdgcn_mfma_f32_16x16x32_bf16(Bt[n][k], At[m][k], acc[ai][bj][m][n], 0, 0, 0); __builtin_amdgcn_s_setprio(0); } while (0)
; #define PG8_WAIT_V(n) asm volatile("s_waitcnt vmcnt(" #n ")" ::: "memory")
; #define PG8_WAIT_L(n) asm volatile("s_waitcnt lgkmcnt(" #n ")" ::: "memory")
;     DI void operator()(Acc& acc, const Unit& u, int wr, int wc, int fr, int fq, LAS unsigned char* lds) const {
;     ...
;             for (int m = 0; m < 4; ++m) { const int row = u.pm * BM + ai * HALF + wr * 64 + m * 16 + fr; const size_t off = (size_t)row * DM + col0; float ss = 0.f;
; #pragma unroll
;                 for (int bj = 0; bj < 2; ++bj) { const size_t o = off + bj * HALF;
;                     f32x4 b0, b1;
;                     if (BASE_BF16) { const u32x4 w = *(const u32x4*)((const bf16_t*)base + o); b0 = (f32x4){bflo(w.x), bfhi(w.x), bflo(w.y), bfhi(w.y)}; b1 = (f32x4){bflo(w.z), bfhi(w.z), bflo(w.w), bfhi(w.w)}; }
;                     else { b0 = *(const f32x4*)((const float*)base + o); b1 = *(const f32x4*)((const float*)base + o + 4); }
; template <class GEO, class Epi>
; __device__ __forceinline__ void gemm_phase(LAS unsigned char* lds, const Gemm g, const StaticOrder& S, const Epi& E) {
;     ...
;             PG8_LDA(At, 1, 1); PG8_STAGE(PG8_SB(1, 0), b3, voffB); PG8_STAGE(PG8_SB(1, 1), b3 + hstepB, voffB); PG8_STAGE(PG8_SA(1, 0), a3, voffA);
;             PG8_WAIT_V(8); PG8_WAIT_L(0); PG8_BAR; PG8_MMA(1, 0, At, B0); PG8_MMA(1, 1, At, B1); PG8_BAR; PG8_SCHED;
;         }
;         if (wr == 0) PG8_BAR;
	s_add_i32 s28, s47, s30
	v_lshl_add_u64 v[214:215], v[214:215], 0, s[8:9]
	s_mov_b32 m0, s28
	ds_read_b128 v[182:185], v153 offset:49152
	ds_read_b128 v[186:189], v153 offset:50176
	ds_read_b128 v[190:193], v153 offset:51200
	ds_read_b128 v[194:197], v153 offset:52224
	ds_read_b128 v[198:201], v153 offset:53248
	ds_read_b128 v[202:205], v153 offset:54272
	ds_read_b128 v[206:209], v153 offset:55296
	ds_read_b128 v[210:213], v153 offset:56320
	global_load_lds_dwordx4 v[214:215], off
	s_add_i32 m0, s28, 0x2000
	s_add_u32 s24, s24, 0x100080
	v_lshl_add_u64 v[214:215], v[216:217], 0, s[8:9]
	s_addc_u32 s25, s25, 0
	s_add_i32 s28, s48, s30
	global_load_lds_dwordx4 v[214:215], off
	v_lshl_add_u64 v[214:215], s[24:25], 0, v[130:131]
	s_mov_b32 m0, s28
	s_nop 0
	global_load_lds_dwordx4 v[214:215], off
	v_lshl_add_u64 v[214:215], s[24:25], 0, v[134:135]
	s_add_i32 m0, s28, 0x2000
	s_nop 0
	global_load_lds_dwordx4 v[214:215], off
	v_lshl_add_u64 v[214:215], v[218:219], 0, s[8:9]
	s_mov_b32 m0, s35
	s_nop 0
	global_load_lds_dwordx4 v[214:215], off
	v_lshl_add_u64 v[214:215], v[220:221], 0, s[8:9]
	s_mov_b32 m0, s36
	s_nop 0
	global_load_lds_dwordx4 v[214:215], off
	s_waitcnt vmcnt(8)
	s_waitcnt lgkmcnt(0)
	s_barrier
	s_waitcnt lgkmcnt(0)
	v_mfma_f32_16x16x32_bf16 v[60:63], v[144:147], v[182:185], v[60:63]
	v_mfma_f32_16x16x32_bf16 v[56:59], v[158:161], v[182:185], v[56:59]
	v_mfma_f32_16x16x32_bf16 v[44:47], v[144:147], v[190:193], v[44:47]
	v_mfma_f32_16x16x32_bf16 v[40:43], v[158:161], v[190:193], v[40:43]
	v_mfma_f32_16x16x32_bf16 v[28:31], v[144:147], v[198:201], v[28:31]
	v_mfma_f32_16x16x32_bf16 v[24:27], v[158:161], v[198:201], v[24:27]
	v_mfma_f32_16x16x32_bf16 v[12:15], v[144:147], v[206:209], v[12:15]
	v_mfma_f32_16x16x32_bf16 v[8:11], v[158:161], v[206:209], v[8:11]
	v_mfma_f32_16x16x32_bf16 v[60:63], v[154:157], v[186:189], v[60:63]
	v_mfma_f32_16x16x32_bf16 v[56:59], v[162:165], v[186:189], v[56:59]
	v_mfma_f32_16x16x32_bf16 v[44:47], v[154:157], v[194:197], v[44:47]
	v_mfma_f32_16x16x32_bf16 v[40:43], v[162:165], v[194:197], v[40:43]
	v_mfma_f32_16x16x32_bf16 v[28:31], v[154:157], v[202:205], v[28:31]
	v_mfma_f32_16x16x32_bf16 v[24:27], v[162:165], v[202:205], v[24:27]
	v_mfma_f32_16x16x32_bf16 v[12:15], v[154:157], v[210:213], v[12:15]
	v_mfma_f32_16x16x32_bf16 v[8:11], v[162:165], v[210:213], v[8:11]
	v_mfma_f32_16x16x32_bf16 v[52:55], v[166:169], v[182:185], v[52:55]
	v_mfma_f32_16x16x32_bf16 v[48:51], v[174:177], v[182:185], v[48:51]
	v_mfma_f32_16x16x32_bf16 v[36:39], v[166:169], v[190:193], v[36:39]
	v_mfma_f32_16x16x32_bf16 v[32:35], v[174:177], v[190:193], v[32:35]
	v_mfma_f32_16x16x32_bf16 v[20:23], v[166:169], v[198:201], v[20:23]
	v_mfma_f32_16x16x32_bf16 v[16:19], v[174:177], v[198:201], v[16:19]
	v_mfma_f32_16x16x32_bf16 v[4:7], v[166:169], v[206:209], v[4:7]
	v_mfma_f32_16x16x32_bf16 v[0:3], v[174:177], v[206:209], v[0:3]
	v_mfma_f32_16x16x32_bf16 v[52:55], v[170:173], v[186:189], v[52:55]
	v_mfma_f32_16x16x32_bf16 v[48:51], v[178:181], v[186:189], v[48:51]
	v_mfma_f32_16x16x32_bf16 v[36:39], v[170:173], v[194:197], v[36:39]
	v_mfma_f32_16x16x32_bf16 v[32:35], v[178:181], v[194:197], v[32:35]
	v_mfma_f32_16x16x32_bf16 v[20:23], v[170:173], v[202:205], v[20:23]
	v_mfma_f32_16x16x32_bf16 v[16:19], v[178:181], v[202:205], v[16:19]
	v_mfma_f32_16x16x32_bf16 v[4:7], v[170:173], v[210:213], v[4:7]
	v_mfma_f32_16x16x32_bf16 v[0:3], v[178:181], v[210:213], v[0:3]
	s_add_i32 s46, s46, 2
	s_add_u32 s22, s22, 0x100
	s_addc_u32 s23, s23, 0
	s_add_u32 s44, s44, 0x100
	s_addc_u32 s45, s45, 0
	s_cmp_gt_u32 s46, 61
	s_cbranch_scc0 .Lrot_6
	s_barrier
	v_lshl_add_u32 v146, s20, 8, v148
	v_lshl_or_b32 v144, s41, 8, v150
	v_ashrrev_i32_e32 v147, 31, v146
	v_ashrrev_i32_e32 v145, 31, v144
	v_lshlrev_b64 v[154:155], 10, v[146:147]
	v_lshl_add_u64 v[158:159], v[154:155], 0, v[144:145]
	v_lshlrev_b64 v[154:155], 1, v[158:159]
	v_lshl_add_u64 v[154:155], s[26:27], 0, v[154:155]
	v_lshl_add_u64 v[158:159], v[158:159], 2, s[74:75]
	s_mov_b32 s42, 0x8000
	s_mov_b32 s43, 0
	s_mov_b32 s44, 0x40000
	s_mov_b32 s45, 0
	s_mov_b32 s46, 0x10000
	s_mov_b32 s47, 0
	s_mov_b32 s48, 0x80000
	s_mov_b32 s49, 0
	v_lshl_add_u64 v[224:225], v[154:155], 0, s[44:45]
	global_load_dwordx4 v[160:163], v[154:155], off
	global_load_dwordx4 v[164:167], v[154:155], off offset:256
	v_lshl_add_u64 v[156:157], v[154:155], 0, s[42:43]
	global_load_dwordx4 v[168:171], v[156:157], off
	global_load_dwordx4 v[172:175], v[156:157], off offset:256
	v_lshl_add_u64 v[154:155], v[156:157], 0, s[42:43]
	global_load_dwordx4 v[176:179], v[154:155], off
	global_load_dwordx4 v[180:183], v[154:155], off offset:256
	v_lshl_add_u64 v[156:157], v[154:155], 0, s[42:43]
	global_load_dwordx4 v[184:187], v[156:157], off
	global_load_dwordx4 v[188:191], v[156:157], off offset:256
	global_load_dwordx4 v[192:195], v[224:225], off
	global_load_dwordx4 v[196:199], v[224:225], off offset:256
	v_lshl_add_u64 v[156:157], v[224:225], 0, s[42:43]
	global_load_dwordx4 v[200:203], v[156:157], off
	global_load_dwordx4 v[204:207], v[156:157], off offset:256
	v_lshl_add_u64 v[154:155], v[156:157], 0, s[42:43]
	global_load_dwordx4 v[208:211], v[154:155], off
	global_load_dwordx4 v[212:215], v[154:155], off offset:256
	v_lshl_add_u64 v[156:157], v[154:155], 0, s[42:43]
	global_load_dwordx4 v[216:219], v[156:157], off
	global_load_dwordx4 v[220:223], v[156:157], off offset:256
	s_and_b64 vcc, exec, s[12:13]
	s_cbranch_vccz .LBB0_1151
	s_barrier
